# gather remapped: 8 tokens x 8 slice pieces per wave, no cross-lane reduce in v accumulate; final pass without unused id/gate/scale loads
# speedup vs baseline: 1.0085x; 1.0085x over previous
.LBB0_923:
	s_andn2_b64 vcc, exec, s[16:17]
	s_cbranch_vccnz .LBB0_222
	s_lshr_b32 s7, s67, 6
	s_add_i32 s16, s7, s3
	v_mov_b32_e32 v2, v238
	s_cmpk_gt_i32 s16, 0x3fff
	s_cbranch_scc1 .LBB0_1033
	s_add_u32 s18, s78, 0x61a00000
	s_addc_u32 s19, s79, 0
	s_add_u32 s20, s78, 0x62200000
	s_addc_u32 s21, s79, 0
	s_add_u32 s7, s78, 0x6ac00000
	s_addc_u32 s10, s79, 0
	s_add_i32 s11, s96, -1
	s_cmp_lt_u32 s11, 2
	s_cselect_b64 s[46:47], -1, 0
	s_add_u32 s11, s78, s52
	s_addc_u32 s12, s79, s53
	s_add_u32 s11, s11, 0x100000
	s_addc_u32 s12, s12, 0
	s_add_u32 s52, s54, 0x40000
	s_addc_u32 s53, s55, 0
	s_cmp_lg_u32 s96, 3
	v_readlane_b32 s64, v252, 0
	v_readlane_b32 s4, v252, 34
	s_cselect_b64 s[60:61], -1, 0
	s_cmp_eq_u32 s96, 3
	v_readlane_b32 s66, v252, 2
	v_readlane_b32 s67, v252, 3
	v_readlane_b32 s5, v252, 35
	s_cselect_b32 s15, s67, s5
	s_cselect_b32 s14, s66, s4
	s_lshl_b64 s[36:37], s[50:51], 2
	v_readlane_b32 s65, v252, 1
	s_add_u32 s50, s64, s36
	v_and_b32_e32 v1, 32, v2
	v_and_b32_e32 v66, 63, v2
	s_addc_u32 s51, s65, s37
	v_cmp_eq_u32_e64 s[36:37], 0, v1
	v_and_b32_e32 v1, 16, v2
	s_add_u32 s62, s50, 0x2000
	v_cmp_eq_u32_e64 s[38:39], 0, v1
	v_and_b32_e32 v1, 8, v2
	v_bfe_u32 v67, v2, 3, 3
	v_lshlrev_b32_e32 v2, 3, v66
	v_mov_b32_e32 v3, v187
	v_readlane_b32 s70, v252, 6
	v_readlane_b32 s71, v252, 7
	s_addc_u32 s63, s51, 0
	v_readlane_b32 s4, v254, 61
	v_lshlrev_b32_e32 v186, 4, v66
	v_lshl_add_u64 v[72:73], s[88:89], 0, v[2:3]
	v_sub_co_u32_e32 v2, vcc, 0, v2
	v_readlane_b32 s70, v254, 46
	v_readlane_b32 s5, v254, 62
	s_add_u32 s64, s4, 0x2000
	v_lshl_add_u64 v[74:75], s[14:15], 0, v[186:187]
	v_subb_co_u32_e64 v3, s[14:15], 0, 0, vcc
	v_readlane_b32 s71, v254, 47
	s_addc_u32 s65, s5, 0
	v_lshl_add_u64 v[68:69], s[56:57], 0, v[186:187]
	v_lshl_add_u64 v[70:71], s[58:59], 0, v[186:187]
	s_mov_b32 s101, 0x1fff80
	v_mad_u64_u32 v[68:69], vcc, v67, s101, v[68:69]
	v_mad_u64_u32 v[70:71], vcc, v67, s101, v[70:71]
	v_cmp_eq_u32_e64 s[40:41], 0, v1
	v_lshl_add_u64 v[76:77], v[74:75], 0, v[2:3]
	v_readlane_b32 s68, v252, 4
	v_readlane_b32 s69, v252, 5
	v_and_b32_e32 v17, 7, v66
	v_lshlrev_b32_e32 v78, 4, v17
	v_readfirstlane_b32 s100, v238
	s_lshr_b32 s100, s100, 6
	s_mul_i32 s100, s100, 12288
	v_lshlrev_b32_e32 v18, 9, v67
	v_add_u32_e32 v164, s100, v18
	v_add_u32_e32 v168, 4096, v164
	v_lshl_add_u32 v165, v66, 2, s100
	v_add_u32_e32 v165, 8192, v165
	v_and_b32_e32 v18, 1, v17
	v_lshlrev_b32_e32 v18, 2, v18
	v_and_b32_e32 v19, 2, v17
	v_or_b32_e32 v18, v18, v19
	v_lshrrev_b32_e32 v19, 2, v17
	v_or_b32_e32 v18, v18, v19
	v_lshlrev_b32_e32 v170, 2, v18
	v_mov_b32_e32 v19, s82
	v_mad_u32_u24 v19, v67, v19, s16
	v_lshlrev_b32_e32 v171, 12, v19
	v_lshl_add_u32 v171, v17, 3, v171
	v_lshlrev_b32_e32 v172, 4, v19
	v_lshl_add_u32 v173, v19, 9, v170
	v_lshl_add_u32 v174, v19, 13, v78
	s_mov_b32 s36, 0xcccccccc
	s_mov_b32 s37, 0xcccccccc
	s_mov_b32 s38, 0xaaaaaaaa
	s_mov_b32 s39, 0xaaaaaaaa
	v_mov_b32_e32 v20, 0
	v_mov_b32_e32 v21, 0
	v_mov_b32_e32 v22, 0
	v_mov_b32_e32 v23, 0
	v_lshl_add_u32 v19, v66, 4, s100
	ds_write_b128 v19, v[20:23] offset:8192
	ds_write_b128 v19, v[20:23] offset:9216
	ds_write_b128 v19, v[20:23] offset:10240
	ds_write_b128 v19, v[20:23] offset:11264
	v_lshl_add_u32 v18, v66, 2, s100
	v_lshlrev_b32_e32 v1, 2, v66
	s_mov_b32 s15, s16
	s_ashr_i32 s101, s15, 31
	s_mov_b32 s100, s15
	s_lshl_b64 s[100:101], s[100:101], 9
	s_add_u32 s42, s18, s100
	s_addc_u32 s43, s19, s101
	global_load_dword v20, v1, s[42:43]
	global_load_dword v21, v1, s[42:43] offset:256
	s_add_i32 s15, s15, s82
	s_ashr_i32 s101, s15, 31
	s_mov_b32 s100, s15
	s_lshl_b64 s[100:101], s[100:101], 9
	s_add_u32 s42, s18, s100
	s_addc_u32 s43, s19, s101
	global_load_dword v22, v1, s[42:43]
	global_load_dword v23, v1, s[42:43] offset:256
	s_add_i32 s15, s15, s82
	s_ashr_i32 s101, s15, 31
	s_mov_b32 s100, s15
	s_lshl_b64 s[100:101], s[100:101], 9
	s_add_u32 s42, s18, s100
	s_addc_u32 s43, s19, s101
	global_load_dword v24, v1, s[42:43]
	global_load_dword v25, v1, s[42:43] offset:256
	s_add_i32 s15, s15, s82
	s_ashr_i32 s101, s15, 31
	s_mov_b32 s100, s15
	s_lshl_b64 s[100:101], s[100:101], 9
	s_add_u32 s42, s18, s100
	s_addc_u32 s43, s19, s101
	global_load_dword v26, v1, s[42:43]
	global_load_dword v27, v1, s[42:43] offset:256
	s_add_i32 s15, s15, s82
	s_ashr_i32 s101, s15, 31
	s_mov_b32 s100, s15
	s_lshl_b64 s[100:101], s[100:101], 9
	s_add_u32 s42, s18, s100
	s_addc_u32 s43, s19, s101
	global_load_dword v28, v1, s[42:43]
	global_load_dword v29, v1, s[42:43] offset:256
	s_add_i32 s15, s15, s82
	s_ashr_i32 s101, s15, 31
	s_mov_b32 s100, s15
	s_lshl_b64 s[100:101], s[100:101], 9
	s_add_u32 s42, s18, s100
	s_addc_u32 s43, s19, s101
	global_load_dword v30, v1, s[42:43]
	global_load_dword v31, v1, s[42:43] offset:256
	s_add_i32 s15, s15, s82
	s_ashr_i32 s101, s15, 31
	s_mov_b32 s100, s15
	s_lshl_b64 s[100:101], s[100:101], 9
	s_add_u32 s42, s18, s100
	s_addc_u32 s43, s19, s101
	global_load_dword v32, v1, s[42:43]
	global_load_dword v33, v1, s[42:43] offset:256
	s_add_i32 s15, s15, s82
	s_ashr_i32 s101, s15, 31
	s_mov_b32 s100, s15
	s_lshl_b64 s[100:101], s[100:101], 9
	s_add_u32 s42, s18, s100
	s_addc_u32 s43, s19, s101
	global_load_dword v34, v1, s[42:43]
	global_load_dword v35, v1, s[42:43] offset:256
	s_add_i32 s15, s15, s82
	s_waitcnt vmcnt(0)
	ds_write_b32 v18, v20 offset:0
	ds_write_b32 v18, v21 offset:256
	ds_write_b32 v18, v22 offset:512
	ds_write_b32 v18, v23 offset:768
	ds_write_b32 v18, v24 offset:1024
	ds_write_b32 v18, v25 offset:1280
	ds_write_b32 v18, v26 offset:1536
	ds_write_b32 v18, v27 offset:1792
	ds_write_b32 v18, v28 offset:2048
	ds_write_b32 v18, v29 offset:2304
	ds_write_b32 v18, v30 offset:2560
	ds_write_b32 v18, v31 offset:2816
	ds_write_b32 v18, v32 offset:3072
	ds_write_b32 v18, v33 offset:3328
	ds_write_b32 v18, v34 offset:3584
	ds_write_b32 v18, v35 offset:3840
	s_mov_b32 s13, 0
	ds_read_b128 v[2:5], v164 offset:0
	ds_read_b128 v[6:9], v164 offset:16
	ds_read_b128 v[10:13], v164 offset:32
	ds_read_b128 v[14:17], v164 offset:48
	s_mov_b64 s[40:41], s[56:57]
	s_waitcnt lgkmcnt(0)
	v_lshl_add_u32 v2, v2, 7, v78
	v_lshl_add_u32 v3, v3, 7, v78
	v_lshl_add_u32 v4, v4, 7, v78
	v_lshl_add_u32 v5, v5, 7, v78
	v_lshl_add_u32 v6, v6, 7, v78
	v_lshl_add_u32 v7, v7, 7, v78
	v_lshl_add_u32 v8, v8, 7, v78
	v_lshl_add_u32 v9, v9, 7, v78
	v_lshl_add_u32 v10, v10, 7, v78
	v_lshl_add_u32 v11, v11, 7, v78
	v_lshl_add_u32 v12, v12, 7, v78
	v_lshl_add_u32 v13, v13, 7, v78
	v_lshl_add_u32 v14, v14, 7, v78
	v_lshl_add_u32 v15, v15, 7, v78
	v_lshl_add_u32 v16, v16, 7, v78
	v_lshl_add_u32 v17, v17, 7, v78
	global_load_dwordx4 v[100:103], v2, s[40:41]
	global_load_dwordx4 v[104:107], v3, s[40:41]
	global_load_dwordx4 v[108:111], v4, s[40:41]
	global_load_dwordx4 v[112:115], v5, s[40:41]
	global_load_dwordx4 v[116:119], v6, s[40:41]
	global_load_dwordx4 v[120:123], v7, s[40:41]
	global_load_dwordx4 v[124:127], v8, s[40:41]
	global_load_dwordx4 v[128:131], v9, s[40:41]
	global_load_dwordx4 v[132:135], v10, s[40:41]
	global_load_dwordx4 v[136:139], v11, s[40:41]
	global_load_dwordx4 v[140:143], v12, s[40:41]
	global_load_dwordx4 v[144:147], v13, s[40:41]
	global_load_dwordx4 v[148:151], v14, s[40:41]
	global_load_dwordx4 v[152:155], v15, s[40:41]
	global_load_dwordx4 v[156:159], v16, s[40:41]
	global_load_dwordx4 v[160:163], v17, s[40:41]
.Lg4_u_slice:
	s_lshl_b32 s101, s13, 6
	v_add_u32_e32 v1, s101, v171
	s_lshl_b32 s101, s13, 7
	v_add_u32_e32 v64, s101, v78
	v_add_u32_e32 v65, 0x1000, v64
	v_readlane_b32 s4, v254, 61
	v_readlane_b32 s5, v254, 62
	s_mov_b32 s44, s11
	s_mov_b32 s45, s12
	global_load_dwordx4 v[52:55], v172, s[44:45]
	global_load_dwordx2 v[2:3], v1, s[88:89] offset:0
	global_load_dwordx2 v[4:5], v1, s[88:89] offset:512
	global_load_dwordx2 v[6:7], v1, s[88:89] offset:1024
	global_load_dwordx2 v[8:9], v1, s[88:89] offset:1536
	global_load_dwordx2 v[10:11], v1, s[88:89] offset:2048
	global_load_dwordx2 v[12:13], v1, s[88:89] offset:2560
	global_load_dwordx2 v[14:15], v1, s[88:89] offset:3072
	global_load_dwordx2 v[16:17], v1, s[88:89] offset:3584
	global_load_dwordx4 v[80:83], v64, s[4:5] offset:0
	global_load_dwordx4 v[96:99], v64, s[50:51] offset:0
	global_load_dwordx4 v[84:87], v64, s[4:5] offset:1024
	global_load_dwordx4 v[56:59], v64, s[50:51] offset:1024
	global_load_dwordx4 v[88:91], v64, s[4:5] offset:2048
	global_load_dwordx4 v[60:63], v64, s[50:51] offset:2048
	global_load_dwordx4 v[92:95], v64, s[4:5] offset:3072
	global_load_dwordx4 v[44:47], v64, s[50:51] offset:3072
	s_waitcnt vmcnt(16)
	v_cvt_f64_i32_e32 v[20:21], v53
	v_cvt_f64_u32_e32 v[22:23], v52
	v_ldexp_f64 v[20:21], v[20:21], 32
	v_cvt_f64_i32_e32 v[24:25], v55
	v_add_f64 v[22:23], v[20:21], v[22:23]
	v_cvt_f64_u32_e32 v[26:27], v54
	v_ldexp_f64 v[24:25], v[24:25], 32
	v_ldexp_f64 v[22:23], v[22:23], s33
	v_add_f64 v[26:27], v[24:25], v[26:27]
	v_cvt_f32_f64_e32 v28, v[22:23]
	v_ldexp_f64 v[26:27], v[26:27], s33
	v_mul_f32_e32 v52, 0x3a000000, v28
	v_cvt_f32_f64_e32 v29, v[26:27]
	v_mul_f32_e32 v30, v52, v52
	v_fma_f32 v29, v29, v0, -v30
	v_add_f32_e32 v29, 0x3727c5ac, v29
	v_mul_f32_e32 v30, 0x4f800000, v29
	v_cmp_gt_f32_e32 vcc, s6, v29
	s_nop 1
	v_cndmask_b32_e32 v29, v29, v30, vcc
	v_sqrt_f32_e32 v31, v29
	s_nop 0
	v_add_u32_e32 v32, -1, v31
	v_add_u32_e32 v33, 1, v31
	v_fma_f32 v34, -v32, v31, v29
	v_fma_f32 v35, -v33, v31, v29
	v_cmp_ge_f32_e64 s[42:43], 0, v34
	s_nop 1
	v_cndmask_b32_e64 v31, v31, v32, s[42:43]
	v_cmp_lt_f32_e64 s[42:43], 0, v35
	s_nop 1
	v_cndmask_b32_e64 v31, v31, v33, s[42:43]
	v_mul_f32_e32 v32, 0x37800000, v31
	v_cndmask_b32_e32 v31, v31, v32, vcc
	v_cmp_class_f32_e32 vcc, v29, v229
	s_nop 1
	v_cndmask_b32_e32 v29, v31, v29, vcc
	v_div_scale_f32 v30, s[44:45], v29, v29, 1.0
	v_rcp_f32_e32 v31, v30
	v_div_scale_f32 v32, vcc, 1.0, v29, 1.0
	v_fma_f32 v33, -v30, v31, 1.0
	v_fmac_f32_e32 v31, v33, v31
	v_mul_f32_e32 v33, v32, v31
	v_fma_f32 v34, -v30, v33, v32
	v_fmac_f32_e32 v33, v34, v31
	v_fma_f32 v30, -v30, v33, v32
	v_div_fmas_f32 v30, v30, v31, v33
	v_div_fixup_f32 v54, v30, v29, 1.0
	s_waitcnt vmcnt(0)
	v_lshlrev_b32_e32 v20, 16, v2
	v_and_b32_e32 v21, 0xffff0000, v2
	v_lshlrev_b32_e32 v22, 16, v3
	v_and_b32_e32 v23, 0xffff0000, v3
	v_pk_fma_f32 v[20:21], v[80:81], v[52:53], v[20:21] op_sel_hi:[1,0,1] neg_lo:[1,0,0] neg_hi:[1,0,0]
	v_pk_fma_f32 v[22:23], v[82:83], v[52:53], v[22:23] op_sel_hi:[1,0,1] neg_lo:[1,0,0] neg_hi:[1,0,0]
	v_pk_fma_f32 v[20:21], v[54:55], v[20:21], v[96:97] op_sel_hi:[0,1,1]
	v_pk_fma_f32 v[22:23], v[54:55], v[22:23], v[98:99] op_sel_hi:[0,1,1]
	v_lshlrev_b32_e32 v24, 16, v4
	v_and_b32_e32 v25, 0xffff0000, v4
	v_lshlrev_b32_e32 v26, 16, v5
	v_and_b32_e32 v27, 0xffff0000, v5
	v_pk_fma_f32 v[24:25], v[84:85], v[52:53], v[24:25] op_sel_hi:[1,0,1] neg_lo:[1,0,0] neg_hi:[1,0,0]
	v_pk_fma_f32 v[26:27], v[86:87], v[52:53], v[26:27] op_sel_hi:[1,0,1] neg_lo:[1,0,0] neg_hi:[1,0,0]
	v_pk_fma_f32 v[24:25], v[54:55], v[24:25], v[56:57] op_sel_hi:[0,1,1]
	v_pk_fma_f32 v[26:27], v[54:55], v[26:27], v[58:59] op_sel_hi:[0,1,1]
	v_lshlrev_b32_e32 v28, 16, v6
	v_and_b32_e32 v29, 0xffff0000, v6
	v_lshlrev_b32_e32 v30, 16, v7
	v_and_b32_e32 v31, 0xffff0000, v7
	v_pk_fma_f32 v[28:29], v[88:89], v[52:53], v[28:29] op_sel_hi:[1,0,1] neg_lo:[1,0,0] neg_hi:[1,0,0]
	v_pk_fma_f32 v[30:31], v[90:91], v[52:53], v[30:31] op_sel_hi:[1,0,1] neg_lo:[1,0,0] neg_hi:[1,0,0]
	v_pk_fma_f32 v[28:29], v[54:55], v[28:29], v[60:61] op_sel_hi:[0,1,1]
	v_pk_fma_f32 v[30:31], v[54:55], v[30:31], v[62:63] op_sel_hi:[0,1,1]
	v_lshlrev_b32_e32 v32, 16, v8
	v_and_b32_e32 v33, 0xffff0000, v8
	v_lshlrev_b32_e32 v34, 16, v9
	v_and_b32_e32 v35, 0xffff0000, v9
	v_pk_fma_f32 v[32:33], v[92:93], v[52:53], v[32:33] op_sel_hi:[1,0,1] neg_lo:[1,0,0] neg_hi:[1,0,0]
	v_pk_fma_f32 v[34:35], v[94:95], v[52:53], v[34:35] op_sel_hi:[1,0,1] neg_lo:[1,0,0] neg_hi:[1,0,0]
	v_pk_fma_f32 v[32:33], v[54:55], v[32:33], v[44:45] op_sel_hi:[0,1,1]
	v_pk_fma_f32 v[34:35], v[54:55], v[34:35], v[46:47] op_sel_hi:[0,1,1]
	global_load_dwordx4 v[80:83], v65, s[4:5] offset:0
	global_load_dwordx4 v[96:99], v65, s[50:51] offset:0
	global_load_dwordx4 v[84:87], v65, s[4:5] offset:1024
	global_load_dwordx4 v[56:59], v65, s[50:51] offset:1024
	global_load_dwordx4 v[88:91], v65, s[4:5] offset:2048
	global_load_dwordx4 v[60:63], v65, s[50:51] offset:2048
	global_load_dwordx4 v[92:95], v65, s[4:5] offset:3072
	global_load_dwordx4 v[2:5], v65, s[50:51] offset:3072
	s_waitcnt vmcnt(0)
	v_lshlrev_b32_e32 v36, 16, v10
	v_and_b32_e32 v37, 0xffff0000, v10
	v_lshlrev_b32_e32 v38, 16, v11
	v_and_b32_e32 v39, 0xffff0000, v11
	v_pk_fma_f32 v[36:37], v[80:81], v[52:53], v[36:37] op_sel_hi:[1,0,1] neg_lo:[1,0,0] neg_hi:[1,0,0]
	v_pk_fma_f32 v[38:39], v[82:83], v[52:53], v[38:39] op_sel_hi:[1,0,1] neg_lo:[1,0,0] neg_hi:[1,0,0]
	v_pk_fma_f32 v[36:37], v[54:55], v[36:37], v[96:97] op_sel_hi:[0,1,1]
	v_pk_fma_f32 v[38:39], v[54:55], v[38:39], v[98:99] op_sel_hi:[0,1,1]
	v_lshlrev_b32_e32 v40, 16, v12
	v_and_b32_e32 v41, 0xffff0000, v12
	v_lshlrev_b32_e32 v42, 16, v13
	v_and_b32_e32 v43, 0xffff0000, v13
	v_pk_fma_f32 v[40:41], v[84:85], v[52:53], v[40:41] op_sel_hi:[1,0,1] neg_lo:[1,0,0] neg_hi:[1,0,0]
	v_pk_fma_f32 v[42:43], v[86:87], v[52:53], v[42:43] op_sel_hi:[1,0,1] neg_lo:[1,0,0] neg_hi:[1,0,0]
	v_pk_fma_f32 v[40:41], v[54:55], v[40:41], v[56:57] op_sel_hi:[0,1,1]
	v_pk_fma_f32 v[42:43], v[54:55], v[42:43], v[58:59] op_sel_hi:[0,1,1]
	v_lshlrev_b32_e32 v44, 16, v14
	v_and_b32_e32 v45, 0xffff0000, v14
	v_lshlrev_b32_e32 v46, 16, v15
	v_and_b32_e32 v47, 0xffff0000, v15
	v_pk_fma_f32 v[44:45], v[88:89], v[52:53], v[44:45] op_sel_hi:[1,0,1] neg_lo:[1,0,0] neg_hi:[1,0,0]
	v_pk_fma_f32 v[46:47], v[90:91], v[52:53], v[46:47] op_sel_hi:[1,0,1] neg_lo:[1,0,0] neg_hi:[1,0,0]
	v_pk_fma_f32 v[44:45], v[54:55], v[44:45], v[60:61] op_sel_hi:[0,1,1]
	v_pk_fma_f32 v[46:47], v[54:55], v[46:47], v[62:63] op_sel_hi:[0,1,1]
	v_lshlrev_b32_e32 v48, 16, v16
	v_and_b32_e32 v49, 0xffff0000, v16
	v_lshlrev_b32_e32 v50, 16, v17
	v_and_b32_e32 v51, 0xffff0000, v17
	v_pk_fma_f32 v[48:49], v[92:93], v[52:53], v[48:49] op_sel_hi:[1,0,1] neg_lo:[1,0,0] neg_hi:[1,0,0]
	v_pk_fma_f32 v[50:51], v[94:95], v[52:53], v[50:51] op_sel_hi:[1,0,1] neg_lo:[1,0,0] neg_hi:[1,0,0]
	v_pk_fma_f32 v[48:49], v[54:55], v[48:49], v[2:3] op_sel_hi:[0,1,1]
	v_pk_fma_f32 v[50:51], v[54:55], v[50:51], v[4:5] op_sel_hi:[0,1,1]
	s_mov_b32 s14, 0
	v_mov_b32_e32 v167, v165
.Lg4_u_gp:
	s_lshl_b32 s100, s14, 1
	s_add_i32 s100, s100, 2
	s_lshr_b32 s101, s100, 4
	s_and_b32 s100, s100, 15
	s_lshl_b32 s100, s100, 5
	v_add_u32_e32 v1, s100, v164
	s_add_i32 s101, s101, s13
	s_min_u32 s101, s101, 7
	s_lshl_b32 s101, s101, 21
	s_add_u32 s40, s56, s101
	s_addc_u32 s41, s57, 0
	ds_read_b128 v[2:5], v1 offset:0
	ds_read_b128 v[6:9], v1 offset:16
	s_waitcnt vmcnt(15)
	v_cvt_scalef32_pk_f32_fp4 v[60:61], v100, 1.0
	v_cvt_scalef32_pk_f32_fp4 v[62:63], v100, 1.0 op_sel:[1,0,0]
	v_cvt_scalef32_pk_f32_fp4 v[64:65], v100, 1.0 op_sel:[0,1,0]
	v_cvt_scalef32_pk_f32_fp4 v[80:81], v100, 1.0 op_sel:[1,1,0]
	v_cvt_scalef32_pk_f32_fp4 v[82:83], v101, 1.0
	v_cvt_scalef32_pk_f32_fp4 v[84:85], v101, 1.0 op_sel:[1,0,0]
	v_cvt_scalef32_pk_f32_fp4 v[86:87], v101, 1.0 op_sel:[0,1,0]
	v_cvt_scalef32_pk_f32_fp4 v[88:89], v101, 1.0 op_sel:[1,1,0]
	v_pk_mul_f32 v[54:55], v[60:61], v[20:21]
	v_pk_mul_f32 v[52:53], v[62:63], v[22:23]
	v_pk_mul_f32 v[58:59], v[64:65], v[24:25]
	v_pk_mul_f32 v[56:57], v[80:81], v[26:27]
	v_cvt_scalef32_pk_f32_fp4 v[60:61], v102, 1.0
	v_cvt_scalef32_pk_f32_fp4 v[62:63], v102, 1.0 op_sel:[1,0,0]
	v_cvt_scalef32_pk_f32_fp4 v[64:65], v102, 1.0 op_sel:[0,1,0]
	v_cvt_scalef32_pk_f32_fp4 v[80:81], v102, 1.0 op_sel:[1,1,0]
	v_pk_fma_f32 v[54:55], v[82:83], v[28:29], v[54:55]
	v_pk_fma_f32 v[52:53], v[84:85], v[30:31], v[52:53]
	v_pk_fma_f32 v[58:59], v[86:87], v[32:33], v[58:59]
	v_pk_fma_f32 v[56:57], v[88:89], v[34:35], v[56:57]
	v_cvt_scalef32_pk_f32_fp4 v[82:83], v103, 1.0
	v_cvt_scalef32_pk_f32_fp4 v[84:85], v103, 1.0 op_sel:[1,0,0]
	v_cvt_scalef32_pk_f32_fp4 v[86:87], v103, 1.0 op_sel:[0,1,0]
	v_cvt_scalef32_pk_f32_fp4 v[88:89], v103, 1.0 op_sel:[1,1,0]
	v_pk_fma_f32 v[54:55], v[60:61], v[36:37], v[54:55]
	v_pk_fma_f32 v[52:53], v[62:63], v[38:39], v[52:53]
	v_pk_fma_f32 v[58:59], v[64:65], v[40:41], v[58:59]
	v_pk_fma_f32 v[56:57], v[80:81], v[42:43], v[56:57]
	v_pk_fma_f32 v[54:55], v[82:83], v[44:45], v[54:55]
	v_pk_fma_f32 v[52:53], v[84:85], v[46:47], v[52:53]
	v_pk_fma_f32 v[58:59], v[86:87], v[48:49], v[58:59]
	v_pk_fma_f32 v[56:57], v[88:89], v[50:51], v[56:57]
	s_waitcnt lgkmcnt(0)
	v_lshl_add_u32 v2, v2, 7, v78
	v_lshl_add_u32 v3, v3, 7, v78
	v_lshl_add_u32 v4, v4, 7, v78
	v_lshl_add_u32 v5, v5, 7, v78
	v_lshl_add_u32 v6, v6, 7, v78
	v_lshl_add_u32 v7, v7, 7, v78
	v_lshl_add_u32 v8, v8, 7, v78
	v_lshl_add_u32 v9, v9, 7, v78
	global_load_dwordx4 v[100:103], v2, s[40:41]
	v_pk_add_f32 v[54:55], v[54:55], v[52:53]
	v_pk_add_f32 v[58:59], v[58:59], v[56:57]
	v_pk_add_f32 v[54:55], v[54:55], v[58:59]
	v_add_f32_e32 v90, v54, v55
	s_waitcnt vmcnt(15)
	v_cvt_scalef32_pk_f32_fp4 v[60:61], v104, 1.0
	v_cvt_scalef32_pk_f32_fp4 v[62:63], v104, 1.0 op_sel:[1,0,0]
	v_cvt_scalef32_pk_f32_fp4 v[64:65], v104, 1.0 op_sel:[0,1,0]
	v_cvt_scalef32_pk_f32_fp4 v[80:81], v104, 1.0 op_sel:[1,1,0]
	v_cvt_scalef32_pk_f32_fp4 v[82:83], v105, 1.0
	v_cvt_scalef32_pk_f32_fp4 v[84:85], v105, 1.0 op_sel:[1,0,0]
	v_cvt_scalef32_pk_f32_fp4 v[86:87], v105, 1.0 op_sel:[0,1,0]
	v_cvt_scalef32_pk_f32_fp4 v[88:89], v105, 1.0 op_sel:[1,1,0]
	v_pk_mul_f32 v[54:55], v[60:61], v[20:21]
	v_pk_mul_f32 v[52:53], v[62:63], v[22:23]
	v_pk_mul_f32 v[58:59], v[64:65], v[24:25]
	v_pk_mul_f32 v[56:57], v[80:81], v[26:27]
	v_cvt_scalef32_pk_f32_fp4 v[60:61], v106, 1.0
	v_cvt_scalef32_pk_f32_fp4 v[62:63], v106, 1.0 op_sel:[1,0,0]
	v_cvt_scalef32_pk_f32_fp4 v[64:65], v106, 1.0 op_sel:[0,1,0]
	v_cvt_scalef32_pk_f32_fp4 v[80:81], v106, 1.0 op_sel:[1,1,0]
	v_pk_fma_f32 v[54:55], v[82:83], v[28:29], v[54:55]
	v_pk_fma_f32 v[52:53], v[84:85], v[30:31], v[52:53]
	v_pk_fma_f32 v[58:59], v[86:87], v[32:33], v[58:59]
	v_pk_fma_f32 v[56:57], v[88:89], v[34:35], v[56:57]
	v_cvt_scalef32_pk_f32_fp4 v[82:83], v107, 1.0
	v_cvt_scalef32_pk_f32_fp4 v[84:85], v107, 1.0 op_sel:[1,0,0]
	v_cvt_scalef32_pk_f32_fp4 v[86:87], v107, 1.0 op_sel:[0,1,0]
	v_cvt_scalef32_pk_f32_fp4 v[88:89], v107, 1.0 op_sel:[1,1,0]
	v_pk_fma_f32 v[54:55], v[60:61], v[36:37], v[54:55]
	v_pk_fma_f32 v[52:53], v[62:63], v[38:39], v[52:53]
	v_pk_fma_f32 v[58:59], v[64:65], v[40:41], v[58:59]
	v_pk_fma_f32 v[56:57], v[80:81], v[42:43], v[56:57]
	v_pk_fma_f32 v[54:55], v[82:83], v[44:45], v[54:55]
	v_pk_fma_f32 v[52:53], v[84:85], v[46:47], v[52:53]
	v_pk_fma_f32 v[58:59], v[86:87], v[48:49], v[58:59]
	v_pk_fma_f32 v[56:57], v[88:89], v[50:51], v[56:57]
	global_load_dwordx4 v[104:107], v3, s[40:41]
	v_pk_add_f32 v[54:55], v[54:55], v[52:53]
	v_pk_add_f32 v[58:59], v[58:59], v[56:57]
	v_pk_add_f32 v[54:55], v[54:55], v[58:59]
	v_add_f32_e32 v91, v54, v55
	s_waitcnt vmcnt(15)
	v_cvt_scalef32_pk_f32_fp4 v[60:61], v108, 1.0
	v_cvt_scalef32_pk_f32_fp4 v[62:63], v108, 1.0 op_sel:[1,0,0]
	v_cvt_scalef32_pk_f32_fp4 v[64:65], v108, 1.0 op_sel:[0,1,0]
	v_cvt_scalef32_pk_f32_fp4 v[80:81], v108, 1.0 op_sel:[1,1,0]
	v_cvt_scalef32_pk_f32_fp4 v[82:83], v109, 1.0
	v_cvt_scalef32_pk_f32_fp4 v[84:85], v109, 1.0 op_sel:[1,0,0]
	v_cvt_scalef32_pk_f32_fp4 v[86:87], v109, 1.0 op_sel:[0,1,0]
	v_cvt_scalef32_pk_f32_fp4 v[88:89], v109, 1.0 op_sel:[1,1,0]
	v_pk_mul_f32 v[54:55], v[60:61], v[20:21]
	v_pk_mul_f32 v[52:53], v[62:63], v[22:23]
	v_pk_mul_f32 v[58:59], v[64:65], v[24:25]
	v_pk_mul_f32 v[56:57], v[80:81], v[26:27]
	v_cvt_scalef32_pk_f32_fp4 v[60:61], v110, 1.0
	v_cvt_scalef32_pk_f32_fp4 v[62:63], v110, 1.0 op_sel:[1,0,0]
	v_cvt_scalef32_pk_f32_fp4 v[64:65], v110, 1.0 op_sel:[0,1,0]
	v_cvt_scalef32_pk_f32_fp4 v[80:81], v110, 1.0 op_sel:[1,1,0]
	v_pk_fma_f32 v[54:55], v[82:83], v[28:29], v[54:55]
	v_pk_fma_f32 v[52:53], v[84:85], v[30:31], v[52:53]
	v_pk_fma_f32 v[58:59], v[86:87], v[32:33], v[58:59]
	v_pk_fma_f32 v[56:57], v[88:89], v[34:35], v[56:57]
	v_cvt_scalef32_pk_f32_fp4 v[82:83], v111, 1.0
	v_cvt_scalef32_pk_f32_fp4 v[84:85], v111, 1.0 op_sel:[1,0,0]
	v_cvt_scalef32_pk_f32_fp4 v[86:87], v111, 1.0 op_sel:[0,1,0]
	v_cvt_scalef32_pk_f32_fp4 v[88:89], v111, 1.0 op_sel:[1,1,0]
	v_pk_fma_f32 v[54:55], v[60:61], v[36:37], v[54:55]
	v_pk_fma_f32 v[52:53], v[62:63], v[38:39], v[52:53]
	v_pk_fma_f32 v[58:59], v[64:65], v[40:41], v[58:59]
	v_pk_fma_f32 v[56:57], v[80:81], v[42:43], v[56:57]
	v_pk_fma_f32 v[54:55], v[82:83], v[44:45], v[54:55]
	v_pk_fma_f32 v[52:53], v[84:85], v[46:47], v[52:53]
	v_pk_fma_f32 v[58:59], v[86:87], v[48:49], v[58:59]
	v_pk_fma_f32 v[56:57], v[88:89], v[50:51], v[56:57]
	global_load_dwordx4 v[108:111], v4, s[40:41]
	v_pk_add_f32 v[54:55], v[54:55], v[52:53]
	v_pk_add_f32 v[58:59], v[58:59], v[56:57]
	v_pk_add_f32 v[54:55], v[54:55], v[58:59]
	v_add_f32_e32 v92, v54, v55
	s_waitcnt vmcnt(15)
	v_cvt_scalef32_pk_f32_fp4 v[60:61], v112, 1.0
	v_cvt_scalef32_pk_f32_fp4 v[62:63], v112, 1.0 op_sel:[1,0,0]
	v_cvt_scalef32_pk_f32_fp4 v[64:65], v112, 1.0 op_sel:[0,1,0]
	v_cvt_scalef32_pk_f32_fp4 v[80:81], v112, 1.0 op_sel:[1,1,0]
	v_cvt_scalef32_pk_f32_fp4 v[82:83], v113, 1.0
	v_cvt_scalef32_pk_f32_fp4 v[84:85], v113, 1.0 op_sel:[1,0,0]
	v_cvt_scalef32_pk_f32_fp4 v[86:87], v113, 1.0 op_sel:[0,1,0]
	v_cvt_scalef32_pk_f32_fp4 v[88:89], v113, 1.0 op_sel:[1,1,0]
	v_pk_mul_f32 v[54:55], v[60:61], v[20:21]
	v_pk_mul_f32 v[52:53], v[62:63], v[22:23]
	v_pk_mul_f32 v[58:59], v[64:65], v[24:25]
	v_pk_mul_f32 v[56:57], v[80:81], v[26:27]
	v_cvt_scalef32_pk_f32_fp4 v[60:61], v114, 1.0
	v_cvt_scalef32_pk_f32_fp4 v[62:63], v114, 1.0 op_sel:[1,0,0]
	v_cvt_scalef32_pk_f32_fp4 v[64:65], v114, 1.0 op_sel:[0,1,0]
	v_cvt_scalef32_pk_f32_fp4 v[80:81], v114, 1.0 op_sel:[1,1,0]
	v_pk_fma_f32 v[54:55], v[82:83], v[28:29], v[54:55]
	v_pk_fma_f32 v[52:53], v[84:85], v[30:31], v[52:53]
	v_pk_fma_f32 v[58:59], v[86:87], v[32:33], v[58:59]
	v_pk_fma_f32 v[56:57], v[88:89], v[34:35], v[56:57]
	v_cvt_scalef32_pk_f32_fp4 v[82:83], v115, 1.0
	v_cvt_scalef32_pk_f32_fp4 v[84:85], v115, 1.0 op_sel:[1,0,0]
	v_cvt_scalef32_pk_f32_fp4 v[86:87], v115, 1.0 op_sel:[0,1,0]
	v_cvt_scalef32_pk_f32_fp4 v[88:89], v115, 1.0 op_sel:[1,1,0]
	v_pk_fma_f32 v[54:55], v[60:61], v[36:37], v[54:55]
	v_pk_fma_f32 v[52:53], v[62:63], v[38:39], v[52:53]
	v_pk_fma_f32 v[58:59], v[64:65], v[40:41], v[58:59]
	v_pk_fma_f32 v[56:57], v[80:81], v[42:43], v[56:57]
	v_pk_fma_f32 v[54:55], v[82:83], v[44:45], v[54:55]
	v_pk_fma_f32 v[52:53], v[84:85], v[46:47], v[52:53]
	v_pk_fma_f32 v[58:59], v[86:87], v[48:49], v[58:59]
	v_pk_fma_f32 v[56:57], v[88:89], v[50:51], v[56:57]
	global_load_dwordx4 v[112:115], v5, s[40:41]
	v_pk_add_f32 v[54:55], v[54:55], v[52:53]
	v_pk_add_f32 v[58:59], v[58:59], v[56:57]
	v_pk_add_f32 v[54:55], v[54:55], v[58:59]
	v_add_f32_e32 v93, v54, v55
	s_waitcnt vmcnt(15)
	v_cvt_scalef32_pk_f32_fp4 v[60:61], v116, 1.0
	v_cvt_scalef32_pk_f32_fp4 v[62:63], v116, 1.0 op_sel:[1,0,0]
	v_cvt_scalef32_pk_f32_fp4 v[64:65], v116, 1.0 op_sel:[0,1,0]
	v_cvt_scalef32_pk_f32_fp4 v[80:81], v116, 1.0 op_sel:[1,1,0]
	v_cvt_scalef32_pk_f32_fp4 v[82:83], v117, 1.0
	v_cvt_scalef32_pk_f32_fp4 v[84:85], v117, 1.0 op_sel:[1,0,0]
	v_cvt_scalef32_pk_f32_fp4 v[86:87], v117, 1.0 op_sel:[0,1,0]
	v_cvt_scalef32_pk_f32_fp4 v[88:89], v117, 1.0 op_sel:[1,1,0]
	v_pk_mul_f32 v[54:55], v[60:61], v[20:21]
	v_pk_mul_f32 v[52:53], v[62:63], v[22:23]
	v_pk_mul_f32 v[58:59], v[64:65], v[24:25]
	v_pk_mul_f32 v[56:57], v[80:81], v[26:27]
	v_cvt_scalef32_pk_f32_fp4 v[60:61], v118, 1.0
	v_cvt_scalef32_pk_f32_fp4 v[62:63], v118, 1.0 op_sel:[1,0,0]
	v_cvt_scalef32_pk_f32_fp4 v[64:65], v118, 1.0 op_sel:[0,1,0]
	v_cvt_scalef32_pk_f32_fp4 v[80:81], v118, 1.0 op_sel:[1,1,0]
	v_pk_fma_f32 v[54:55], v[82:83], v[28:29], v[54:55]
	v_pk_fma_f32 v[52:53], v[84:85], v[30:31], v[52:53]
	v_pk_fma_f32 v[58:59], v[86:87], v[32:33], v[58:59]
	v_pk_fma_f32 v[56:57], v[88:89], v[34:35], v[56:57]
	v_cvt_scalef32_pk_f32_fp4 v[82:83], v119, 1.0
	v_cvt_scalef32_pk_f32_fp4 v[84:85], v119, 1.0 op_sel:[1,0,0]
	v_cvt_scalef32_pk_f32_fp4 v[86:87], v119, 1.0 op_sel:[0,1,0]
	v_cvt_scalef32_pk_f32_fp4 v[88:89], v119, 1.0 op_sel:[1,1,0]
	v_pk_fma_f32 v[54:55], v[60:61], v[36:37], v[54:55]
	v_pk_fma_f32 v[52:53], v[62:63], v[38:39], v[52:53]
	v_pk_fma_f32 v[58:59], v[64:65], v[40:41], v[58:59]
	v_pk_fma_f32 v[56:57], v[80:81], v[42:43], v[56:57]
	v_pk_fma_f32 v[54:55], v[82:83], v[44:45], v[54:55]
	v_pk_fma_f32 v[52:53], v[84:85], v[46:47], v[52:53]
	v_pk_fma_f32 v[58:59], v[86:87], v[48:49], v[58:59]
	v_pk_fma_f32 v[56:57], v[88:89], v[50:51], v[56:57]
	global_load_dwordx4 v[116:119], v6, s[40:41]
	v_pk_add_f32 v[54:55], v[54:55], v[52:53]
	v_pk_add_f32 v[58:59], v[58:59], v[56:57]
	v_pk_add_f32 v[54:55], v[54:55], v[58:59]
	v_add_f32_e32 v94, v54, v55
	s_waitcnt vmcnt(15)
	v_cvt_scalef32_pk_f32_fp4 v[60:61], v120, 1.0
	v_cvt_scalef32_pk_f32_fp4 v[62:63], v120, 1.0 op_sel:[1,0,0]
	v_cvt_scalef32_pk_f32_fp4 v[64:65], v120, 1.0 op_sel:[0,1,0]
	v_cvt_scalef32_pk_f32_fp4 v[80:81], v120, 1.0 op_sel:[1,1,0]
	v_cvt_scalef32_pk_f32_fp4 v[82:83], v121, 1.0
	v_cvt_scalef32_pk_f32_fp4 v[84:85], v121, 1.0 op_sel:[1,0,0]
	v_cvt_scalef32_pk_f32_fp4 v[86:87], v121, 1.0 op_sel:[0,1,0]
	v_cvt_scalef32_pk_f32_fp4 v[88:89], v121, 1.0 op_sel:[1,1,0]
	v_pk_mul_f32 v[54:55], v[60:61], v[20:21]
	v_pk_mul_f32 v[52:53], v[62:63], v[22:23]
	v_pk_mul_f32 v[58:59], v[64:65], v[24:25]
	v_pk_mul_f32 v[56:57], v[80:81], v[26:27]
	v_cvt_scalef32_pk_f32_fp4 v[60:61], v122, 1.0
	v_cvt_scalef32_pk_f32_fp4 v[62:63], v122, 1.0 op_sel:[1,0,0]
	v_cvt_scalef32_pk_f32_fp4 v[64:65], v122, 1.0 op_sel:[0,1,0]
	v_cvt_scalef32_pk_f32_fp4 v[80:81], v122, 1.0 op_sel:[1,1,0]
	v_pk_fma_f32 v[54:55], v[82:83], v[28:29], v[54:55]
	v_pk_fma_f32 v[52:53], v[84:85], v[30:31], v[52:53]
	v_pk_fma_f32 v[58:59], v[86:87], v[32:33], v[58:59]
	v_pk_fma_f32 v[56:57], v[88:89], v[34:35], v[56:57]
	v_cvt_scalef32_pk_f32_fp4 v[82:83], v123, 1.0
	v_cvt_scalef32_pk_f32_fp4 v[84:85], v123, 1.0 op_sel:[1,0,0]
	v_cvt_scalef32_pk_f32_fp4 v[86:87], v123, 1.0 op_sel:[0,1,0]
	v_cvt_scalef32_pk_f32_fp4 v[88:89], v123, 1.0 op_sel:[1,1,0]
	v_pk_fma_f32 v[54:55], v[60:61], v[36:37], v[54:55]
	v_pk_fma_f32 v[52:53], v[62:63], v[38:39], v[52:53]
	v_pk_fma_f32 v[58:59], v[64:65], v[40:41], v[58:59]
	v_pk_fma_f32 v[56:57], v[80:81], v[42:43], v[56:57]
	v_pk_fma_f32 v[54:55], v[82:83], v[44:45], v[54:55]
	v_pk_fma_f32 v[52:53], v[84:85], v[46:47], v[52:53]
	v_pk_fma_f32 v[58:59], v[86:87], v[48:49], v[58:59]
	v_pk_fma_f32 v[56:57], v[88:89], v[50:51], v[56:57]
	global_load_dwordx4 v[120:123], v7, s[40:41]
	v_pk_add_f32 v[54:55], v[54:55], v[52:53]
	v_pk_add_f32 v[58:59], v[58:59], v[56:57]
	v_pk_add_f32 v[54:55], v[54:55], v[58:59]
	v_add_f32_e32 v95, v54, v55
	s_waitcnt vmcnt(15)
	v_cvt_scalef32_pk_f32_fp4 v[60:61], v124, 1.0
	v_cvt_scalef32_pk_f32_fp4 v[62:63], v124, 1.0 op_sel:[1,0,0]
	v_cvt_scalef32_pk_f32_fp4 v[64:65], v124, 1.0 op_sel:[0,1,0]
	v_cvt_scalef32_pk_f32_fp4 v[80:81], v124, 1.0 op_sel:[1,1,0]
	v_cvt_scalef32_pk_f32_fp4 v[82:83], v125, 1.0
	v_cvt_scalef32_pk_f32_fp4 v[84:85], v125, 1.0 op_sel:[1,0,0]
	v_cvt_scalef32_pk_f32_fp4 v[86:87], v125, 1.0 op_sel:[0,1,0]
	v_cvt_scalef32_pk_f32_fp4 v[88:89], v125, 1.0 op_sel:[1,1,0]
	v_pk_mul_f32 v[54:55], v[60:61], v[20:21]
	v_pk_mul_f32 v[52:53], v[62:63], v[22:23]
	v_pk_mul_f32 v[58:59], v[64:65], v[24:25]
	v_pk_mul_f32 v[56:57], v[80:81], v[26:27]
	v_cvt_scalef32_pk_f32_fp4 v[60:61], v126, 1.0
	v_cvt_scalef32_pk_f32_fp4 v[62:63], v126, 1.0 op_sel:[1,0,0]
	v_cvt_scalef32_pk_f32_fp4 v[64:65], v126, 1.0 op_sel:[0,1,0]
	v_cvt_scalef32_pk_f32_fp4 v[80:81], v126, 1.0 op_sel:[1,1,0]
	v_pk_fma_f32 v[54:55], v[82:83], v[28:29], v[54:55]
	v_pk_fma_f32 v[52:53], v[84:85], v[30:31], v[52:53]
	v_pk_fma_f32 v[58:59], v[86:87], v[32:33], v[58:59]
	v_pk_fma_f32 v[56:57], v[88:89], v[34:35], v[56:57]
	v_cvt_scalef32_pk_f32_fp4 v[82:83], v127, 1.0
	v_cvt_scalef32_pk_f32_fp4 v[84:85], v127, 1.0 op_sel:[1,0,0]
	v_cvt_scalef32_pk_f32_fp4 v[86:87], v127, 1.0 op_sel:[0,1,0]
	v_cvt_scalef32_pk_f32_fp4 v[88:89], v127, 1.0 op_sel:[1,1,0]
	v_pk_fma_f32 v[54:55], v[60:61], v[36:37], v[54:55]
	v_pk_fma_f32 v[52:53], v[62:63], v[38:39], v[52:53]
	v_pk_fma_f32 v[58:59], v[64:65], v[40:41], v[58:59]
	v_pk_fma_f32 v[56:57], v[80:81], v[42:43], v[56:57]
	v_pk_fma_f32 v[54:55], v[82:83], v[44:45], v[54:55]
	v_pk_fma_f32 v[52:53], v[84:85], v[46:47], v[52:53]
	v_pk_fma_f32 v[58:59], v[86:87], v[48:49], v[58:59]
	v_pk_fma_f32 v[56:57], v[88:89], v[50:51], v[56:57]
	global_load_dwordx4 v[124:127], v8, s[40:41]
	v_pk_add_f32 v[54:55], v[54:55], v[52:53]
	v_pk_add_f32 v[58:59], v[58:59], v[56:57]
	v_pk_add_f32 v[54:55], v[54:55], v[58:59]
	v_add_f32_e32 v96, v54, v55
	s_waitcnt vmcnt(15)
	v_cvt_scalef32_pk_f32_fp4 v[60:61], v128, 1.0
	v_cvt_scalef32_pk_f32_fp4 v[62:63], v128, 1.0 op_sel:[1,0,0]
	v_cvt_scalef32_pk_f32_fp4 v[64:65], v128, 1.0 op_sel:[0,1,0]
	v_cvt_scalef32_pk_f32_fp4 v[80:81], v128, 1.0 op_sel:[1,1,0]
	v_cvt_scalef32_pk_f32_fp4 v[82:83], v129, 1.0
	v_cvt_scalef32_pk_f32_fp4 v[84:85], v129, 1.0 op_sel:[1,0,0]
	v_cvt_scalef32_pk_f32_fp4 v[86:87], v129, 1.0 op_sel:[0,1,0]
	v_cvt_scalef32_pk_f32_fp4 v[88:89], v129, 1.0 op_sel:[1,1,0]
	v_pk_mul_f32 v[54:55], v[60:61], v[20:21]
	v_pk_mul_f32 v[52:53], v[62:63], v[22:23]
	v_pk_mul_f32 v[58:59], v[64:65], v[24:25]
	v_pk_mul_f32 v[56:57], v[80:81], v[26:27]
	v_cvt_scalef32_pk_f32_fp4 v[60:61], v130, 1.0
	v_cvt_scalef32_pk_f32_fp4 v[62:63], v130, 1.0 op_sel:[1,0,0]
	v_cvt_scalef32_pk_f32_fp4 v[64:65], v130, 1.0 op_sel:[0,1,0]
	v_cvt_scalef32_pk_f32_fp4 v[80:81], v130, 1.0 op_sel:[1,1,0]
	v_pk_fma_f32 v[54:55], v[82:83], v[28:29], v[54:55]
	v_pk_fma_f32 v[52:53], v[84:85], v[30:31], v[52:53]
	v_pk_fma_f32 v[58:59], v[86:87], v[32:33], v[58:59]
	v_pk_fma_f32 v[56:57], v[88:89], v[34:35], v[56:57]
	v_cvt_scalef32_pk_f32_fp4 v[82:83], v131, 1.0
	v_cvt_scalef32_pk_f32_fp4 v[84:85], v131, 1.0 op_sel:[1,0,0]
	v_cvt_scalef32_pk_f32_fp4 v[86:87], v131, 1.0 op_sel:[0,1,0]
	v_cvt_scalef32_pk_f32_fp4 v[88:89], v131, 1.0 op_sel:[1,1,0]
	v_pk_fma_f32 v[54:55], v[60:61], v[36:37], v[54:55]
	v_pk_fma_f32 v[52:53], v[62:63], v[38:39], v[52:53]
	v_pk_fma_f32 v[58:59], v[64:65], v[40:41], v[58:59]
	v_pk_fma_f32 v[56:57], v[80:81], v[42:43], v[56:57]
	v_pk_fma_f32 v[54:55], v[82:83], v[44:45], v[54:55]
	v_pk_fma_f32 v[52:53], v[84:85], v[46:47], v[52:53]
	v_pk_fma_f32 v[58:59], v[86:87], v[48:49], v[58:59]
	v_pk_fma_f32 v[56:57], v[88:89], v[50:51], v[56:57]
	global_load_dwordx4 v[128:131], v9, s[40:41]
	v_pk_add_f32 v[54:55], v[54:55], v[52:53]
	v_pk_add_f32 v[58:59], v[58:59], v[56:57]
	v_pk_add_f32 v[54:55], v[54:55], v[58:59]
	v_add_f32_e32 v97, v54, v55
	ds_read_b32 v99, v167 offset:0
	s_nop 0
	v_add_f32_dpp v10, v90, v90 row_shl:4 row_mask:0xf bank_mask:0x5
	v_add_f32_dpp v10, v91, v91 row_shr:4 row_mask:0xf bank_mask:0xa
	v_add_f32_dpp v11, v92, v92 row_shl:4 row_mask:0xf bank_mask:0x5
	v_add_f32_dpp v11, v93, v93 row_shr:4 row_mask:0xf bank_mask:0xa
	v_add_f32_dpp v12, v94, v94 row_shl:4 row_mask:0xf bank_mask:0x5
	v_add_f32_dpp v12, v95, v95 row_shr:4 row_mask:0xf bank_mask:0xa
	v_add_f32_dpp v13, v96, v96 row_shl:4 row_mask:0xf bank_mask:0x5
	v_add_f32_dpp v13, v97, v97 row_shr:4 row_mask:0xf bank_mask:0xa
	v_cndmask_b32_e64 v16, v10, v11, s[36:37]
	v_cndmask_b32_e64 v17, v11, v10, s[36:37]
	s_nop 1
	v_add_f32_dpp v14, v17, v16 quad_perm:[2,3,0,1] row_mask:0xf bank_mask:0xf
	v_cndmask_b32_e64 v16, v12, v13, s[36:37]
	v_cndmask_b32_e64 v17, v13, v12, s[36:37]
	s_nop 1
	v_add_f32_dpp v15, v17, v16 quad_perm:[2,3,0,1] row_mask:0xf bank_mask:0xf
	v_cndmask_b32_e64 v16, v14, v15, s[38:39]
	v_cndmask_b32_e64 v17, v15, v14, s[38:39]
	s_nop 1
	v_add_f32_dpp v98, v17, v16 quad_perm:[1,0,3,2] row_mask:0xf bank_mask:0xf
	s_waitcnt lgkmcnt(0)
	v_add_f32_e32 v99, v99, v98
	ds_write_b32 v167, v99 offset:0
	s_lshl_b32 s100, s14, 1
	s_add_i32 s100, s100, 3
	s_lshr_b32 s101, s100, 4
	s_and_b32 s100, s100, 15
	s_lshl_b32 s100, s100, 5
	v_add_u32_e32 v1, s100, v164
	s_add_i32 s101, s101, s13
	s_min_u32 s101, s101, 7
	s_lshl_b32 s101, s101, 21
	s_add_u32 s40, s56, s101
	s_addc_u32 s41, s57, 0
	ds_read_b128 v[2:5], v1 offset:0
	ds_read_b128 v[6:9], v1 offset:16
	s_waitcnt vmcnt(15)
	v_cvt_scalef32_pk_f32_fp4 v[60:61], v132, 1.0
	v_cvt_scalef32_pk_f32_fp4 v[62:63], v132, 1.0 op_sel:[1,0,0]
	v_cvt_scalef32_pk_f32_fp4 v[64:65], v132, 1.0 op_sel:[0,1,0]
	v_cvt_scalef32_pk_f32_fp4 v[80:81], v132, 1.0 op_sel:[1,1,0]
	v_cvt_scalef32_pk_f32_fp4 v[82:83], v133, 1.0
	v_cvt_scalef32_pk_f32_fp4 v[84:85], v133, 1.0 op_sel:[1,0,0]
	v_cvt_scalef32_pk_f32_fp4 v[86:87], v133, 1.0 op_sel:[0,1,0]
	v_cvt_scalef32_pk_f32_fp4 v[88:89], v133, 1.0 op_sel:[1,1,0]
	v_pk_mul_f32 v[54:55], v[60:61], v[20:21]
	v_pk_mul_f32 v[52:53], v[62:63], v[22:23]
	v_pk_mul_f32 v[58:59], v[64:65], v[24:25]
	v_pk_mul_f32 v[56:57], v[80:81], v[26:27]
	v_cvt_scalef32_pk_f32_fp4 v[60:61], v134, 1.0
	v_cvt_scalef32_pk_f32_fp4 v[62:63], v134, 1.0 op_sel:[1,0,0]
	v_cvt_scalef32_pk_f32_fp4 v[64:65], v134, 1.0 op_sel:[0,1,0]
	v_cvt_scalef32_pk_f32_fp4 v[80:81], v134, 1.0 op_sel:[1,1,0]
	v_pk_fma_f32 v[54:55], v[82:83], v[28:29], v[54:55]
	v_pk_fma_f32 v[52:53], v[84:85], v[30:31], v[52:53]
	v_pk_fma_f32 v[58:59], v[86:87], v[32:33], v[58:59]
	v_pk_fma_f32 v[56:57], v[88:89], v[34:35], v[56:57]
	v_cvt_scalef32_pk_f32_fp4 v[82:83], v135, 1.0
	v_cvt_scalef32_pk_f32_fp4 v[84:85], v135, 1.0 op_sel:[1,0,0]
	v_cvt_scalef32_pk_f32_fp4 v[86:87], v135, 1.0 op_sel:[0,1,0]
	v_cvt_scalef32_pk_f32_fp4 v[88:89], v135, 1.0 op_sel:[1,1,0]
	v_pk_fma_f32 v[54:55], v[60:61], v[36:37], v[54:55]
	v_pk_fma_f32 v[52:53], v[62:63], v[38:39], v[52:53]
	v_pk_fma_f32 v[58:59], v[64:65], v[40:41], v[58:59]
	v_pk_fma_f32 v[56:57], v[80:81], v[42:43], v[56:57]
	v_pk_fma_f32 v[54:55], v[82:83], v[44:45], v[54:55]
	v_pk_fma_f32 v[52:53], v[84:85], v[46:47], v[52:53]
	v_pk_fma_f32 v[58:59], v[86:87], v[48:49], v[58:59]
	v_pk_fma_f32 v[56:57], v[88:89], v[50:51], v[56:57]
	s_waitcnt lgkmcnt(0)
	v_lshl_add_u32 v2, v2, 7, v78
	v_lshl_add_u32 v3, v3, 7, v78
	v_lshl_add_u32 v4, v4, 7, v78
	v_lshl_add_u32 v5, v5, 7, v78
	v_lshl_add_u32 v6, v6, 7, v78
	v_lshl_add_u32 v7, v7, 7, v78
	v_lshl_add_u32 v8, v8, 7, v78
	v_lshl_add_u32 v9, v9, 7, v78
	global_load_dwordx4 v[132:135], v2, s[40:41]
	v_pk_add_f32 v[54:55], v[54:55], v[52:53]
	v_pk_add_f32 v[58:59], v[58:59], v[56:57]
	v_pk_add_f32 v[54:55], v[54:55], v[58:59]
	v_add_f32_e32 v90, v54, v55
	s_waitcnt vmcnt(15)
	v_cvt_scalef32_pk_f32_fp4 v[60:61], v136, 1.0
	v_cvt_scalef32_pk_f32_fp4 v[62:63], v136, 1.0 op_sel:[1,0,0]
	v_cvt_scalef32_pk_f32_fp4 v[64:65], v136, 1.0 op_sel:[0,1,0]
	v_cvt_scalef32_pk_f32_fp4 v[80:81], v136, 1.0 op_sel:[1,1,0]
	v_cvt_scalef32_pk_f32_fp4 v[82:83], v137, 1.0
	v_cvt_scalef32_pk_f32_fp4 v[84:85], v137, 1.0 op_sel:[1,0,0]
	v_cvt_scalef32_pk_f32_fp4 v[86:87], v137, 1.0 op_sel:[0,1,0]
	v_cvt_scalef32_pk_f32_fp4 v[88:89], v137, 1.0 op_sel:[1,1,0]
	v_pk_mul_f32 v[54:55], v[60:61], v[20:21]
	v_pk_mul_f32 v[52:53], v[62:63], v[22:23]
	v_pk_mul_f32 v[58:59], v[64:65], v[24:25]
	v_pk_mul_f32 v[56:57], v[80:81], v[26:27]
	v_cvt_scalef32_pk_f32_fp4 v[60:61], v138, 1.0
	v_cvt_scalef32_pk_f32_fp4 v[62:63], v138, 1.0 op_sel:[1,0,0]
	v_cvt_scalef32_pk_f32_fp4 v[64:65], v138, 1.0 op_sel:[0,1,0]
	v_cvt_scalef32_pk_f32_fp4 v[80:81], v138, 1.0 op_sel:[1,1,0]
	v_pk_fma_f32 v[54:55], v[82:83], v[28:29], v[54:55]
	v_pk_fma_f32 v[52:53], v[84:85], v[30:31], v[52:53]
	v_pk_fma_f32 v[58:59], v[86:87], v[32:33], v[58:59]
	v_pk_fma_f32 v[56:57], v[88:89], v[34:35], v[56:57]
	v_cvt_scalef32_pk_f32_fp4 v[82:83], v139, 1.0
	v_cvt_scalef32_pk_f32_fp4 v[84:85], v139, 1.0 op_sel:[1,0,0]
	v_cvt_scalef32_pk_f32_fp4 v[86:87], v139, 1.0 op_sel:[0,1,0]
	v_cvt_scalef32_pk_f32_fp4 v[88:89], v139, 1.0 op_sel:[1,1,0]
	v_pk_fma_f32 v[54:55], v[60:61], v[36:37], v[54:55]
	v_pk_fma_f32 v[52:53], v[62:63], v[38:39], v[52:53]
	v_pk_fma_f32 v[58:59], v[64:65], v[40:41], v[58:59]
	v_pk_fma_f32 v[56:57], v[80:81], v[42:43], v[56:57]
	v_pk_fma_f32 v[54:55], v[82:83], v[44:45], v[54:55]
	v_pk_fma_f32 v[52:53], v[84:85], v[46:47], v[52:53]
	v_pk_fma_f32 v[58:59], v[86:87], v[48:49], v[58:59]
	v_pk_fma_f32 v[56:57], v[88:89], v[50:51], v[56:57]
	global_load_dwordx4 v[136:139], v3, s[40:41]
	v_pk_add_f32 v[54:55], v[54:55], v[52:53]
	v_pk_add_f32 v[58:59], v[58:59], v[56:57]
	v_pk_add_f32 v[54:55], v[54:55], v[58:59]
	v_add_f32_e32 v91, v54, v55
	s_waitcnt vmcnt(15)
	v_cvt_scalef32_pk_f32_fp4 v[60:61], v140, 1.0
	v_cvt_scalef32_pk_f32_fp4 v[62:63], v140, 1.0 op_sel:[1,0,0]
	v_cvt_scalef32_pk_f32_fp4 v[64:65], v140, 1.0 op_sel:[0,1,0]
	v_cvt_scalef32_pk_f32_fp4 v[80:81], v140, 1.0 op_sel:[1,1,0]
	v_cvt_scalef32_pk_f32_fp4 v[82:83], v141, 1.0
	v_cvt_scalef32_pk_f32_fp4 v[84:85], v141, 1.0 op_sel:[1,0,0]
	v_cvt_scalef32_pk_f32_fp4 v[86:87], v141, 1.0 op_sel:[0,1,0]
	v_cvt_scalef32_pk_f32_fp4 v[88:89], v141, 1.0 op_sel:[1,1,0]
	v_pk_mul_f32 v[54:55], v[60:61], v[20:21]
	v_pk_mul_f32 v[52:53], v[62:63], v[22:23]
	v_pk_mul_f32 v[58:59], v[64:65], v[24:25]
	v_pk_mul_f32 v[56:57], v[80:81], v[26:27]
	v_cvt_scalef32_pk_f32_fp4 v[60:61], v142, 1.0
	v_cvt_scalef32_pk_f32_fp4 v[62:63], v142, 1.0 op_sel:[1,0,0]
	v_cvt_scalef32_pk_f32_fp4 v[64:65], v142, 1.0 op_sel:[0,1,0]
	v_cvt_scalef32_pk_f32_fp4 v[80:81], v142, 1.0 op_sel:[1,1,0]
	v_pk_fma_f32 v[54:55], v[82:83], v[28:29], v[54:55]
	v_pk_fma_f32 v[52:53], v[84:85], v[30:31], v[52:53]
	v_pk_fma_f32 v[58:59], v[86:87], v[32:33], v[58:59]
	v_pk_fma_f32 v[56:57], v[88:89], v[34:35], v[56:57]
	v_cvt_scalef32_pk_f32_fp4 v[82:83], v143, 1.0
	v_cvt_scalef32_pk_f32_fp4 v[84:85], v143, 1.0 op_sel:[1,0,0]
	v_cvt_scalef32_pk_f32_fp4 v[86:87], v143, 1.0 op_sel:[0,1,0]
	v_cvt_scalef32_pk_f32_fp4 v[88:89], v143, 1.0 op_sel:[1,1,0]
	v_pk_fma_f32 v[54:55], v[60:61], v[36:37], v[54:55]
	v_pk_fma_f32 v[52:53], v[62:63], v[38:39], v[52:53]
	v_pk_fma_f32 v[58:59], v[64:65], v[40:41], v[58:59]
	v_pk_fma_f32 v[56:57], v[80:81], v[42:43], v[56:57]
	v_pk_fma_f32 v[54:55], v[82:83], v[44:45], v[54:55]
	v_pk_fma_f32 v[52:53], v[84:85], v[46:47], v[52:53]
	v_pk_fma_f32 v[58:59], v[86:87], v[48:49], v[58:59]
	v_pk_fma_f32 v[56:57], v[88:89], v[50:51], v[56:57]
	global_load_dwordx4 v[140:143], v4, s[40:41]
	v_pk_add_f32 v[54:55], v[54:55], v[52:53]
	v_pk_add_f32 v[58:59], v[58:59], v[56:57]
	v_pk_add_f32 v[54:55], v[54:55], v[58:59]
	v_add_f32_e32 v92, v54, v55
	s_waitcnt vmcnt(15)
	v_cvt_scalef32_pk_f32_fp4 v[60:61], v144, 1.0
	v_cvt_scalef32_pk_f32_fp4 v[62:63], v144, 1.0 op_sel:[1,0,0]
	v_cvt_scalef32_pk_f32_fp4 v[64:65], v144, 1.0 op_sel:[0,1,0]
	v_cvt_scalef32_pk_f32_fp4 v[80:81], v144, 1.0 op_sel:[1,1,0]
	v_cvt_scalef32_pk_f32_fp4 v[82:83], v145, 1.0
	v_cvt_scalef32_pk_f32_fp4 v[84:85], v145, 1.0 op_sel:[1,0,0]
	v_cvt_scalef32_pk_f32_fp4 v[86:87], v145, 1.0 op_sel:[0,1,0]
	v_cvt_scalef32_pk_f32_fp4 v[88:89], v145, 1.0 op_sel:[1,1,0]
	v_pk_mul_f32 v[54:55], v[60:61], v[20:21]
	v_pk_mul_f32 v[52:53], v[62:63], v[22:23]
	v_pk_mul_f32 v[58:59], v[64:65], v[24:25]
	v_pk_mul_f32 v[56:57], v[80:81], v[26:27]
	v_cvt_scalef32_pk_f32_fp4 v[60:61], v146, 1.0
	v_cvt_scalef32_pk_f32_fp4 v[62:63], v146, 1.0 op_sel:[1,0,0]
	v_cvt_scalef32_pk_f32_fp4 v[64:65], v146, 1.0 op_sel:[0,1,0]
	v_cvt_scalef32_pk_f32_fp4 v[80:81], v146, 1.0 op_sel:[1,1,0]
	v_pk_fma_f32 v[54:55], v[82:83], v[28:29], v[54:55]
	v_pk_fma_f32 v[52:53], v[84:85], v[30:31], v[52:53]
	v_pk_fma_f32 v[58:59], v[86:87], v[32:33], v[58:59]
	v_pk_fma_f32 v[56:57], v[88:89], v[34:35], v[56:57]
	v_cvt_scalef32_pk_f32_fp4 v[82:83], v147, 1.0
	v_cvt_scalef32_pk_f32_fp4 v[84:85], v147, 1.0 op_sel:[1,0,0]
	v_cvt_scalef32_pk_f32_fp4 v[86:87], v147, 1.0 op_sel:[0,1,0]
	v_cvt_scalef32_pk_f32_fp4 v[88:89], v147, 1.0 op_sel:[1,1,0]
	v_pk_fma_f32 v[54:55], v[60:61], v[36:37], v[54:55]
	v_pk_fma_f32 v[52:53], v[62:63], v[38:39], v[52:53]
	v_pk_fma_f32 v[58:59], v[64:65], v[40:41], v[58:59]
	v_pk_fma_f32 v[56:57], v[80:81], v[42:43], v[56:57]
	v_pk_fma_f32 v[54:55], v[82:83], v[44:45], v[54:55]
	v_pk_fma_f32 v[52:53], v[84:85], v[46:47], v[52:53]
	v_pk_fma_f32 v[58:59], v[86:87], v[48:49], v[58:59]
	v_pk_fma_f32 v[56:57], v[88:89], v[50:51], v[56:57]
	global_load_dwordx4 v[144:147], v5, s[40:41]
	v_pk_add_f32 v[54:55], v[54:55], v[52:53]
	v_pk_add_f32 v[58:59], v[58:59], v[56:57]
	v_pk_add_f32 v[54:55], v[54:55], v[58:59]
	v_add_f32_e32 v93, v54, v55
	s_waitcnt vmcnt(15)
	v_cvt_scalef32_pk_f32_fp4 v[60:61], v148, 1.0
	v_cvt_scalef32_pk_f32_fp4 v[62:63], v148, 1.0 op_sel:[1,0,0]
	v_cvt_scalef32_pk_f32_fp4 v[64:65], v148, 1.0 op_sel:[0,1,0]
	v_cvt_scalef32_pk_f32_fp4 v[80:81], v148, 1.0 op_sel:[1,1,0]
	v_cvt_scalef32_pk_f32_fp4 v[82:83], v149, 1.0
	v_cvt_scalef32_pk_f32_fp4 v[84:85], v149, 1.0 op_sel:[1,0,0]
	v_cvt_scalef32_pk_f32_fp4 v[86:87], v149, 1.0 op_sel:[0,1,0]
	v_cvt_scalef32_pk_f32_fp4 v[88:89], v149, 1.0 op_sel:[1,1,0]
	v_pk_mul_f32 v[54:55], v[60:61], v[20:21]
	v_pk_mul_f32 v[52:53], v[62:63], v[22:23]
	v_pk_mul_f32 v[58:59], v[64:65], v[24:25]
	v_pk_mul_f32 v[56:57], v[80:81], v[26:27]
	v_cvt_scalef32_pk_f32_fp4 v[60:61], v150, 1.0
	v_cvt_scalef32_pk_f32_fp4 v[62:63], v150, 1.0 op_sel:[1,0,0]
	v_cvt_scalef32_pk_f32_fp4 v[64:65], v150, 1.0 op_sel:[0,1,0]
	v_cvt_scalef32_pk_f32_fp4 v[80:81], v150, 1.0 op_sel:[1,1,0]
	v_pk_fma_f32 v[54:55], v[82:83], v[28:29], v[54:55]
	v_pk_fma_f32 v[52:53], v[84:85], v[30:31], v[52:53]
	v_pk_fma_f32 v[58:59], v[86:87], v[32:33], v[58:59]
	v_pk_fma_f32 v[56:57], v[88:89], v[34:35], v[56:57]
	v_cvt_scalef32_pk_f32_fp4 v[82:83], v151, 1.0
	v_cvt_scalef32_pk_f32_fp4 v[84:85], v151, 1.0 op_sel:[1,0,0]
	v_cvt_scalef32_pk_f32_fp4 v[86:87], v151, 1.0 op_sel:[0,1,0]
	v_cvt_scalef32_pk_f32_fp4 v[88:89], v151, 1.0 op_sel:[1,1,0]
	v_pk_fma_f32 v[54:55], v[60:61], v[36:37], v[54:55]
	v_pk_fma_f32 v[52:53], v[62:63], v[38:39], v[52:53]
	v_pk_fma_f32 v[58:59], v[64:65], v[40:41], v[58:59]
	v_pk_fma_f32 v[56:57], v[80:81], v[42:43], v[56:57]
	v_pk_fma_f32 v[54:55], v[82:83], v[44:45], v[54:55]
	v_pk_fma_f32 v[52:53], v[84:85], v[46:47], v[52:53]
	v_pk_fma_f32 v[58:59], v[86:87], v[48:49], v[58:59]
	v_pk_fma_f32 v[56:57], v[88:89], v[50:51], v[56:57]
	global_load_dwordx4 v[148:151], v6, s[40:41]
	v_pk_add_f32 v[54:55], v[54:55], v[52:53]
	v_pk_add_f32 v[58:59], v[58:59], v[56:57]
	v_pk_add_f32 v[54:55], v[54:55], v[58:59]
	v_add_f32_e32 v94, v54, v55
	s_waitcnt vmcnt(15)
	v_cvt_scalef32_pk_f32_fp4 v[60:61], v152, 1.0
	v_cvt_scalef32_pk_f32_fp4 v[62:63], v152, 1.0 op_sel:[1,0,0]
	v_cvt_scalef32_pk_f32_fp4 v[64:65], v152, 1.0 op_sel:[0,1,0]
	v_cvt_scalef32_pk_f32_fp4 v[80:81], v152, 1.0 op_sel:[1,1,0]
	v_cvt_scalef32_pk_f32_fp4 v[82:83], v153, 1.0
	v_cvt_scalef32_pk_f32_fp4 v[84:85], v153, 1.0 op_sel:[1,0,0]
	v_cvt_scalef32_pk_f32_fp4 v[86:87], v153, 1.0 op_sel:[0,1,0]
	v_cvt_scalef32_pk_f32_fp4 v[88:89], v153, 1.0 op_sel:[1,1,0]
	v_pk_mul_f32 v[54:55], v[60:61], v[20:21]
	v_pk_mul_f32 v[52:53], v[62:63], v[22:23]
	v_pk_mul_f32 v[58:59], v[64:65], v[24:25]
	v_pk_mul_f32 v[56:57], v[80:81], v[26:27]
	v_cvt_scalef32_pk_f32_fp4 v[60:61], v154, 1.0
	v_cvt_scalef32_pk_f32_fp4 v[62:63], v154, 1.0 op_sel:[1,0,0]
	v_cvt_scalef32_pk_f32_fp4 v[64:65], v154, 1.0 op_sel:[0,1,0]
	v_cvt_scalef32_pk_f32_fp4 v[80:81], v154, 1.0 op_sel:[1,1,0]
	v_pk_fma_f32 v[54:55], v[82:83], v[28:29], v[54:55]
	v_pk_fma_f32 v[52:53], v[84:85], v[30:31], v[52:53]
	v_pk_fma_f32 v[58:59], v[86:87], v[32:33], v[58:59]
	v_pk_fma_f32 v[56:57], v[88:89], v[34:35], v[56:57]
	v_cvt_scalef32_pk_f32_fp4 v[82:83], v155, 1.0
	v_cvt_scalef32_pk_f32_fp4 v[84:85], v155, 1.0 op_sel:[1,0,0]
	v_cvt_scalef32_pk_f32_fp4 v[86:87], v155, 1.0 op_sel:[0,1,0]
	v_cvt_scalef32_pk_f32_fp4 v[88:89], v155, 1.0 op_sel:[1,1,0]
	v_pk_fma_f32 v[54:55], v[60:61], v[36:37], v[54:55]
	v_pk_fma_f32 v[52:53], v[62:63], v[38:39], v[52:53]
	v_pk_fma_f32 v[58:59], v[64:65], v[40:41], v[58:59]
	v_pk_fma_f32 v[56:57], v[80:81], v[42:43], v[56:57]
	v_pk_fma_f32 v[54:55], v[82:83], v[44:45], v[54:55]
	v_pk_fma_f32 v[52:53], v[84:85], v[46:47], v[52:53]
	v_pk_fma_f32 v[58:59], v[86:87], v[48:49], v[58:59]
	v_pk_fma_f32 v[56:57], v[88:89], v[50:51], v[56:57]
	global_load_dwordx4 v[152:155], v7, s[40:41]
	v_pk_add_f32 v[54:55], v[54:55], v[52:53]
	v_pk_add_f32 v[58:59], v[58:59], v[56:57]
	v_pk_add_f32 v[54:55], v[54:55], v[58:59]
	v_add_f32_e32 v95, v54, v55
	s_waitcnt vmcnt(15)
	v_cvt_scalef32_pk_f32_fp4 v[60:61], v156, 1.0
	v_cvt_scalef32_pk_f32_fp4 v[62:63], v156, 1.0 op_sel:[1,0,0]
	v_cvt_scalef32_pk_f32_fp4 v[64:65], v156, 1.0 op_sel:[0,1,0]
	v_cvt_scalef32_pk_f32_fp4 v[80:81], v156, 1.0 op_sel:[1,1,0]
	v_cvt_scalef32_pk_f32_fp4 v[82:83], v157, 1.0
	v_cvt_scalef32_pk_f32_fp4 v[84:85], v157, 1.0 op_sel:[1,0,0]
	v_cvt_scalef32_pk_f32_fp4 v[86:87], v157, 1.0 op_sel:[0,1,0]
	v_cvt_scalef32_pk_f32_fp4 v[88:89], v157, 1.0 op_sel:[1,1,0]
	v_pk_mul_f32 v[54:55], v[60:61], v[20:21]
	v_pk_mul_f32 v[52:53], v[62:63], v[22:23]
	v_pk_mul_f32 v[58:59], v[64:65], v[24:25]
	v_pk_mul_f32 v[56:57], v[80:81], v[26:27]
	v_cvt_scalef32_pk_f32_fp4 v[60:61], v158, 1.0
	v_cvt_scalef32_pk_f32_fp4 v[62:63], v158, 1.0 op_sel:[1,0,0]
	v_cvt_scalef32_pk_f32_fp4 v[64:65], v158, 1.0 op_sel:[0,1,0]
	v_cvt_scalef32_pk_f32_fp4 v[80:81], v158, 1.0 op_sel:[1,1,0]
	v_pk_fma_f32 v[54:55], v[82:83], v[28:29], v[54:55]
	v_pk_fma_f32 v[52:53], v[84:85], v[30:31], v[52:53]
	v_pk_fma_f32 v[58:59], v[86:87], v[32:33], v[58:59]
	v_pk_fma_f32 v[56:57], v[88:89], v[34:35], v[56:57]
	v_cvt_scalef32_pk_f32_fp4 v[82:83], v159, 1.0
	v_cvt_scalef32_pk_f32_fp4 v[84:85], v159, 1.0 op_sel:[1,0,0]
	v_cvt_scalef32_pk_f32_fp4 v[86:87], v159, 1.0 op_sel:[0,1,0]
	v_cvt_scalef32_pk_f32_fp4 v[88:89], v159, 1.0 op_sel:[1,1,0]
	v_pk_fma_f32 v[54:55], v[60:61], v[36:37], v[54:55]
	v_pk_fma_f32 v[52:53], v[62:63], v[38:39], v[52:53]
	v_pk_fma_f32 v[58:59], v[64:65], v[40:41], v[58:59]
	v_pk_fma_f32 v[56:57], v[80:81], v[42:43], v[56:57]
	v_pk_fma_f32 v[54:55], v[82:83], v[44:45], v[54:55]
	v_pk_fma_f32 v[52:53], v[84:85], v[46:47], v[52:53]
	v_pk_fma_f32 v[58:59], v[86:87], v[48:49], v[58:59]
	v_pk_fma_f32 v[56:57], v[88:89], v[50:51], v[56:57]
	global_load_dwordx4 v[156:159], v8, s[40:41]
	v_pk_add_f32 v[54:55], v[54:55], v[52:53]
	v_pk_add_f32 v[58:59], v[58:59], v[56:57]
	v_pk_add_f32 v[54:55], v[54:55], v[58:59]
	v_add_f32_e32 v96, v54, v55
	s_waitcnt vmcnt(15)
	v_cvt_scalef32_pk_f32_fp4 v[60:61], v160, 1.0
	v_cvt_scalef32_pk_f32_fp4 v[62:63], v160, 1.0 op_sel:[1,0,0]
	v_cvt_scalef32_pk_f32_fp4 v[64:65], v160, 1.0 op_sel:[0,1,0]
	v_cvt_scalef32_pk_f32_fp4 v[80:81], v160, 1.0 op_sel:[1,1,0]
	v_cvt_scalef32_pk_f32_fp4 v[82:83], v161, 1.0
	v_cvt_scalef32_pk_f32_fp4 v[84:85], v161, 1.0 op_sel:[1,0,0]
	v_cvt_scalef32_pk_f32_fp4 v[86:87], v161, 1.0 op_sel:[0,1,0]
	v_cvt_scalef32_pk_f32_fp4 v[88:89], v161, 1.0 op_sel:[1,1,0]
	v_pk_mul_f32 v[54:55], v[60:61], v[20:21]
	v_pk_mul_f32 v[52:53], v[62:63], v[22:23]
	v_pk_mul_f32 v[58:59], v[64:65], v[24:25]
	v_pk_mul_f32 v[56:57], v[80:81], v[26:27]
	v_cvt_scalef32_pk_f32_fp4 v[60:61], v162, 1.0
	v_cvt_scalef32_pk_f32_fp4 v[62:63], v162, 1.0 op_sel:[1,0,0]
	v_cvt_scalef32_pk_f32_fp4 v[64:65], v162, 1.0 op_sel:[0,1,0]
	v_cvt_scalef32_pk_f32_fp4 v[80:81], v162, 1.0 op_sel:[1,1,0]
	v_pk_fma_f32 v[54:55], v[82:83], v[28:29], v[54:55]
	v_pk_fma_f32 v[52:53], v[84:85], v[30:31], v[52:53]
	v_pk_fma_f32 v[58:59], v[86:87], v[32:33], v[58:59]
	v_pk_fma_f32 v[56:57], v[88:89], v[34:35], v[56:57]
	v_cvt_scalef32_pk_f32_fp4 v[82:83], v163, 1.0
	v_cvt_scalef32_pk_f32_fp4 v[84:85], v163, 1.0 op_sel:[1,0,0]
	v_cvt_scalef32_pk_f32_fp4 v[86:87], v163, 1.0 op_sel:[0,1,0]
	v_cvt_scalef32_pk_f32_fp4 v[88:89], v163, 1.0 op_sel:[1,1,0]
	v_pk_fma_f32 v[54:55], v[60:61], v[36:37], v[54:55]
	v_pk_fma_f32 v[52:53], v[62:63], v[38:39], v[52:53]
	v_pk_fma_f32 v[58:59], v[64:65], v[40:41], v[58:59]
	v_pk_fma_f32 v[56:57], v[80:81], v[42:43], v[56:57]
	v_pk_fma_f32 v[54:55], v[82:83], v[44:45], v[54:55]
	v_pk_fma_f32 v[52:53], v[84:85], v[46:47], v[52:53]
	v_pk_fma_f32 v[58:59], v[86:87], v[48:49], v[58:59]
	v_pk_fma_f32 v[56:57], v[88:89], v[50:51], v[56:57]
	global_load_dwordx4 v[160:163], v9, s[40:41]
	v_pk_add_f32 v[54:55], v[54:55], v[52:53]
	v_pk_add_f32 v[58:59], v[58:59], v[56:57]
	v_pk_add_f32 v[54:55], v[54:55], v[58:59]
	v_add_f32_e32 v97, v54, v55
	ds_read_b32 v99, v167 offset:256
	s_nop 0
	v_add_f32_dpp v10, v90, v90 row_shl:4 row_mask:0xf bank_mask:0x5
	v_add_f32_dpp v10, v91, v91 row_shr:4 row_mask:0xf bank_mask:0xa
	v_add_f32_dpp v11, v92, v92 row_shl:4 row_mask:0xf bank_mask:0x5
	v_add_f32_dpp v11, v93, v93 row_shr:4 row_mask:0xf bank_mask:0xa
	v_add_f32_dpp v12, v94, v94 row_shl:4 row_mask:0xf bank_mask:0x5
	v_add_f32_dpp v12, v95, v95 row_shr:4 row_mask:0xf bank_mask:0xa
	v_add_f32_dpp v13, v96, v96 row_shl:4 row_mask:0xf bank_mask:0x5
	v_add_f32_dpp v13, v97, v97 row_shr:4 row_mask:0xf bank_mask:0xa
	v_cndmask_b32_e64 v16, v10, v11, s[36:37]
	v_cndmask_b32_e64 v17, v11, v10, s[36:37]
	s_nop 1
	v_add_f32_dpp v14, v17, v16 quad_perm:[2,3,0,1] row_mask:0xf bank_mask:0xf
	v_cndmask_b32_e64 v16, v12, v13, s[36:37]
	v_cndmask_b32_e64 v17, v13, v12, s[36:37]
	s_nop 1
	v_add_f32_dpp v15, v17, v16 quad_perm:[2,3,0,1] row_mask:0xf bank_mask:0xf
	v_cndmask_b32_e64 v16, v14, v15, s[38:39]
	v_cndmask_b32_e64 v17, v15, v14, s[38:39]
	s_nop 1
	v_add_f32_dpp v98, v17, v16 quad_perm:[1,0,3,2] row_mask:0xf bank_mask:0xf
	s_waitcnt lgkmcnt(0)
	v_add_f32_e32 v99, v99, v98
	ds_write_b32 v167, v99 offset:256
	v_add_u32_e32 v167, 512, v167
	s_add_i32 s14, s14, 1
	s_cmp_lt_u32 s14, 8
	s_cbranch_scc1 .Lg4_u_gp
	s_add_i32 s13, s13, 1
	s_cmp_lt_u32 s13, 8
	s_cbranch_scc1 .Lg4_u_slice
	s_waitcnt vmcnt(0) lgkmcnt(0)
	v_add_u32_e32 v166, v164, v170
	v_add_u32_e32 v169, v168, v170
	ds_read_b32 v1, v166 offset:0
	ds_read_b32 v2, v166 offset:32
	ds_read_b32 v3, v166 offset:64
	ds_read_b32 v4, v166 offset:96
	ds_read_b32 v5, v165 offset:0
	ds_read_b32 v6, v165 offset:256
	ds_read_b32 v7, v165 offset:512
	ds_read_b32 v8, v165 offset:768
	global_load_dword v9, v173, s[20:21] offset:0
	global_load_dword v10, v173, s[20:21] offset:32
	global_load_dword v11, v173, s[20:21] offset:64
	global_load_dword v12, v173, s[20:21] offset:96
	s_waitcnt lgkmcnt(4)
	v_lshlrev_b32_e32 v1, 2, v1
	v_lshlrev_b32_e32 v2, 2, v2
	v_lshlrev_b32_e32 v3, 2, v3
	v_lshlrev_b32_e32 v4, 2, v4
	global_load_dword v13, v1, s[54:55]
	global_load_dword v17, v1, s[52:53]
	global_load_dword v14, v2, s[54:55]
	global_load_dword v18, v2, s[52:53]
	global_load_dword v15, v3, s[54:55]
	global_load_dword v19, v3, s[52:53]
	global_load_dword v16, v4, s[54:55]
	global_load_dword v64, v4, s[52:53]
	s_waitcnt vmcnt(0) lgkmcnt(0)
	v_mul_f32_e32 v9, v9, v17
	v_mul_f32_e32 v5, v5, v13
	v_mul_f32_e32 v20, 0x3d372713, v5
	v_mul_f32_e32 v20, v5, v20
	v_fma_f32 v20, v5, v20, v5
	v_mul_f32_e32 v20, 0x3f4c422a, v20
	v_add_f32_e32 v20, v20, v20
	v_mul_f32_e32 v20, 0x3fb8aa3b, v20
	v_exp_f32_e32 v20, v20
	v_mul_f32_e32 v5, 0.5, v5
	v_add_f32_e32 v20, 1.0, v20
	v_div_scale_f32 v21, s[44:45], v20, v20, 2.0
	v_rcp_f32_e32 v22, v21
	v_div_scale_f32 v23, vcc, 2.0, v20, 2.0
	v_fma_f32 v24, -v21, v22, 1.0
	v_fmac_f32_e32 v22, v24, v22
	v_mul_f32_e32 v24, v23, v22
	v_fma_f32 v25, -v21, v24, v23
	v_fmac_f32_e32 v24, v25, v22
	v_fma_f32 v21, -v21, v24, v23
	v_div_fmas_f32 v21, v21, v22, v24
	v_div_fixup_f32 v20, v21, v20, 2.0
	v_sub_f32_e32 v20, 1.0, v20
	v_add_f32_e32 v20, 1.0, v20
	v_mul_f32_e32 v5, v5, v20
	v_mul_f32_e32 v5, v5, v9
	ds_write_b32 v169, v5 offset:0
	v_mul_f32_e32 v10, v10, v18
	v_mul_f32_e32 v6, v6, v14
	v_mul_f32_e32 v20, 0x3d372713, v6
	v_mul_f32_e32 v20, v6, v20
	v_fma_f32 v20, v6, v20, v6
	v_mul_f32_e32 v20, 0x3f4c422a, v20
	v_add_f32_e32 v20, v20, v20
	v_mul_f32_e32 v20, 0x3fb8aa3b, v20
	v_exp_f32_e32 v20, v20
	v_mul_f32_e32 v6, 0.5, v6
	v_add_f32_e32 v20, 1.0, v20
	v_div_scale_f32 v21, s[44:45], v20, v20, 2.0
	v_rcp_f32_e32 v22, v21
	v_div_scale_f32 v23, vcc, 2.0, v20, 2.0
	v_fma_f32 v24, -v21, v22, 1.0
	v_fmac_f32_e32 v22, v24, v22
	v_mul_f32_e32 v24, v23, v22
	v_fma_f32 v25, -v21, v24, v23
	v_fmac_f32_e32 v24, v25, v22
	v_fma_f32 v21, -v21, v24, v23
	v_div_fmas_f32 v21, v21, v22, v24
	v_div_fixup_f32 v20, v21, v20, 2.0
	v_sub_f32_e32 v20, 1.0, v20
	v_add_f32_e32 v20, 1.0, v20
	v_mul_f32_e32 v6, v6, v20
	v_mul_f32_e32 v6, v6, v10
	ds_write_b32 v169, v6 offset:32
	v_mul_f32_e32 v11, v11, v19
	v_mul_f32_e32 v7, v7, v15
	v_mul_f32_e32 v20, 0x3d372713, v7
	v_mul_f32_e32 v20, v7, v20
	v_fma_f32 v20, v7, v20, v7
	v_mul_f32_e32 v20, 0x3f4c422a, v20
	v_add_f32_e32 v20, v20, v20
	v_mul_f32_e32 v20, 0x3fb8aa3b, v20
	v_exp_f32_e32 v20, v20
	v_mul_f32_e32 v7, 0.5, v7
	v_add_f32_e32 v20, 1.0, v20
	v_div_scale_f32 v21, s[44:45], v20, v20, 2.0
	v_rcp_f32_e32 v22, v21
	v_div_scale_f32 v23, vcc, 2.0, v20, 2.0
	v_fma_f32 v24, -v21, v22, 1.0
	v_fmac_f32_e32 v22, v24, v22
	v_mul_f32_e32 v24, v23, v22
	v_fma_f32 v25, -v21, v24, v23
	v_fmac_f32_e32 v24, v25, v22
	v_fma_f32 v21, -v21, v24, v23
	v_div_fmas_f32 v21, v21, v22, v24
	v_div_fixup_f32 v20, v21, v20, 2.0
	v_sub_f32_e32 v20, 1.0, v20
	v_add_f32_e32 v20, 1.0, v20
	v_mul_f32_e32 v7, v7, v20
	v_mul_f32_e32 v7, v7, v11
	ds_write_b32 v169, v7 offset:64
	v_mul_f32_e32 v12, v12, v64
	v_mul_f32_e32 v8, v8, v16
	v_mul_f32_e32 v20, 0x3d372713, v8
	v_mul_f32_e32 v20, v8, v20
	v_fma_f32 v20, v8, v20, v8
	v_mul_f32_e32 v20, 0x3f4c422a, v20
	v_add_f32_e32 v20, v20, v20
	v_mul_f32_e32 v20, 0x3fb8aa3b, v20
	v_exp_f32_e32 v20, v20
	v_mul_f32_e32 v8, 0.5, v8
	v_add_f32_e32 v20, 1.0, v20
	v_div_scale_f32 v21, s[44:45], v20, v20, 2.0
	v_rcp_f32_e32 v22, v21
	v_div_scale_f32 v23, vcc, 2.0, v20, 2.0
	v_fma_f32 v24, -v21, v22, 1.0
	v_fmac_f32_e32 v22, v24, v22
	v_mul_f32_e32 v24, v23, v22
	v_fma_f32 v25, -v21, v24, v23
	v_fmac_f32_e32 v24, v25, v22
	v_fma_f32 v21, -v21, v24, v23
	v_div_fmas_f32 v21, v21, v22, v24
	v_div_fixup_f32 v20, v21, v20, 2.0
	v_sub_f32_e32 v20, 1.0, v20
	v_add_f32_e32 v20, 1.0, v20
	v_mul_f32_e32 v8, v8, v20
	v_mul_f32_e32 v8, v8, v12
	ds_write_b32 v169, v8 offset:96
	ds_read_b32 v1, v166 offset:128
	ds_read_b32 v2, v166 offset:160
	ds_read_b32 v3, v166 offset:192
	ds_read_b32 v4, v166 offset:224
	ds_read_b32 v5, v165 offset:1024
	ds_read_b32 v6, v165 offset:1280
	ds_read_b32 v7, v165 offset:1536
	ds_read_b32 v8, v165 offset:1792
	global_load_dword v9, v173, s[20:21] offset:128
	global_load_dword v10, v173, s[20:21] offset:160
	global_load_dword v11, v173, s[20:21] offset:192
	global_load_dword v12, v173, s[20:21] offset:224
	s_waitcnt lgkmcnt(4)
	v_lshlrev_b32_e32 v1, 2, v1
	v_lshlrev_b32_e32 v2, 2, v2
	v_lshlrev_b32_e32 v3, 2, v3
	v_lshlrev_b32_e32 v4, 2, v4
	global_load_dword v13, v1, s[54:55]
	global_load_dword v17, v1, s[52:53]
	global_load_dword v14, v2, s[54:55]
	global_load_dword v18, v2, s[52:53]
	global_load_dword v15, v3, s[54:55]
	global_load_dword v19, v3, s[52:53]
	global_load_dword v16, v4, s[54:55]
	global_load_dword v64, v4, s[52:53]
	s_waitcnt vmcnt(0) lgkmcnt(0)
	v_mul_f32_e32 v9, v9, v17
	v_mul_f32_e32 v5, v5, v13
	v_mul_f32_e32 v20, 0x3d372713, v5
	v_mul_f32_e32 v20, v5, v20
	v_fma_f32 v20, v5, v20, v5
	v_mul_f32_e32 v20, 0x3f4c422a, v20
	v_add_f32_e32 v20, v20, v20
	v_mul_f32_e32 v20, 0x3fb8aa3b, v20
	v_exp_f32_e32 v20, v20
	v_mul_f32_e32 v5, 0.5, v5
	v_add_f32_e32 v20, 1.0, v20
	v_div_scale_f32 v21, s[44:45], v20, v20, 2.0
	v_rcp_f32_e32 v22, v21
	v_div_scale_f32 v23, vcc, 2.0, v20, 2.0
	v_fma_f32 v24, -v21, v22, 1.0
	v_fmac_f32_e32 v22, v24, v22
	v_mul_f32_e32 v24, v23, v22
	v_fma_f32 v25, -v21, v24, v23
	v_fmac_f32_e32 v24, v25, v22
	v_fma_f32 v21, -v21, v24, v23
	v_div_fmas_f32 v21, v21, v22, v24
	v_div_fixup_f32 v20, v21, v20, 2.0
	v_sub_f32_e32 v20, 1.0, v20
	v_add_f32_e32 v20, 1.0, v20
	v_mul_f32_e32 v5, v5, v20
	v_mul_f32_e32 v5, v5, v9
	ds_write_b32 v169, v5 offset:128
	v_mul_f32_e32 v10, v10, v18
	v_mul_f32_e32 v6, v6, v14
	v_mul_f32_e32 v20, 0x3d372713, v6
	v_mul_f32_e32 v20, v6, v20
	v_fma_f32 v20, v6, v20, v6
	v_mul_f32_e32 v20, 0x3f4c422a, v20
	v_add_f32_e32 v20, v20, v20
	v_mul_f32_e32 v20, 0x3fb8aa3b, v20
	v_exp_f32_e32 v20, v20
	v_mul_f32_e32 v6, 0.5, v6
	v_add_f32_e32 v20, 1.0, v20
	v_div_scale_f32 v21, s[44:45], v20, v20, 2.0
	v_rcp_f32_e32 v22, v21
	v_div_scale_f32 v23, vcc, 2.0, v20, 2.0
	v_fma_f32 v24, -v21, v22, 1.0
	v_fmac_f32_e32 v22, v24, v22
	v_mul_f32_e32 v24, v23, v22
	v_fma_f32 v25, -v21, v24, v23
	v_fmac_f32_e32 v24, v25, v22
	v_fma_f32 v21, -v21, v24, v23
	v_div_fmas_f32 v21, v21, v22, v24
	v_div_fixup_f32 v20, v21, v20, 2.0
	v_sub_f32_e32 v20, 1.0, v20
	v_add_f32_e32 v20, 1.0, v20
	v_mul_f32_e32 v6, v6, v20
	v_mul_f32_e32 v6, v6, v10
	ds_write_b32 v169, v6 offset:160
	v_mul_f32_e32 v11, v11, v19
	v_mul_f32_e32 v7, v7, v15
	v_mul_f32_e32 v20, 0x3d372713, v7
	v_mul_f32_e32 v20, v7, v20
	v_fma_f32 v20, v7, v20, v7
	v_mul_f32_e32 v20, 0x3f4c422a, v20
	v_add_f32_e32 v20, v20, v20
	v_mul_f32_e32 v20, 0x3fb8aa3b, v20
	v_exp_f32_e32 v20, v20
	v_mul_f32_e32 v7, 0.5, v7
	v_add_f32_e32 v20, 1.0, v20
	v_div_scale_f32 v21, s[44:45], v20, v20, 2.0
	v_rcp_f32_e32 v22, v21
	v_div_scale_f32 v23, vcc, 2.0, v20, 2.0
	v_fma_f32 v24, -v21, v22, 1.0
	v_fmac_f32_e32 v22, v24, v22
	v_mul_f32_e32 v24, v23, v22
	v_fma_f32 v25, -v21, v24, v23
	v_fmac_f32_e32 v24, v25, v22
	v_fma_f32 v21, -v21, v24, v23
	v_div_fmas_f32 v21, v21, v22, v24
	v_div_fixup_f32 v20, v21, v20, 2.0
	v_sub_f32_e32 v20, 1.0, v20
	v_add_f32_e32 v20, 1.0, v20
	v_mul_f32_e32 v7, v7, v20
	v_mul_f32_e32 v7, v7, v11
	ds_write_b32 v169, v7 offset:192
	v_mul_f32_e32 v12, v12, v64
	v_mul_f32_e32 v8, v8, v16
	v_mul_f32_e32 v20, 0x3d372713, v8
	v_mul_f32_e32 v20, v8, v20
	v_fma_f32 v20, v8, v20, v8
	v_mul_f32_e32 v20, 0x3f4c422a, v20
	v_add_f32_e32 v20, v20, v20
	v_mul_f32_e32 v20, 0x3fb8aa3b, v20
	v_exp_f32_e32 v20, v20
	v_mul_f32_e32 v8, 0.5, v8
	v_add_f32_e32 v20, 1.0, v20
	v_div_scale_f32 v21, s[44:45], v20, v20, 2.0
	v_rcp_f32_e32 v22, v21
	v_div_scale_f32 v23, vcc, 2.0, v20, 2.0
	v_fma_f32 v24, -v21, v22, 1.0
	v_fmac_f32_e32 v22, v24, v22
	v_mul_f32_e32 v24, v23, v22
	v_fma_f32 v25, -v21, v24, v23
	v_fmac_f32_e32 v24, v25, v22
	v_fma_f32 v21, -v21, v24, v23
	v_div_fmas_f32 v21, v21, v22, v24
	v_div_fixup_f32 v20, v21, v20, 2.0
	v_sub_f32_e32 v20, 1.0, v20
	v_add_f32_e32 v20, 1.0, v20
	v_mul_f32_e32 v8, v8, v20
	v_mul_f32_e32 v8, v8, v12
	ds_write_b32 v169, v8 offset:224
	ds_read_b32 v1, v166 offset:256
	ds_read_b32 v2, v166 offset:288
	ds_read_b32 v3, v166 offset:320
	ds_read_b32 v4, v166 offset:352
	ds_read_b32 v5, v165 offset:2048
	ds_read_b32 v6, v165 offset:2304
	ds_read_b32 v7, v165 offset:2560
	ds_read_b32 v8, v165 offset:2816
	global_load_dword v9, v173, s[20:21] offset:256
	global_load_dword v10, v173, s[20:21] offset:288
	global_load_dword v11, v173, s[20:21] offset:320
	global_load_dword v12, v173, s[20:21] offset:352
	s_waitcnt lgkmcnt(4)
	v_lshlrev_b32_e32 v1, 2, v1
	v_lshlrev_b32_e32 v2, 2, v2
	v_lshlrev_b32_e32 v3, 2, v3
	v_lshlrev_b32_e32 v4, 2, v4
	global_load_dword v13, v1, s[54:55]
	global_load_dword v17, v1, s[52:53]
	global_load_dword v14, v2, s[54:55]
	global_load_dword v18, v2, s[52:53]
	global_load_dword v15, v3, s[54:55]
	global_load_dword v19, v3, s[52:53]
	global_load_dword v16, v4, s[54:55]
	global_load_dword v64, v4, s[52:53]
	s_waitcnt vmcnt(0) lgkmcnt(0)
	v_mul_f32_e32 v9, v9, v17
	v_mul_f32_e32 v5, v5, v13
	v_mul_f32_e32 v20, 0x3d372713, v5
	v_mul_f32_e32 v20, v5, v20
	v_fma_f32 v20, v5, v20, v5
	v_mul_f32_e32 v20, 0x3f4c422a, v20
	v_add_f32_e32 v20, v20, v20
	v_mul_f32_e32 v20, 0x3fb8aa3b, v20
	v_exp_f32_e32 v20, v20
	v_mul_f32_e32 v5, 0.5, v5
	v_add_f32_e32 v20, 1.0, v20
	v_div_scale_f32 v21, s[44:45], v20, v20, 2.0
	v_rcp_f32_e32 v22, v21
	v_div_scale_f32 v23, vcc, 2.0, v20, 2.0
	v_fma_f32 v24, -v21, v22, 1.0
	v_fmac_f32_e32 v22, v24, v22
	v_mul_f32_e32 v24, v23, v22
	v_fma_f32 v25, -v21, v24, v23
	v_fmac_f32_e32 v24, v25, v22
	v_fma_f32 v21, -v21, v24, v23
	v_div_fmas_f32 v21, v21, v22, v24
	v_div_fixup_f32 v20, v21, v20, 2.0
	v_sub_f32_e32 v20, 1.0, v20
	v_add_f32_e32 v20, 1.0, v20
	v_mul_f32_e32 v5, v5, v20
	v_mul_f32_e32 v5, v5, v9
	ds_write_b32 v169, v5 offset:256
	v_mul_f32_e32 v10, v10, v18
	v_mul_f32_e32 v6, v6, v14
	v_mul_f32_e32 v20, 0x3d372713, v6
	v_mul_f32_e32 v20, v6, v20
	v_fma_f32 v20, v6, v20, v6
	v_mul_f32_e32 v20, 0x3f4c422a, v20
	v_add_f32_e32 v20, v20, v20
	v_mul_f32_e32 v20, 0x3fb8aa3b, v20
	v_exp_f32_e32 v20, v20
	v_mul_f32_e32 v6, 0.5, v6
	v_add_f32_e32 v20, 1.0, v20
	v_div_scale_f32 v21, s[44:45], v20, v20, 2.0
	v_rcp_f32_e32 v22, v21
	v_div_scale_f32 v23, vcc, 2.0, v20, 2.0
	v_fma_f32 v24, -v21, v22, 1.0
	v_fmac_f32_e32 v22, v24, v22
	v_mul_f32_e32 v24, v23, v22
	v_fma_f32 v25, -v21, v24, v23
	v_fmac_f32_e32 v24, v25, v22
	v_fma_f32 v21, -v21, v24, v23
	v_div_fmas_f32 v21, v21, v22, v24
	v_div_fixup_f32 v20, v21, v20, 2.0
	v_sub_f32_e32 v20, 1.0, v20
	v_add_f32_e32 v20, 1.0, v20
	v_mul_f32_e32 v6, v6, v20
	v_mul_f32_e32 v6, v6, v10
	ds_write_b32 v169, v6 offset:288
	v_mul_f32_e32 v11, v11, v19
	v_mul_f32_e32 v7, v7, v15
	v_mul_f32_e32 v20, 0x3d372713, v7
	v_mul_f32_e32 v20, v7, v20
	v_fma_f32 v20, v7, v20, v7
	v_mul_f32_e32 v20, 0x3f4c422a, v20
	v_add_f32_e32 v20, v20, v20
	v_mul_f32_e32 v20, 0x3fb8aa3b, v20
	v_exp_f32_e32 v20, v20
	v_mul_f32_e32 v7, 0.5, v7
	v_add_f32_e32 v20, 1.0, v20
	v_div_scale_f32 v21, s[44:45], v20, v20, 2.0
	v_rcp_f32_e32 v22, v21
	v_div_scale_f32 v23, vcc, 2.0, v20, 2.0
	v_fma_f32 v24, -v21, v22, 1.0
	v_fmac_f32_e32 v22, v24, v22
	v_mul_f32_e32 v24, v23, v22
	v_fma_f32 v25, -v21, v24, v23
	v_fmac_f32_e32 v24, v25, v22
	v_fma_f32 v21, -v21, v24, v23
	v_div_fmas_f32 v21, v21, v22, v24
	v_div_fixup_f32 v20, v21, v20, 2.0
	v_sub_f32_e32 v20, 1.0, v20
	v_add_f32_e32 v20, 1.0, v20
	v_mul_f32_e32 v7, v7, v20
	v_mul_f32_e32 v7, v7, v11
	ds_write_b32 v169, v7 offset:320
	v_mul_f32_e32 v12, v12, v64
	v_mul_f32_e32 v8, v8, v16
	v_mul_f32_e32 v20, 0x3d372713, v8
	v_mul_f32_e32 v20, v8, v20
	v_fma_f32 v20, v8, v20, v8
	v_mul_f32_e32 v20, 0x3f4c422a, v20
	v_add_f32_e32 v20, v20, v20
	v_mul_f32_e32 v20, 0x3fb8aa3b, v20
	v_exp_f32_e32 v20, v20
	v_mul_f32_e32 v8, 0.5, v8
	v_add_f32_e32 v20, 1.0, v20
	v_div_scale_f32 v21, s[44:45], v20, v20, 2.0
	v_rcp_f32_e32 v22, v21
	v_div_scale_f32 v23, vcc, 2.0, v20, 2.0
	v_fma_f32 v24, -v21, v22, 1.0
	v_fmac_f32_e32 v22, v24, v22
	v_mul_f32_e32 v24, v23, v22
	v_fma_f32 v25, -v21, v24, v23
	v_fmac_f32_e32 v24, v25, v22
	v_fma_f32 v21, -v21, v24, v23
	v_div_fmas_f32 v21, v21, v22, v24
	v_div_fixup_f32 v20, v21, v20, 2.0
	v_sub_f32_e32 v20, 1.0, v20
	v_add_f32_e32 v20, 1.0, v20
	v_mul_f32_e32 v8, v8, v20
	v_mul_f32_e32 v8, v8, v12
	ds_write_b32 v169, v8 offset:352
	ds_read_b32 v1, v166 offset:384
	ds_read_b32 v2, v166 offset:416
	ds_read_b32 v3, v166 offset:448
	ds_read_b32 v4, v166 offset:480
	ds_read_b32 v5, v165 offset:3072
	ds_read_b32 v6, v165 offset:3328
	ds_read_b32 v7, v165 offset:3584
	ds_read_b32 v8, v165 offset:3840
	global_load_dword v9, v173, s[20:21] offset:384
	global_load_dword v10, v173, s[20:21] offset:416
	global_load_dword v11, v173, s[20:21] offset:448
	global_load_dword v12, v173, s[20:21] offset:480
	s_waitcnt lgkmcnt(4)
	v_lshlrev_b32_e32 v1, 2, v1
	v_lshlrev_b32_e32 v2, 2, v2
	v_lshlrev_b32_e32 v3, 2, v3
	v_lshlrev_b32_e32 v4, 2, v4
	global_load_dword v13, v1, s[54:55]
	global_load_dword v17, v1, s[52:53]
	global_load_dword v14, v2, s[54:55]
	global_load_dword v18, v2, s[52:53]
	global_load_dword v15, v3, s[54:55]
	global_load_dword v19, v3, s[52:53]
	global_load_dword v16, v4, s[54:55]
	global_load_dword v64, v4, s[52:53]
	s_waitcnt vmcnt(0) lgkmcnt(0)
	v_mul_f32_e32 v9, v9, v17
	v_mul_f32_e32 v5, v5, v13
	v_mul_f32_e32 v20, 0x3d372713, v5
	v_mul_f32_e32 v20, v5, v20
	v_fma_f32 v20, v5, v20, v5
	v_mul_f32_e32 v20, 0x3f4c422a, v20
	v_add_f32_e32 v20, v20, v20
	v_mul_f32_e32 v20, 0x3fb8aa3b, v20
	v_exp_f32_e32 v20, v20
	v_mul_f32_e32 v5, 0.5, v5
	v_add_f32_e32 v20, 1.0, v20
	v_div_scale_f32 v21, s[44:45], v20, v20, 2.0
	v_rcp_f32_e32 v22, v21
	v_div_scale_f32 v23, vcc, 2.0, v20, 2.0
	v_fma_f32 v24, -v21, v22, 1.0
	v_fmac_f32_e32 v22, v24, v22
	v_mul_f32_e32 v24, v23, v22
	v_fma_f32 v25, -v21, v24, v23
	v_fmac_f32_e32 v24, v25, v22
	v_fma_f32 v21, -v21, v24, v23
	v_div_fmas_f32 v21, v21, v22, v24
	v_div_fixup_f32 v20, v21, v20, 2.0
	v_sub_f32_e32 v20, 1.0, v20
	v_add_f32_e32 v20, 1.0, v20
	v_mul_f32_e32 v5, v5, v20
	v_mul_f32_e32 v5, v5, v9
	ds_write_b32 v169, v5 offset:384
	v_mul_f32_e32 v10, v10, v18
	v_mul_f32_e32 v6, v6, v14
	v_mul_f32_e32 v20, 0x3d372713, v6
	v_mul_f32_e32 v20, v6, v20
	v_fma_f32 v20, v6, v20, v6
	v_mul_f32_e32 v20, 0x3f4c422a, v20
	v_add_f32_e32 v20, v20, v20
	v_mul_f32_e32 v20, 0x3fb8aa3b, v20
	v_exp_f32_e32 v20, v20
	v_mul_f32_e32 v6, 0.5, v6
	v_add_f32_e32 v20, 1.0, v20
	v_div_scale_f32 v21, s[44:45], v20, v20, 2.0
	v_rcp_f32_e32 v22, v21
	v_div_scale_f32 v23, vcc, 2.0, v20, 2.0
	v_fma_f32 v24, -v21, v22, 1.0
	v_fmac_f32_e32 v22, v24, v22
	v_mul_f32_e32 v24, v23, v22
	v_fma_f32 v25, -v21, v24, v23
	v_fmac_f32_e32 v24, v25, v22
	v_fma_f32 v21, -v21, v24, v23
	v_div_fmas_f32 v21, v21, v22, v24
	v_div_fixup_f32 v20, v21, v20, 2.0
	v_sub_f32_e32 v20, 1.0, v20
	v_add_f32_e32 v20, 1.0, v20
	v_mul_f32_e32 v6, v6, v20
	v_mul_f32_e32 v6, v6, v10
	ds_write_b32 v169, v6 offset:416
	v_mul_f32_e32 v11, v11, v19
	v_mul_f32_e32 v7, v7, v15
	v_mul_f32_e32 v20, 0x3d372713, v7
	v_mul_f32_e32 v20, v7, v20
	v_fma_f32 v20, v7, v20, v7
	v_mul_f32_e32 v20, 0x3f4c422a, v20
	v_add_f32_e32 v20, v20, v20
	v_mul_f32_e32 v20, 0x3fb8aa3b, v20
	v_exp_f32_e32 v20, v20
	v_mul_f32_e32 v7, 0.5, v7
	v_add_f32_e32 v20, 1.0, v20
	v_div_scale_f32 v21, s[44:45], v20, v20, 2.0
	v_rcp_f32_e32 v22, v21
	v_div_scale_f32 v23, vcc, 2.0, v20, 2.0
	v_fma_f32 v24, -v21, v22, 1.0
	v_fmac_f32_e32 v22, v24, v22
	v_mul_f32_e32 v24, v23, v22
	v_fma_f32 v25, -v21, v24, v23
	v_fmac_f32_e32 v24, v25, v22
	v_fma_f32 v21, -v21, v24, v23
	v_div_fmas_f32 v21, v21, v22, v24
	v_div_fixup_f32 v20, v21, v20, 2.0
	v_sub_f32_e32 v20, 1.0, v20
	v_add_f32_e32 v20, 1.0, v20
	v_mul_f32_e32 v7, v7, v20
	v_mul_f32_e32 v7, v7, v11
	ds_write_b32 v169, v7 offset:448
	v_mul_f32_e32 v12, v12, v64
	v_mul_f32_e32 v8, v8, v16
	v_mul_f32_e32 v20, 0x3d372713, v8
	v_mul_f32_e32 v20, v8, v20
	v_fma_f32 v20, v8, v20, v8
	v_mul_f32_e32 v20, 0x3f4c422a, v20
	v_add_f32_e32 v20, v20, v20
	v_mul_f32_e32 v20, 0x3fb8aa3b, v20
	v_exp_f32_e32 v20, v20
	v_mul_f32_e32 v8, 0.5, v8
	v_add_f32_e32 v20, 1.0, v20
	v_div_scale_f32 v21, s[44:45], v20, v20, 2.0
	v_rcp_f32_e32 v22, v21
	v_div_scale_f32 v23, vcc, 2.0, v20, 2.0
	v_fma_f32 v24, -v21, v22, 1.0
	v_fmac_f32_e32 v22, v24, v22
	v_mul_f32_e32 v24, v23, v22
	v_fma_f32 v25, -v21, v24, v23
	v_fmac_f32_e32 v24, v25, v22
	v_fma_f32 v21, -v21, v24, v23
	v_div_fmas_f32 v21, v21, v22, v24
	v_div_fixup_f32 v20, v21, v20, 2.0
	v_sub_f32_e32 v20, 1.0, v20
	v_add_f32_e32 v20, 1.0, v20
	v_mul_f32_e32 v8, v8, v20
	v_mul_f32_e32 v8, v8, v12
	ds_write_b32 v169, v8 offset:480
	s_waitcnt lgkmcnt(0)
	s_mov_b32 s13, 0
	ds_read_b128 v[2:5], v164 offset:0
	ds_read_b128 v[6:9], v164 offset:16
	ds_read_b128 v[10:13], v164 offset:32
	ds_read_b128 v[14:17], v164 offset:48
	s_mov_b64 s[40:41], s[58:59]
	s_waitcnt lgkmcnt(0)
	v_lshl_add_u32 v2, v2, 7, v78
	v_lshl_add_u32 v3, v3, 7, v78
	v_lshl_add_u32 v4, v4, 7, v78
	v_lshl_add_u32 v5, v5, 7, v78
	v_lshl_add_u32 v6, v6, 7, v78
	v_lshl_add_u32 v7, v7, 7, v78
	v_lshl_add_u32 v8, v8, 7, v78
	v_lshl_add_u32 v9, v9, 7, v78
	v_lshl_add_u32 v10, v10, 7, v78
	v_lshl_add_u32 v11, v11, 7, v78
	v_lshl_add_u32 v12, v12, 7, v78
	v_lshl_add_u32 v13, v13, 7, v78
	v_lshl_add_u32 v14, v14, 7, v78
	v_lshl_add_u32 v15, v15, 7, v78
	v_lshl_add_u32 v16, v16, 7, v78
	v_lshl_add_u32 v17, v17, 7, v78
	global_load_dwordx4 v[100:103], v2, s[40:41]
	global_load_dwordx4 v[104:107], v3, s[40:41]
	global_load_dwordx4 v[108:111], v4, s[40:41]
	global_load_dwordx4 v[112:115], v5, s[40:41]
	global_load_dwordx4 v[116:119], v6, s[40:41]
	global_load_dwordx4 v[120:123], v7, s[40:41]
	global_load_dwordx4 v[124:127], v8, s[40:41]
	global_load_dwordx4 v[128:131], v9, s[40:41]
	global_load_dwordx4 v[132:135], v10, s[40:41]
	global_load_dwordx4 v[136:139], v11, s[40:41]
	global_load_dwordx4 v[140:143], v12, s[40:41]
	global_load_dwordx4 v[144:147], v13, s[40:41]
	global_load_dwordx4 v[148:151], v14, s[40:41]
	global_load_dwordx4 v[152:155], v15, s[40:41]
	global_load_dwordx4 v[156:159], v16, s[40:41]
	global_load_dwordx4 v[160:163], v17, s[40:41]
	ds_read_b128 v[82:85], v168
	ds_read_b128 v[86:89], v168 offset:16
	s_add_u32 s42, s78, 0x2da00000
	s_addc_u32 s43, s79, 0
.Lg4_v_slice:
	v_mov_b32_e32 v20, 0
	v_mov_b32_e32 v21, 0
	v_mov_b32_e32 v22, 0
	v_mov_b32_e32 v23, 0
	v_mov_b32_e32 v24, 0
	v_mov_b32_e32 v25, 0
	v_mov_b32_e32 v26, 0
	v_mov_b32_e32 v27, 0
	v_mov_b32_e32 v28, 0
	v_mov_b32_e32 v29, 0
	v_mov_b32_e32 v30, 0
	v_mov_b32_e32 v31, 0
	v_mov_b32_e32 v32, 0
	v_mov_b32_e32 v33, 0
	v_mov_b32_e32 v34, 0
	v_mov_b32_e32 v35, 0
	v_mov_b32_e32 v36, 0
	v_mov_b32_e32 v37, 0
	v_mov_b32_e32 v38, 0
	v_mov_b32_e32 v39, 0
	v_mov_b32_e32 v40, 0
	v_mov_b32_e32 v41, 0
	v_mov_b32_e32 v42, 0
	v_mov_b32_e32 v43, 0
	v_mov_b32_e32 v44, 0
	v_mov_b32_e32 v45, 0
	v_mov_b32_e32 v46, 0
	v_mov_b32_e32 v47, 0
	v_mov_b32_e32 v48, 0
	v_mov_b32_e32 v49, 0
	v_mov_b32_e32 v50, 0
	v_mov_b32_e32 v51, 0
	s_mov_b32 s14, 0
.Lg4_v_gp:
	s_lshl_b32 s100, s14, 1
	s_add_i32 s100, s100, 2
	s_lshr_b32 s101, s100, 4
	s_and_b32 s100, s100, 15
	s_lshl_b32 s100, s100, 5
	v_add_u32_e32 v1, s100, v164
	s_add_i32 s101, s101, s13
	s_min_u32 s101, s101, 7
	s_lshl_b32 s101, s101, 21
	s_add_u32 s40, s58, s101
	s_addc_u32 s41, s59, 0
	ds_read_b128 v[2:5], v1 offset:0
	ds_read_b128 v[6:9], v1 offset:16
	s_lshl_b32 s100, s14, 1
	s_add_i32 s100, s100, 1
	s_and_b32 s100, s100, 15
	s_lshl_b32 s100, s100, 5
	v_add_u32_e32 v169, s100, v168
	ds_read_b128 v[90:93], v169
	ds_read_b128 v[94:97], v169 offset:16
	s_waitcnt vmcnt(15)
	v_cvt_scalef32_pk_f32_fp4 v[54:55], v100, 1.0
	v_cvt_scalef32_pk_f32_fp4 v[52:53], v100, 1.0 op_sel:[1,0,0]
	v_cvt_scalef32_pk_f32_fp4 v[58:59], v100, 1.0 op_sel:[0,1,0]
	v_cvt_scalef32_pk_f32_fp4 v[56:57], v100, 1.0 op_sel:[1,1,0]
	v_cvt_scalef32_pk_f32_fp4 v[62:63], v101, 1.0
	v_cvt_scalef32_pk_f32_fp4 v[60:61], v101, 1.0 op_sel:[1,0,0]
	v_cvt_scalef32_pk_f32_fp4 v[18:19], v101, 1.0 op_sel:[0,1,0]
	v_cvt_scalef32_pk_f32_fp4 v[64:65], v101, 1.0 op_sel:[1,1,0]
	s_waitcnt lgkmcnt(4)
	v_pk_fma_f32 v[20:21], v[54:55], v[82:83], v[20:21] op_sel_hi:[1,0,1]
	v_pk_fma_f32 v[22:23], v[52:53], v[82:83], v[22:23] op_sel_hi:[1,0,1]
	v_pk_fma_f32 v[24:25], v[58:59], v[82:83], v[24:25] op_sel_hi:[1,0,1]
	v_pk_fma_f32 v[26:27], v[56:57], v[82:83], v[26:27] op_sel_hi:[1,0,1]
	v_cvt_scalef32_pk_f32_fp4 v[54:55], v102, 1.0
	v_cvt_scalef32_pk_f32_fp4 v[52:53], v102, 1.0 op_sel:[1,0,0]
	v_cvt_scalef32_pk_f32_fp4 v[58:59], v102, 1.0 op_sel:[0,1,0]
	v_cvt_scalef32_pk_f32_fp4 v[56:57], v102, 1.0 op_sel:[1,1,0]
	v_pk_fma_f32 v[28:29], v[62:63], v[82:83], v[28:29] op_sel_hi:[1,0,1]
	v_pk_fma_f32 v[30:31], v[60:61], v[82:83], v[30:31] op_sel_hi:[1,0,1]
	v_pk_fma_f32 v[32:33], v[18:19], v[82:83], v[32:33] op_sel_hi:[1,0,1]
	v_pk_fma_f32 v[34:35], v[64:65], v[82:83], v[34:35] op_sel_hi:[1,0,1]
	v_cvt_scalef32_pk_f32_fp4 v[62:63], v103, 1.0
	v_cvt_scalef32_pk_f32_fp4 v[60:61], v103, 1.0 op_sel:[1,0,0]
	v_cvt_scalef32_pk_f32_fp4 v[18:19], v103, 1.0 op_sel:[0,1,0]
	v_cvt_scalef32_pk_f32_fp4 v[64:65], v103, 1.0 op_sel:[1,1,0]
	v_pk_fma_f32 v[36:37], v[54:55], v[82:83], v[36:37] op_sel_hi:[1,0,1]
	v_pk_fma_f32 v[38:39], v[52:53], v[82:83], v[38:39] op_sel_hi:[1,0,1]
	v_pk_fma_f32 v[40:41], v[58:59], v[82:83], v[40:41] op_sel_hi:[1,0,1]
	v_pk_fma_f32 v[42:43], v[56:57], v[82:83], v[42:43] op_sel_hi:[1,0,1]
	v_pk_fma_f32 v[44:45], v[62:63], v[82:83], v[44:45] op_sel_hi:[1,0,1]
	v_pk_fma_f32 v[46:47], v[60:61], v[82:83], v[46:47] op_sel_hi:[1,0,1]
	v_pk_fma_f32 v[48:49], v[18:19], v[82:83], v[48:49] op_sel_hi:[1,0,1]
	v_pk_fma_f32 v[50:51], v[64:65], v[82:83], v[50:51] op_sel_hi:[1,0,1]
	s_waitcnt lgkmcnt(2)
	v_lshl_add_u32 v2, v2, 7, v78
	v_lshl_add_u32 v3, v3, 7, v78
	v_lshl_add_u32 v4, v4, 7, v78
	v_lshl_add_u32 v5, v5, 7, v78
	v_lshl_add_u32 v6, v6, 7, v78
	v_lshl_add_u32 v7, v7, 7, v78
	v_lshl_add_u32 v8, v8, 7, v78
	v_lshl_add_u32 v9, v9, 7, v78
	global_load_dwordx4 v[100:103], v2, s[40:41]
	s_waitcnt vmcnt(15)
	v_cvt_scalef32_pk_f32_fp4 v[54:55], v104, 1.0
	v_cvt_scalef32_pk_f32_fp4 v[52:53], v104, 1.0 op_sel:[1,0,0]
	v_cvt_scalef32_pk_f32_fp4 v[58:59], v104, 1.0 op_sel:[0,1,0]
	v_cvt_scalef32_pk_f32_fp4 v[56:57], v104, 1.0 op_sel:[1,1,0]
	v_cvt_scalef32_pk_f32_fp4 v[62:63], v105, 1.0
	v_cvt_scalef32_pk_f32_fp4 v[60:61], v105, 1.0 op_sel:[1,0,0]
	v_cvt_scalef32_pk_f32_fp4 v[18:19], v105, 1.0 op_sel:[0,1,0]
	v_cvt_scalef32_pk_f32_fp4 v[64:65], v105, 1.0 op_sel:[1,1,0]
	v_pk_fma_f32 v[20:21], v[54:55], v[82:83], v[20:21] op_sel:[0,1,0] op_sel_hi:[1,1,1]
	v_pk_fma_f32 v[22:23], v[52:53], v[82:83], v[22:23] op_sel:[0,1,0] op_sel_hi:[1,1,1]
	v_pk_fma_f32 v[24:25], v[58:59], v[82:83], v[24:25] op_sel:[0,1,0] op_sel_hi:[1,1,1]
	v_pk_fma_f32 v[26:27], v[56:57], v[82:83], v[26:27] op_sel:[0,1,0] op_sel_hi:[1,1,1]
	v_cvt_scalef32_pk_f32_fp4 v[54:55], v106, 1.0
	v_cvt_scalef32_pk_f32_fp4 v[52:53], v106, 1.0 op_sel:[1,0,0]
	v_cvt_scalef32_pk_f32_fp4 v[58:59], v106, 1.0 op_sel:[0,1,0]
	v_cvt_scalef32_pk_f32_fp4 v[56:57], v106, 1.0 op_sel:[1,1,0]
	v_pk_fma_f32 v[28:29], v[62:63], v[82:83], v[28:29] op_sel:[0,1,0] op_sel_hi:[1,1,1]
	v_pk_fma_f32 v[30:31], v[60:61], v[82:83], v[30:31] op_sel:[0,1,0] op_sel_hi:[1,1,1]
	v_pk_fma_f32 v[32:33], v[18:19], v[82:83], v[32:33] op_sel:[0,1,0] op_sel_hi:[1,1,1]
	v_pk_fma_f32 v[34:35], v[64:65], v[82:83], v[34:35] op_sel:[0,1,0] op_sel_hi:[1,1,1]
	v_cvt_scalef32_pk_f32_fp4 v[62:63], v107, 1.0
	v_cvt_scalef32_pk_f32_fp4 v[60:61], v107, 1.0 op_sel:[1,0,0]
	v_cvt_scalef32_pk_f32_fp4 v[18:19], v107, 1.0 op_sel:[0,1,0]
	v_cvt_scalef32_pk_f32_fp4 v[64:65], v107, 1.0 op_sel:[1,1,0]
	v_pk_fma_f32 v[36:37], v[54:55], v[82:83], v[36:37] op_sel:[0,1,0] op_sel_hi:[1,1,1]
	v_pk_fma_f32 v[38:39], v[52:53], v[82:83], v[38:39] op_sel:[0,1,0] op_sel_hi:[1,1,1]
	v_pk_fma_f32 v[40:41], v[58:59], v[82:83], v[40:41] op_sel:[0,1,0] op_sel_hi:[1,1,1]
	v_pk_fma_f32 v[42:43], v[56:57], v[82:83], v[42:43] op_sel:[0,1,0] op_sel_hi:[1,1,1]
	v_pk_fma_f32 v[44:45], v[62:63], v[82:83], v[44:45] op_sel:[0,1,0] op_sel_hi:[1,1,1]
	v_pk_fma_f32 v[46:47], v[60:61], v[82:83], v[46:47] op_sel:[0,1,0] op_sel_hi:[1,1,1]
	v_pk_fma_f32 v[48:49], v[18:19], v[82:83], v[48:49] op_sel:[0,1,0] op_sel_hi:[1,1,1]
	v_pk_fma_f32 v[50:51], v[64:65], v[82:83], v[50:51] op_sel:[0,1,0] op_sel_hi:[1,1,1]
	global_load_dwordx4 v[104:107], v3, s[40:41]
	s_waitcnt vmcnt(15)
	v_cvt_scalef32_pk_f32_fp4 v[54:55], v108, 1.0
	v_cvt_scalef32_pk_f32_fp4 v[52:53], v108, 1.0 op_sel:[1,0,0]
	v_cvt_scalef32_pk_f32_fp4 v[58:59], v108, 1.0 op_sel:[0,1,0]
	v_cvt_scalef32_pk_f32_fp4 v[56:57], v108, 1.0 op_sel:[1,1,0]
	v_cvt_scalef32_pk_f32_fp4 v[62:63], v109, 1.0
	v_cvt_scalef32_pk_f32_fp4 v[60:61], v109, 1.0 op_sel:[1,0,0]
	v_cvt_scalef32_pk_f32_fp4 v[18:19], v109, 1.0 op_sel:[0,1,0]
	v_cvt_scalef32_pk_f32_fp4 v[64:65], v109, 1.0 op_sel:[1,1,0]
	v_pk_fma_f32 v[20:21], v[54:55], v[84:85], v[20:21] op_sel_hi:[1,0,1]
	v_pk_fma_f32 v[22:23], v[52:53], v[84:85], v[22:23] op_sel_hi:[1,0,1]
	v_pk_fma_f32 v[24:25], v[58:59], v[84:85], v[24:25] op_sel_hi:[1,0,1]
	v_pk_fma_f32 v[26:27], v[56:57], v[84:85], v[26:27] op_sel_hi:[1,0,1]
	v_cvt_scalef32_pk_f32_fp4 v[54:55], v110, 1.0
	v_cvt_scalef32_pk_f32_fp4 v[52:53], v110, 1.0 op_sel:[1,0,0]
	v_cvt_scalef32_pk_f32_fp4 v[58:59], v110, 1.0 op_sel:[0,1,0]
	v_cvt_scalef32_pk_f32_fp4 v[56:57], v110, 1.0 op_sel:[1,1,0]
	v_pk_fma_f32 v[28:29], v[62:63], v[84:85], v[28:29] op_sel_hi:[1,0,1]
	v_pk_fma_f32 v[30:31], v[60:61], v[84:85], v[30:31] op_sel_hi:[1,0,1]
	v_pk_fma_f32 v[32:33], v[18:19], v[84:85], v[32:33] op_sel_hi:[1,0,1]
	v_pk_fma_f32 v[34:35], v[64:65], v[84:85], v[34:35] op_sel_hi:[1,0,1]
	v_cvt_scalef32_pk_f32_fp4 v[62:63], v111, 1.0
	v_cvt_scalef32_pk_f32_fp4 v[60:61], v111, 1.0 op_sel:[1,0,0]
	v_cvt_scalef32_pk_f32_fp4 v[18:19], v111, 1.0 op_sel:[0,1,0]
	v_cvt_scalef32_pk_f32_fp4 v[64:65], v111, 1.0 op_sel:[1,1,0]
	v_pk_fma_f32 v[36:37], v[54:55], v[84:85], v[36:37] op_sel_hi:[1,0,1]
	v_pk_fma_f32 v[38:39], v[52:53], v[84:85], v[38:39] op_sel_hi:[1,0,1]
	v_pk_fma_f32 v[40:41], v[58:59], v[84:85], v[40:41] op_sel_hi:[1,0,1]
	v_pk_fma_f32 v[42:43], v[56:57], v[84:85], v[42:43] op_sel_hi:[1,0,1]
	v_pk_fma_f32 v[44:45], v[62:63], v[84:85], v[44:45] op_sel_hi:[1,0,1]
	v_pk_fma_f32 v[46:47], v[60:61], v[84:85], v[46:47] op_sel_hi:[1,0,1]
	v_pk_fma_f32 v[48:49], v[18:19], v[84:85], v[48:49] op_sel_hi:[1,0,1]
	v_pk_fma_f32 v[50:51], v[64:65], v[84:85], v[50:51] op_sel_hi:[1,0,1]
	global_load_dwordx4 v[108:111], v4, s[40:41]
	s_waitcnt vmcnt(15)
	v_cvt_scalef32_pk_f32_fp4 v[54:55], v112, 1.0
	v_cvt_scalef32_pk_f32_fp4 v[52:53], v112, 1.0 op_sel:[1,0,0]
	v_cvt_scalef32_pk_f32_fp4 v[58:59], v112, 1.0 op_sel:[0,1,0]
	v_cvt_scalef32_pk_f32_fp4 v[56:57], v112, 1.0 op_sel:[1,1,0]
	v_cvt_scalef32_pk_f32_fp4 v[62:63], v113, 1.0
	v_cvt_scalef32_pk_f32_fp4 v[60:61], v113, 1.0 op_sel:[1,0,0]
	v_cvt_scalef32_pk_f32_fp4 v[18:19], v113, 1.0 op_sel:[0,1,0]
	v_cvt_scalef32_pk_f32_fp4 v[64:65], v113, 1.0 op_sel:[1,1,0]
	v_pk_fma_f32 v[20:21], v[54:55], v[84:85], v[20:21] op_sel:[0,1,0] op_sel_hi:[1,1,1]
	v_pk_fma_f32 v[22:23], v[52:53], v[84:85], v[22:23] op_sel:[0,1,0] op_sel_hi:[1,1,1]
	v_pk_fma_f32 v[24:25], v[58:59], v[84:85], v[24:25] op_sel:[0,1,0] op_sel_hi:[1,1,1]
	v_pk_fma_f32 v[26:27], v[56:57], v[84:85], v[26:27] op_sel:[0,1,0] op_sel_hi:[1,1,1]
	v_cvt_scalef32_pk_f32_fp4 v[54:55], v114, 1.0
	v_cvt_scalef32_pk_f32_fp4 v[52:53], v114, 1.0 op_sel:[1,0,0]
	v_cvt_scalef32_pk_f32_fp4 v[58:59], v114, 1.0 op_sel:[0,1,0]
	v_cvt_scalef32_pk_f32_fp4 v[56:57], v114, 1.0 op_sel:[1,1,0]
	v_pk_fma_f32 v[28:29], v[62:63], v[84:85], v[28:29] op_sel:[0,1,0] op_sel_hi:[1,1,1]
	v_pk_fma_f32 v[30:31], v[60:61], v[84:85], v[30:31] op_sel:[0,1,0] op_sel_hi:[1,1,1]
	v_pk_fma_f32 v[32:33], v[18:19], v[84:85], v[32:33] op_sel:[0,1,0] op_sel_hi:[1,1,1]
	v_pk_fma_f32 v[34:35], v[64:65], v[84:85], v[34:35] op_sel:[0,1,0] op_sel_hi:[1,1,1]
	v_cvt_scalef32_pk_f32_fp4 v[62:63], v115, 1.0
	v_cvt_scalef32_pk_f32_fp4 v[60:61], v115, 1.0 op_sel:[1,0,0]
	v_cvt_scalef32_pk_f32_fp4 v[18:19], v115, 1.0 op_sel:[0,1,0]
	v_cvt_scalef32_pk_f32_fp4 v[64:65], v115, 1.0 op_sel:[1,1,0]
	v_pk_fma_f32 v[36:37], v[54:55], v[84:85], v[36:37] op_sel:[0,1,0] op_sel_hi:[1,1,1]
	v_pk_fma_f32 v[38:39], v[52:53], v[84:85], v[38:39] op_sel:[0,1,0] op_sel_hi:[1,1,1]
	v_pk_fma_f32 v[40:41], v[58:59], v[84:85], v[40:41] op_sel:[0,1,0] op_sel_hi:[1,1,1]
	v_pk_fma_f32 v[42:43], v[56:57], v[84:85], v[42:43] op_sel:[0,1,0] op_sel_hi:[1,1,1]
	v_pk_fma_f32 v[44:45], v[62:63], v[84:85], v[44:45] op_sel:[0,1,0] op_sel_hi:[1,1,1]
	v_pk_fma_f32 v[46:47], v[60:61], v[84:85], v[46:47] op_sel:[0,1,0] op_sel_hi:[1,1,1]
	v_pk_fma_f32 v[48:49], v[18:19], v[84:85], v[48:49] op_sel:[0,1,0] op_sel_hi:[1,1,1]
	v_pk_fma_f32 v[50:51], v[64:65], v[84:85], v[50:51] op_sel:[0,1,0] op_sel_hi:[1,1,1]
	global_load_dwordx4 v[112:115], v5, s[40:41]
	s_waitcnt vmcnt(15)
	v_cvt_scalef32_pk_f32_fp4 v[54:55], v116, 1.0
	v_cvt_scalef32_pk_f32_fp4 v[52:53], v116, 1.0 op_sel:[1,0,0]
	v_cvt_scalef32_pk_f32_fp4 v[58:59], v116, 1.0 op_sel:[0,1,0]
	v_cvt_scalef32_pk_f32_fp4 v[56:57], v116, 1.0 op_sel:[1,1,0]
	v_cvt_scalef32_pk_f32_fp4 v[62:63], v117, 1.0
	v_cvt_scalef32_pk_f32_fp4 v[60:61], v117, 1.0 op_sel:[1,0,0]
	v_cvt_scalef32_pk_f32_fp4 v[18:19], v117, 1.0 op_sel:[0,1,0]
	v_cvt_scalef32_pk_f32_fp4 v[64:65], v117, 1.0 op_sel:[1,1,0]
	v_pk_fma_f32 v[20:21], v[54:55], v[86:87], v[20:21] op_sel_hi:[1,0,1]
	v_pk_fma_f32 v[22:23], v[52:53], v[86:87], v[22:23] op_sel_hi:[1,0,1]
	v_pk_fma_f32 v[24:25], v[58:59], v[86:87], v[24:25] op_sel_hi:[1,0,1]
	v_pk_fma_f32 v[26:27], v[56:57], v[86:87], v[26:27] op_sel_hi:[1,0,1]
	v_cvt_scalef32_pk_f32_fp4 v[54:55], v118, 1.0
	v_cvt_scalef32_pk_f32_fp4 v[52:53], v118, 1.0 op_sel:[1,0,0]
	v_cvt_scalef32_pk_f32_fp4 v[58:59], v118, 1.0 op_sel:[0,1,0]
	v_cvt_scalef32_pk_f32_fp4 v[56:57], v118, 1.0 op_sel:[1,1,0]
	v_pk_fma_f32 v[28:29], v[62:63], v[86:87], v[28:29] op_sel_hi:[1,0,1]
	v_pk_fma_f32 v[30:31], v[60:61], v[86:87], v[30:31] op_sel_hi:[1,0,1]
	v_pk_fma_f32 v[32:33], v[18:19], v[86:87], v[32:33] op_sel_hi:[1,0,1]
	v_pk_fma_f32 v[34:35], v[64:65], v[86:87], v[34:35] op_sel_hi:[1,0,1]
	v_cvt_scalef32_pk_f32_fp4 v[62:63], v119, 1.0
	v_cvt_scalef32_pk_f32_fp4 v[60:61], v119, 1.0 op_sel:[1,0,0]
	v_cvt_scalef32_pk_f32_fp4 v[18:19], v119, 1.0 op_sel:[0,1,0]
	v_cvt_scalef32_pk_f32_fp4 v[64:65], v119, 1.0 op_sel:[1,1,0]
	v_pk_fma_f32 v[36:37], v[54:55], v[86:87], v[36:37] op_sel_hi:[1,0,1]
	v_pk_fma_f32 v[38:39], v[52:53], v[86:87], v[38:39] op_sel_hi:[1,0,1]
	v_pk_fma_f32 v[40:41], v[58:59], v[86:87], v[40:41] op_sel_hi:[1,0,1]
	v_pk_fma_f32 v[42:43], v[56:57], v[86:87], v[42:43] op_sel_hi:[1,0,1]
	v_pk_fma_f32 v[44:45], v[62:63], v[86:87], v[44:45] op_sel_hi:[1,0,1]
	v_pk_fma_f32 v[46:47], v[60:61], v[86:87], v[46:47] op_sel_hi:[1,0,1]
	v_pk_fma_f32 v[48:49], v[18:19], v[86:87], v[48:49] op_sel_hi:[1,0,1]
	v_pk_fma_f32 v[50:51], v[64:65], v[86:87], v[50:51] op_sel_hi:[1,0,1]
	global_load_dwordx4 v[116:119], v6, s[40:41]
	s_waitcnt vmcnt(15)
	v_cvt_scalef32_pk_f32_fp4 v[54:55], v120, 1.0
	v_cvt_scalef32_pk_f32_fp4 v[52:53], v120, 1.0 op_sel:[1,0,0]
	v_cvt_scalef32_pk_f32_fp4 v[58:59], v120, 1.0 op_sel:[0,1,0]
	v_cvt_scalef32_pk_f32_fp4 v[56:57], v120, 1.0 op_sel:[1,1,0]
	v_cvt_scalef32_pk_f32_fp4 v[62:63], v121, 1.0
	v_cvt_scalef32_pk_f32_fp4 v[60:61], v121, 1.0 op_sel:[1,0,0]
	v_cvt_scalef32_pk_f32_fp4 v[18:19], v121, 1.0 op_sel:[0,1,0]
	v_cvt_scalef32_pk_f32_fp4 v[64:65], v121, 1.0 op_sel:[1,1,0]
	v_pk_fma_f32 v[20:21], v[54:55], v[86:87], v[20:21] op_sel:[0,1,0] op_sel_hi:[1,1,1]
	v_pk_fma_f32 v[22:23], v[52:53], v[86:87], v[22:23] op_sel:[0,1,0] op_sel_hi:[1,1,1]
	v_pk_fma_f32 v[24:25], v[58:59], v[86:87], v[24:25] op_sel:[0,1,0] op_sel_hi:[1,1,1]
	v_pk_fma_f32 v[26:27], v[56:57], v[86:87], v[26:27] op_sel:[0,1,0] op_sel_hi:[1,1,1]
	v_cvt_scalef32_pk_f32_fp4 v[54:55], v122, 1.0
	v_cvt_scalef32_pk_f32_fp4 v[52:53], v122, 1.0 op_sel:[1,0,0]
	v_cvt_scalef32_pk_f32_fp4 v[58:59], v122, 1.0 op_sel:[0,1,0]
	v_cvt_scalef32_pk_f32_fp4 v[56:57], v122, 1.0 op_sel:[1,1,0]
	v_pk_fma_f32 v[28:29], v[62:63], v[86:87], v[28:29] op_sel:[0,1,0] op_sel_hi:[1,1,1]
	v_pk_fma_f32 v[30:31], v[60:61], v[86:87], v[30:31] op_sel:[0,1,0] op_sel_hi:[1,1,1]
	v_pk_fma_f32 v[32:33], v[18:19], v[86:87], v[32:33] op_sel:[0,1,0] op_sel_hi:[1,1,1]
	v_pk_fma_f32 v[34:35], v[64:65], v[86:87], v[34:35] op_sel:[0,1,0] op_sel_hi:[1,1,1]
	v_cvt_scalef32_pk_f32_fp4 v[62:63], v123, 1.0
	v_cvt_scalef32_pk_f32_fp4 v[60:61], v123, 1.0 op_sel:[1,0,0]
	v_cvt_scalef32_pk_f32_fp4 v[18:19], v123, 1.0 op_sel:[0,1,0]
	v_cvt_scalef32_pk_f32_fp4 v[64:65], v123, 1.0 op_sel:[1,1,0]
	v_pk_fma_f32 v[36:37], v[54:55], v[86:87], v[36:37] op_sel:[0,1,0] op_sel_hi:[1,1,1]
	v_pk_fma_f32 v[38:39], v[52:53], v[86:87], v[38:39] op_sel:[0,1,0] op_sel_hi:[1,1,1]
	v_pk_fma_f32 v[40:41], v[58:59], v[86:87], v[40:41] op_sel:[0,1,0] op_sel_hi:[1,1,1]
	v_pk_fma_f32 v[42:43], v[56:57], v[86:87], v[42:43] op_sel:[0,1,0] op_sel_hi:[1,1,1]
	v_pk_fma_f32 v[44:45], v[62:63], v[86:87], v[44:45] op_sel:[0,1,0] op_sel_hi:[1,1,1]
	v_pk_fma_f32 v[46:47], v[60:61], v[86:87], v[46:47] op_sel:[0,1,0] op_sel_hi:[1,1,1]
	v_pk_fma_f32 v[48:49], v[18:19], v[86:87], v[48:49] op_sel:[0,1,0] op_sel_hi:[1,1,1]
	v_pk_fma_f32 v[50:51], v[64:65], v[86:87], v[50:51] op_sel:[0,1,0] op_sel_hi:[1,1,1]
	global_load_dwordx4 v[120:123], v7, s[40:41]
	s_waitcnt vmcnt(15)
	v_cvt_scalef32_pk_f32_fp4 v[54:55], v124, 1.0
	v_cvt_scalef32_pk_f32_fp4 v[52:53], v124, 1.0 op_sel:[1,0,0]
	v_cvt_scalef32_pk_f32_fp4 v[58:59], v124, 1.0 op_sel:[0,1,0]
	v_cvt_scalef32_pk_f32_fp4 v[56:57], v124, 1.0 op_sel:[1,1,0]
	v_cvt_scalef32_pk_f32_fp4 v[62:63], v125, 1.0
	v_cvt_scalef32_pk_f32_fp4 v[60:61], v125, 1.0 op_sel:[1,0,0]
	v_cvt_scalef32_pk_f32_fp4 v[18:19], v125, 1.0 op_sel:[0,1,0]
	v_cvt_scalef32_pk_f32_fp4 v[64:65], v125, 1.0 op_sel:[1,1,0]
	v_pk_fma_f32 v[20:21], v[54:55], v[88:89], v[20:21] op_sel_hi:[1,0,1]
	v_pk_fma_f32 v[22:23], v[52:53], v[88:89], v[22:23] op_sel_hi:[1,0,1]
	v_pk_fma_f32 v[24:25], v[58:59], v[88:89], v[24:25] op_sel_hi:[1,0,1]
	v_pk_fma_f32 v[26:27], v[56:57], v[88:89], v[26:27] op_sel_hi:[1,0,1]
	v_cvt_scalef32_pk_f32_fp4 v[54:55], v126, 1.0
	v_cvt_scalef32_pk_f32_fp4 v[52:53], v126, 1.0 op_sel:[1,0,0]
	v_cvt_scalef32_pk_f32_fp4 v[58:59], v126, 1.0 op_sel:[0,1,0]
	v_cvt_scalef32_pk_f32_fp4 v[56:57], v126, 1.0 op_sel:[1,1,0]
	v_pk_fma_f32 v[28:29], v[62:63], v[88:89], v[28:29] op_sel_hi:[1,0,1]
	v_pk_fma_f32 v[30:31], v[60:61], v[88:89], v[30:31] op_sel_hi:[1,0,1]
	v_pk_fma_f32 v[32:33], v[18:19], v[88:89], v[32:33] op_sel_hi:[1,0,1]
	v_pk_fma_f32 v[34:35], v[64:65], v[88:89], v[34:35] op_sel_hi:[1,0,1]
	v_cvt_scalef32_pk_f32_fp4 v[62:63], v127, 1.0
	v_cvt_scalef32_pk_f32_fp4 v[60:61], v127, 1.0 op_sel:[1,0,0]
	v_cvt_scalef32_pk_f32_fp4 v[18:19], v127, 1.0 op_sel:[0,1,0]
	v_cvt_scalef32_pk_f32_fp4 v[64:65], v127, 1.0 op_sel:[1,1,0]
	v_pk_fma_f32 v[36:37], v[54:55], v[88:89], v[36:37] op_sel_hi:[1,0,1]
	v_pk_fma_f32 v[38:39], v[52:53], v[88:89], v[38:39] op_sel_hi:[1,0,1]
	v_pk_fma_f32 v[40:41], v[58:59], v[88:89], v[40:41] op_sel_hi:[1,0,1]
	v_pk_fma_f32 v[42:43], v[56:57], v[88:89], v[42:43] op_sel_hi:[1,0,1]
	v_pk_fma_f32 v[44:45], v[62:63], v[88:89], v[44:45] op_sel_hi:[1,0,1]
	v_pk_fma_f32 v[46:47], v[60:61], v[88:89], v[46:47] op_sel_hi:[1,0,1]
	v_pk_fma_f32 v[48:49], v[18:19], v[88:89], v[48:49] op_sel_hi:[1,0,1]
	v_pk_fma_f32 v[50:51], v[64:65], v[88:89], v[50:51] op_sel_hi:[1,0,1]
	global_load_dwordx4 v[124:127], v8, s[40:41]
	s_waitcnt vmcnt(15)
	v_cvt_scalef32_pk_f32_fp4 v[54:55], v128, 1.0
	v_cvt_scalef32_pk_f32_fp4 v[52:53], v128, 1.0 op_sel:[1,0,0]
	v_cvt_scalef32_pk_f32_fp4 v[58:59], v128, 1.0 op_sel:[0,1,0]
	v_cvt_scalef32_pk_f32_fp4 v[56:57], v128, 1.0 op_sel:[1,1,0]
	v_cvt_scalef32_pk_f32_fp4 v[62:63], v129, 1.0
	v_cvt_scalef32_pk_f32_fp4 v[60:61], v129, 1.0 op_sel:[1,0,0]
	v_cvt_scalef32_pk_f32_fp4 v[18:19], v129, 1.0 op_sel:[0,1,0]
	v_cvt_scalef32_pk_f32_fp4 v[64:65], v129, 1.0 op_sel:[1,1,0]
	v_pk_fma_f32 v[20:21], v[54:55], v[88:89], v[20:21] op_sel:[0,1,0] op_sel_hi:[1,1,1]
	v_pk_fma_f32 v[22:23], v[52:53], v[88:89], v[22:23] op_sel:[0,1,0] op_sel_hi:[1,1,1]
	v_pk_fma_f32 v[24:25], v[58:59], v[88:89], v[24:25] op_sel:[0,1,0] op_sel_hi:[1,1,1]
	v_pk_fma_f32 v[26:27], v[56:57], v[88:89], v[26:27] op_sel:[0,1,0] op_sel_hi:[1,1,1]
	v_cvt_scalef32_pk_f32_fp4 v[54:55], v130, 1.0
	v_cvt_scalef32_pk_f32_fp4 v[52:53], v130, 1.0 op_sel:[1,0,0]
	v_cvt_scalef32_pk_f32_fp4 v[58:59], v130, 1.0 op_sel:[0,1,0]
	v_cvt_scalef32_pk_f32_fp4 v[56:57], v130, 1.0 op_sel:[1,1,0]
	v_pk_fma_f32 v[28:29], v[62:63], v[88:89], v[28:29] op_sel:[0,1,0] op_sel_hi:[1,1,1]
	v_pk_fma_f32 v[30:31], v[60:61], v[88:89], v[30:31] op_sel:[0,1,0] op_sel_hi:[1,1,1]
	v_pk_fma_f32 v[32:33], v[18:19], v[88:89], v[32:33] op_sel:[0,1,0] op_sel_hi:[1,1,1]
	v_pk_fma_f32 v[34:35], v[64:65], v[88:89], v[34:35] op_sel:[0,1,0] op_sel_hi:[1,1,1]
	v_cvt_scalef32_pk_f32_fp4 v[62:63], v131, 1.0
	v_cvt_scalef32_pk_f32_fp4 v[60:61], v131, 1.0 op_sel:[1,0,0]
	v_cvt_scalef32_pk_f32_fp4 v[18:19], v131, 1.0 op_sel:[0,1,0]
	v_cvt_scalef32_pk_f32_fp4 v[64:65], v131, 1.0 op_sel:[1,1,0]
	v_pk_fma_f32 v[36:37], v[54:55], v[88:89], v[36:37] op_sel:[0,1,0] op_sel_hi:[1,1,1]
	v_pk_fma_f32 v[38:39], v[52:53], v[88:89], v[38:39] op_sel:[0,1,0] op_sel_hi:[1,1,1]
	v_pk_fma_f32 v[40:41], v[58:59], v[88:89], v[40:41] op_sel:[0,1,0] op_sel_hi:[1,1,1]
	v_pk_fma_f32 v[42:43], v[56:57], v[88:89], v[42:43] op_sel:[0,1,0] op_sel_hi:[1,1,1]
	v_pk_fma_f32 v[44:45], v[62:63], v[88:89], v[44:45] op_sel:[0,1,0] op_sel_hi:[1,1,1]
	v_pk_fma_f32 v[46:47], v[60:61], v[88:89], v[46:47] op_sel:[0,1,0] op_sel_hi:[1,1,1]
	v_pk_fma_f32 v[48:49], v[18:19], v[88:89], v[48:49] op_sel:[0,1,0] op_sel_hi:[1,1,1]
	v_pk_fma_f32 v[50:51], v[64:65], v[88:89], v[50:51] op_sel:[0,1,0] op_sel_hi:[1,1,1]
	global_load_dwordx4 v[128:131], v9, s[40:41]
	s_lshl_b32 s100, s14, 1
	s_add_i32 s100, s100, 3
	s_lshr_b32 s101, s100, 4
	s_and_b32 s100, s100, 15
	s_lshl_b32 s100, s100, 5
	v_add_u32_e32 v1, s100, v164
	s_add_i32 s101, s101, s13
	s_min_u32 s101, s101, 7
	s_lshl_b32 s101, s101, 21
	s_add_u32 s40, s58, s101
	s_addc_u32 s41, s59, 0
	ds_read_b128 v[2:5], v1 offset:0
	ds_read_b128 v[6:9], v1 offset:16
	s_lshl_b32 s100, s14, 1
	s_add_i32 s100, s100, 2
	s_and_b32 s100, s100, 15
	s_lshl_b32 s100, s100, 5
	v_add_u32_e32 v169, s100, v168
	ds_read_b128 v[82:85], v169
	ds_read_b128 v[86:89], v169 offset:16
	s_waitcnt vmcnt(15)
	v_cvt_scalef32_pk_f32_fp4 v[54:55], v132, 1.0
	v_cvt_scalef32_pk_f32_fp4 v[52:53], v132, 1.0 op_sel:[1,0,0]
	v_cvt_scalef32_pk_f32_fp4 v[58:59], v132, 1.0 op_sel:[0,1,0]
	v_cvt_scalef32_pk_f32_fp4 v[56:57], v132, 1.0 op_sel:[1,1,0]
	v_cvt_scalef32_pk_f32_fp4 v[62:63], v133, 1.0
	v_cvt_scalef32_pk_f32_fp4 v[60:61], v133, 1.0 op_sel:[1,0,0]
	v_cvt_scalef32_pk_f32_fp4 v[18:19], v133, 1.0 op_sel:[0,1,0]
	v_cvt_scalef32_pk_f32_fp4 v[64:65], v133, 1.0 op_sel:[1,1,0]
	s_waitcnt lgkmcnt(4)
	v_pk_fma_f32 v[20:21], v[54:55], v[90:91], v[20:21] op_sel_hi:[1,0,1]
	v_pk_fma_f32 v[22:23], v[52:53], v[90:91], v[22:23] op_sel_hi:[1,0,1]
	v_pk_fma_f32 v[24:25], v[58:59], v[90:91], v[24:25] op_sel_hi:[1,0,1]
	v_pk_fma_f32 v[26:27], v[56:57], v[90:91], v[26:27] op_sel_hi:[1,0,1]
	v_cvt_scalef32_pk_f32_fp4 v[54:55], v134, 1.0
	v_cvt_scalef32_pk_f32_fp4 v[52:53], v134, 1.0 op_sel:[1,0,0]
	v_cvt_scalef32_pk_f32_fp4 v[58:59], v134, 1.0 op_sel:[0,1,0]
	v_cvt_scalef32_pk_f32_fp4 v[56:57], v134, 1.0 op_sel:[1,1,0]
	v_pk_fma_f32 v[28:29], v[62:63], v[90:91], v[28:29] op_sel_hi:[1,0,1]
	v_pk_fma_f32 v[30:31], v[60:61], v[90:91], v[30:31] op_sel_hi:[1,0,1]
	v_pk_fma_f32 v[32:33], v[18:19], v[90:91], v[32:33] op_sel_hi:[1,0,1]
	v_pk_fma_f32 v[34:35], v[64:65], v[90:91], v[34:35] op_sel_hi:[1,0,1]
	v_cvt_scalef32_pk_f32_fp4 v[62:63], v135, 1.0
	v_cvt_scalef32_pk_f32_fp4 v[60:61], v135, 1.0 op_sel:[1,0,0]
	v_cvt_scalef32_pk_f32_fp4 v[18:19], v135, 1.0 op_sel:[0,1,0]
	v_cvt_scalef32_pk_f32_fp4 v[64:65], v135, 1.0 op_sel:[1,1,0]
	v_pk_fma_f32 v[36:37], v[54:55], v[90:91], v[36:37] op_sel_hi:[1,0,1]
	v_pk_fma_f32 v[38:39], v[52:53], v[90:91], v[38:39] op_sel_hi:[1,0,1]
	v_pk_fma_f32 v[40:41], v[58:59], v[90:91], v[40:41] op_sel_hi:[1,0,1]
	v_pk_fma_f32 v[42:43], v[56:57], v[90:91], v[42:43] op_sel_hi:[1,0,1]
	v_pk_fma_f32 v[44:45], v[62:63], v[90:91], v[44:45] op_sel_hi:[1,0,1]
	v_pk_fma_f32 v[46:47], v[60:61], v[90:91], v[46:47] op_sel_hi:[1,0,1]
	v_pk_fma_f32 v[48:49], v[18:19], v[90:91], v[48:49] op_sel_hi:[1,0,1]
	v_pk_fma_f32 v[50:51], v[64:65], v[90:91], v[50:51] op_sel_hi:[1,0,1]
	s_waitcnt lgkmcnt(2)
	v_lshl_add_u32 v2, v2, 7, v78
	v_lshl_add_u32 v3, v3, 7, v78
	v_lshl_add_u32 v4, v4, 7, v78
	v_lshl_add_u32 v5, v5, 7, v78
	v_lshl_add_u32 v6, v6, 7, v78
	v_lshl_add_u32 v7, v7, 7, v78
	v_lshl_add_u32 v8, v8, 7, v78
	v_lshl_add_u32 v9, v9, 7, v78
	global_load_dwordx4 v[132:135], v2, s[40:41]
	s_waitcnt vmcnt(15)
	v_cvt_scalef32_pk_f32_fp4 v[54:55], v136, 1.0
	v_cvt_scalef32_pk_f32_fp4 v[52:53], v136, 1.0 op_sel:[1,0,0]
	v_cvt_scalef32_pk_f32_fp4 v[58:59], v136, 1.0 op_sel:[0,1,0]
	v_cvt_scalef32_pk_f32_fp4 v[56:57], v136, 1.0 op_sel:[1,1,0]
	v_cvt_scalef32_pk_f32_fp4 v[62:63], v137, 1.0
	v_cvt_scalef32_pk_f32_fp4 v[60:61], v137, 1.0 op_sel:[1,0,0]
	v_cvt_scalef32_pk_f32_fp4 v[18:19], v137, 1.0 op_sel:[0,1,0]
	v_cvt_scalef32_pk_f32_fp4 v[64:65], v137, 1.0 op_sel:[1,1,0]
	v_pk_fma_f32 v[20:21], v[54:55], v[90:91], v[20:21] op_sel:[0,1,0] op_sel_hi:[1,1,1]
	v_pk_fma_f32 v[22:23], v[52:53], v[90:91], v[22:23] op_sel:[0,1,0] op_sel_hi:[1,1,1]
	v_pk_fma_f32 v[24:25], v[58:59], v[90:91], v[24:25] op_sel:[0,1,0] op_sel_hi:[1,1,1]
	v_pk_fma_f32 v[26:27], v[56:57], v[90:91], v[26:27] op_sel:[0,1,0] op_sel_hi:[1,1,1]
	v_cvt_scalef32_pk_f32_fp4 v[54:55], v138, 1.0
	v_cvt_scalef32_pk_f32_fp4 v[52:53], v138, 1.0 op_sel:[1,0,0]
	v_cvt_scalef32_pk_f32_fp4 v[58:59], v138, 1.0 op_sel:[0,1,0]
	v_cvt_scalef32_pk_f32_fp4 v[56:57], v138, 1.0 op_sel:[1,1,0]
	v_pk_fma_f32 v[28:29], v[62:63], v[90:91], v[28:29] op_sel:[0,1,0] op_sel_hi:[1,1,1]
	v_pk_fma_f32 v[30:31], v[60:61], v[90:91], v[30:31] op_sel:[0,1,0] op_sel_hi:[1,1,1]
	v_pk_fma_f32 v[32:33], v[18:19], v[90:91], v[32:33] op_sel:[0,1,0] op_sel_hi:[1,1,1]
	v_pk_fma_f32 v[34:35], v[64:65], v[90:91], v[34:35] op_sel:[0,1,0] op_sel_hi:[1,1,1]
	v_cvt_scalef32_pk_f32_fp4 v[62:63], v139, 1.0
	v_cvt_scalef32_pk_f32_fp4 v[60:61], v139, 1.0 op_sel:[1,0,0]
	v_cvt_scalef32_pk_f32_fp4 v[18:19], v139, 1.0 op_sel:[0,1,0]
	v_cvt_scalef32_pk_f32_fp4 v[64:65], v139, 1.0 op_sel:[1,1,0]
	v_pk_fma_f32 v[36:37], v[54:55], v[90:91], v[36:37] op_sel:[0,1,0] op_sel_hi:[1,1,1]
	v_pk_fma_f32 v[38:39], v[52:53], v[90:91], v[38:39] op_sel:[0,1,0] op_sel_hi:[1,1,1]
	v_pk_fma_f32 v[40:41], v[58:59], v[90:91], v[40:41] op_sel:[0,1,0] op_sel_hi:[1,1,1]
	v_pk_fma_f32 v[42:43], v[56:57], v[90:91], v[42:43] op_sel:[0,1,0] op_sel_hi:[1,1,1]
	v_pk_fma_f32 v[44:45], v[62:63], v[90:91], v[44:45] op_sel:[0,1,0] op_sel_hi:[1,1,1]
	v_pk_fma_f32 v[46:47], v[60:61], v[90:91], v[46:47] op_sel:[0,1,0] op_sel_hi:[1,1,1]
	v_pk_fma_f32 v[48:49], v[18:19], v[90:91], v[48:49] op_sel:[0,1,0] op_sel_hi:[1,1,1]
	v_pk_fma_f32 v[50:51], v[64:65], v[90:91], v[50:51] op_sel:[0,1,0] op_sel_hi:[1,1,1]
	global_load_dwordx4 v[136:139], v3, s[40:41]
	s_waitcnt vmcnt(15)
	v_cvt_scalef32_pk_f32_fp4 v[54:55], v140, 1.0
	v_cvt_scalef32_pk_f32_fp4 v[52:53], v140, 1.0 op_sel:[1,0,0]
	v_cvt_scalef32_pk_f32_fp4 v[58:59], v140, 1.0 op_sel:[0,1,0]
	v_cvt_scalef32_pk_f32_fp4 v[56:57], v140, 1.0 op_sel:[1,1,0]
	v_cvt_scalef32_pk_f32_fp4 v[62:63], v141, 1.0
	v_cvt_scalef32_pk_f32_fp4 v[60:61], v141, 1.0 op_sel:[1,0,0]
	v_cvt_scalef32_pk_f32_fp4 v[18:19], v141, 1.0 op_sel:[0,1,0]
	v_cvt_scalef32_pk_f32_fp4 v[64:65], v141, 1.0 op_sel:[1,1,0]
	v_pk_fma_f32 v[20:21], v[54:55], v[92:93], v[20:21] op_sel_hi:[1,0,1]
	v_pk_fma_f32 v[22:23], v[52:53], v[92:93], v[22:23] op_sel_hi:[1,0,1]
	v_pk_fma_f32 v[24:25], v[58:59], v[92:93], v[24:25] op_sel_hi:[1,0,1]
	v_pk_fma_f32 v[26:27], v[56:57], v[92:93], v[26:27] op_sel_hi:[1,0,1]
	v_cvt_scalef32_pk_f32_fp4 v[54:55], v142, 1.0
	v_cvt_scalef32_pk_f32_fp4 v[52:53], v142, 1.0 op_sel:[1,0,0]
	v_cvt_scalef32_pk_f32_fp4 v[58:59], v142, 1.0 op_sel:[0,1,0]
	v_cvt_scalef32_pk_f32_fp4 v[56:57], v142, 1.0 op_sel:[1,1,0]
	v_pk_fma_f32 v[28:29], v[62:63], v[92:93], v[28:29] op_sel_hi:[1,0,1]
	v_pk_fma_f32 v[30:31], v[60:61], v[92:93], v[30:31] op_sel_hi:[1,0,1]
	v_pk_fma_f32 v[32:33], v[18:19], v[92:93], v[32:33] op_sel_hi:[1,0,1]
	v_pk_fma_f32 v[34:35], v[64:65], v[92:93], v[34:35] op_sel_hi:[1,0,1]
	v_cvt_scalef32_pk_f32_fp4 v[62:63], v143, 1.0
	v_cvt_scalef32_pk_f32_fp4 v[60:61], v143, 1.0 op_sel:[1,0,0]
	v_cvt_scalef32_pk_f32_fp4 v[18:19], v143, 1.0 op_sel:[0,1,0]
	v_cvt_scalef32_pk_f32_fp4 v[64:65], v143, 1.0 op_sel:[1,1,0]
	v_pk_fma_f32 v[36:37], v[54:55], v[92:93], v[36:37] op_sel_hi:[1,0,1]
	v_pk_fma_f32 v[38:39], v[52:53], v[92:93], v[38:39] op_sel_hi:[1,0,1]
	v_pk_fma_f32 v[40:41], v[58:59], v[92:93], v[40:41] op_sel_hi:[1,0,1]
	v_pk_fma_f32 v[42:43], v[56:57], v[92:93], v[42:43] op_sel_hi:[1,0,1]
	v_pk_fma_f32 v[44:45], v[62:63], v[92:93], v[44:45] op_sel_hi:[1,0,1]
	v_pk_fma_f32 v[46:47], v[60:61], v[92:93], v[46:47] op_sel_hi:[1,0,1]
	v_pk_fma_f32 v[48:49], v[18:19], v[92:93], v[48:49] op_sel_hi:[1,0,1]
	v_pk_fma_f32 v[50:51], v[64:65], v[92:93], v[50:51] op_sel_hi:[1,0,1]
	global_load_dwordx4 v[140:143], v4, s[40:41]
	s_waitcnt vmcnt(15)
	v_cvt_scalef32_pk_f32_fp4 v[54:55], v144, 1.0
	v_cvt_scalef32_pk_f32_fp4 v[52:53], v144, 1.0 op_sel:[1,0,0]
	v_cvt_scalef32_pk_f32_fp4 v[58:59], v144, 1.0 op_sel:[0,1,0]
	v_cvt_scalef32_pk_f32_fp4 v[56:57], v144, 1.0 op_sel:[1,1,0]
	v_cvt_scalef32_pk_f32_fp4 v[62:63], v145, 1.0
	v_cvt_scalef32_pk_f32_fp4 v[60:61], v145, 1.0 op_sel:[1,0,0]
	v_cvt_scalef32_pk_f32_fp4 v[18:19], v145, 1.0 op_sel:[0,1,0]
	v_cvt_scalef32_pk_f32_fp4 v[64:65], v145, 1.0 op_sel:[1,1,0]
	v_pk_fma_f32 v[20:21], v[54:55], v[92:93], v[20:21] op_sel:[0,1,0] op_sel_hi:[1,1,1]
	v_pk_fma_f32 v[22:23], v[52:53], v[92:93], v[22:23] op_sel:[0,1,0] op_sel_hi:[1,1,1]
	v_pk_fma_f32 v[24:25], v[58:59], v[92:93], v[24:25] op_sel:[0,1,0] op_sel_hi:[1,1,1]
	v_pk_fma_f32 v[26:27], v[56:57], v[92:93], v[26:27] op_sel:[0,1,0] op_sel_hi:[1,1,1]
	v_cvt_scalef32_pk_f32_fp4 v[54:55], v146, 1.0
	v_cvt_scalef32_pk_f32_fp4 v[52:53], v146, 1.0 op_sel:[1,0,0]
	v_cvt_scalef32_pk_f32_fp4 v[58:59], v146, 1.0 op_sel:[0,1,0]
	v_cvt_scalef32_pk_f32_fp4 v[56:57], v146, 1.0 op_sel:[1,1,0]
	v_pk_fma_f32 v[28:29], v[62:63], v[92:93], v[28:29] op_sel:[0,1,0] op_sel_hi:[1,1,1]
	v_pk_fma_f32 v[30:31], v[60:61], v[92:93], v[30:31] op_sel:[0,1,0] op_sel_hi:[1,1,1]
	v_pk_fma_f32 v[32:33], v[18:19], v[92:93], v[32:33] op_sel:[0,1,0] op_sel_hi:[1,1,1]
	v_pk_fma_f32 v[34:35], v[64:65], v[92:93], v[34:35] op_sel:[0,1,0] op_sel_hi:[1,1,1]
	v_cvt_scalef32_pk_f32_fp4 v[62:63], v147, 1.0
	v_cvt_scalef32_pk_f32_fp4 v[60:61], v147, 1.0 op_sel:[1,0,0]
	v_cvt_scalef32_pk_f32_fp4 v[18:19], v147, 1.0 op_sel:[0,1,0]
	v_cvt_scalef32_pk_f32_fp4 v[64:65], v147, 1.0 op_sel:[1,1,0]
	v_pk_fma_f32 v[36:37], v[54:55], v[92:93], v[36:37] op_sel:[0,1,0] op_sel_hi:[1,1,1]
	v_pk_fma_f32 v[38:39], v[52:53], v[92:93], v[38:39] op_sel:[0,1,0] op_sel_hi:[1,1,1]
	v_pk_fma_f32 v[40:41], v[58:59], v[92:93], v[40:41] op_sel:[0,1,0] op_sel_hi:[1,1,1]
	v_pk_fma_f32 v[42:43], v[56:57], v[92:93], v[42:43] op_sel:[0,1,0] op_sel_hi:[1,1,1]
	v_pk_fma_f32 v[44:45], v[62:63], v[92:93], v[44:45] op_sel:[0,1,0] op_sel_hi:[1,1,1]
	v_pk_fma_f32 v[46:47], v[60:61], v[92:93], v[46:47] op_sel:[0,1,0] op_sel_hi:[1,1,1]
	v_pk_fma_f32 v[48:49], v[18:19], v[92:93], v[48:49] op_sel:[0,1,0] op_sel_hi:[1,1,1]
	v_pk_fma_f32 v[50:51], v[64:65], v[92:93], v[50:51] op_sel:[0,1,0] op_sel_hi:[1,1,1]
	global_load_dwordx4 v[144:147], v5, s[40:41]
	s_waitcnt vmcnt(15)
	v_cvt_scalef32_pk_f32_fp4 v[54:55], v148, 1.0
	v_cvt_scalef32_pk_f32_fp4 v[52:53], v148, 1.0 op_sel:[1,0,0]
	v_cvt_scalef32_pk_f32_fp4 v[58:59], v148, 1.0 op_sel:[0,1,0]
	v_cvt_scalef32_pk_f32_fp4 v[56:57], v148, 1.0 op_sel:[1,1,0]
	v_cvt_scalef32_pk_f32_fp4 v[62:63], v149, 1.0
	v_cvt_scalef32_pk_f32_fp4 v[60:61], v149, 1.0 op_sel:[1,0,0]
	v_cvt_scalef32_pk_f32_fp4 v[18:19], v149, 1.0 op_sel:[0,1,0]
	v_cvt_scalef32_pk_f32_fp4 v[64:65], v149, 1.0 op_sel:[1,1,0]
	v_pk_fma_f32 v[20:21], v[54:55], v[94:95], v[20:21] op_sel_hi:[1,0,1]
	v_pk_fma_f32 v[22:23], v[52:53], v[94:95], v[22:23] op_sel_hi:[1,0,1]
	v_pk_fma_f32 v[24:25], v[58:59], v[94:95], v[24:25] op_sel_hi:[1,0,1]
	v_pk_fma_f32 v[26:27], v[56:57], v[94:95], v[26:27] op_sel_hi:[1,0,1]
	v_cvt_scalef32_pk_f32_fp4 v[54:55], v150, 1.0
	v_cvt_scalef32_pk_f32_fp4 v[52:53], v150, 1.0 op_sel:[1,0,0]
	v_cvt_scalef32_pk_f32_fp4 v[58:59], v150, 1.0 op_sel:[0,1,0]
	v_cvt_scalef32_pk_f32_fp4 v[56:57], v150, 1.0 op_sel:[1,1,0]
	v_pk_fma_f32 v[28:29], v[62:63], v[94:95], v[28:29] op_sel_hi:[1,0,1]
	v_pk_fma_f32 v[30:31], v[60:61], v[94:95], v[30:31] op_sel_hi:[1,0,1]
	v_pk_fma_f32 v[32:33], v[18:19], v[94:95], v[32:33] op_sel_hi:[1,0,1]
	v_pk_fma_f32 v[34:35], v[64:65], v[94:95], v[34:35] op_sel_hi:[1,0,1]
	v_cvt_scalef32_pk_f32_fp4 v[62:63], v151, 1.0
	v_cvt_scalef32_pk_f32_fp4 v[60:61], v151, 1.0 op_sel:[1,0,0]
	v_cvt_scalef32_pk_f32_fp4 v[18:19], v151, 1.0 op_sel:[0,1,0]
	v_cvt_scalef32_pk_f32_fp4 v[64:65], v151, 1.0 op_sel:[1,1,0]
	v_pk_fma_f32 v[36:37], v[54:55], v[94:95], v[36:37] op_sel_hi:[1,0,1]
	v_pk_fma_f32 v[38:39], v[52:53], v[94:95], v[38:39] op_sel_hi:[1,0,1]
	v_pk_fma_f32 v[40:41], v[58:59], v[94:95], v[40:41] op_sel_hi:[1,0,1]
	v_pk_fma_f32 v[42:43], v[56:57], v[94:95], v[42:43] op_sel_hi:[1,0,1]
	v_pk_fma_f32 v[44:45], v[62:63], v[94:95], v[44:45] op_sel_hi:[1,0,1]
	v_pk_fma_f32 v[46:47], v[60:61], v[94:95], v[46:47] op_sel_hi:[1,0,1]
	v_pk_fma_f32 v[48:49], v[18:19], v[94:95], v[48:49] op_sel_hi:[1,0,1]
	v_pk_fma_f32 v[50:51], v[64:65], v[94:95], v[50:51] op_sel_hi:[1,0,1]
	global_load_dwordx4 v[148:151], v6, s[40:41]
	s_waitcnt vmcnt(15)
	v_cvt_scalef32_pk_f32_fp4 v[54:55], v152, 1.0
	v_cvt_scalef32_pk_f32_fp4 v[52:53], v152, 1.0 op_sel:[1,0,0]
	v_cvt_scalef32_pk_f32_fp4 v[58:59], v152, 1.0 op_sel:[0,1,0]
	v_cvt_scalef32_pk_f32_fp4 v[56:57], v152, 1.0 op_sel:[1,1,0]
	v_cvt_scalef32_pk_f32_fp4 v[62:63], v153, 1.0
	v_cvt_scalef32_pk_f32_fp4 v[60:61], v153, 1.0 op_sel:[1,0,0]
	v_cvt_scalef32_pk_f32_fp4 v[18:19], v153, 1.0 op_sel:[0,1,0]
	v_cvt_scalef32_pk_f32_fp4 v[64:65], v153, 1.0 op_sel:[1,1,0]
	v_pk_fma_f32 v[20:21], v[54:55], v[94:95], v[20:21] op_sel:[0,1,0] op_sel_hi:[1,1,1]
	v_pk_fma_f32 v[22:23], v[52:53], v[94:95], v[22:23] op_sel:[0,1,0] op_sel_hi:[1,1,1]
	v_pk_fma_f32 v[24:25], v[58:59], v[94:95], v[24:25] op_sel:[0,1,0] op_sel_hi:[1,1,1]
	v_pk_fma_f32 v[26:27], v[56:57], v[94:95], v[26:27] op_sel:[0,1,0] op_sel_hi:[1,1,1]
	v_cvt_scalef32_pk_f32_fp4 v[54:55], v154, 1.0
	v_cvt_scalef32_pk_f32_fp4 v[52:53], v154, 1.0 op_sel:[1,0,0]
	v_cvt_scalef32_pk_f32_fp4 v[58:59], v154, 1.0 op_sel:[0,1,0]
	v_cvt_scalef32_pk_f32_fp4 v[56:57], v154, 1.0 op_sel:[1,1,0]
	v_pk_fma_f32 v[28:29], v[62:63], v[94:95], v[28:29] op_sel:[0,1,0] op_sel_hi:[1,1,1]
	v_pk_fma_f32 v[30:31], v[60:61], v[94:95], v[30:31] op_sel:[0,1,0] op_sel_hi:[1,1,1]
	v_pk_fma_f32 v[32:33], v[18:19], v[94:95], v[32:33] op_sel:[0,1,0] op_sel_hi:[1,1,1]
	v_pk_fma_f32 v[34:35], v[64:65], v[94:95], v[34:35] op_sel:[0,1,0] op_sel_hi:[1,1,1]
	v_cvt_scalef32_pk_f32_fp4 v[62:63], v155, 1.0
	v_cvt_scalef32_pk_f32_fp4 v[60:61], v155, 1.0 op_sel:[1,0,0]
	v_cvt_scalef32_pk_f32_fp4 v[18:19], v155, 1.0 op_sel:[0,1,0]
	v_cvt_scalef32_pk_f32_fp4 v[64:65], v155, 1.0 op_sel:[1,1,0]
	v_pk_fma_f32 v[36:37], v[54:55], v[94:95], v[36:37] op_sel:[0,1,0] op_sel_hi:[1,1,1]
	v_pk_fma_f32 v[38:39], v[52:53], v[94:95], v[38:39] op_sel:[0,1,0] op_sel_hi:[1,1,1]
	v_pk_fma_f32 v[40:41], v[58:59], v[94:95], v[40:41] op_sel:[0,1,0] op_sel_hi:[1,1,1]
	v_pk_fma_f32 v[42:43], v[56:57], v[94:95], v[42:43] op_sel:[0,1,0] op_sel_hi:[1,1,1]
	v_pk_fma_f32 v[44:45], v[62:63], v[94:95], v[44:45] op_sel:[0,1,0] op_sel_hi:[1,1,1]
	v_pk_fma_f32 v[46:47], v[60:61], v[94:95], v[46:47] op_sel:[0,1,0] op_sel_hi:[1,1,1]
	v_pk_fma_f32 v[48:49], v[18:19], v[94:95], v[48:49] op_sel:[0,1,0] op_sel_hi:[1,1,1]
	v_pk_fma_f32 v[50:51], v[64:65], v[94:95], v[50:51] op_sel:[0,1,0] op_sel_hi:[1,1,1]
	global_load_dwordx4 v[152:155], v7, s[40:41]
	s_waitcnt vmcnt(15)
	v_cvt_scalef32_pk_f32_fp4 v[54:55], v156, 1.0
	v_cvt_scalef32_pk_f32_fp4 v[52:53], v156, 1.0 op_sel:[1,0,0]
	v_cvt_scalef32_pk_f32_fp4 v[58:59], v156, 1.0 op_sel:[0,1,0]
	v_cvt_scalef32_pk_f32_fp4 v[56:57], v156, 1.0 op_sel:[1,1,0]
	v_cvt_scalef32_pk_f32_fp4 v[62:63], v157, 1.0
	v_cvt_scalef32_pk_f32_fp4 v[60:61], v157, 1.0 op_sel:[1,0,0]
	v_cvt_scalef32_pk_f32_fp4 v[18:19], v157, 1.0 op_sel:[0,1,0]
	v_cvt_scalef32_pk_f32_fp4 v[64:65], v157, 1.0 op_sel:[1,1,0]
	v_pk_fma_f32 v[20:21], v[54:55], v[96:97], v[20:21] op_sel_hi:[1,0,1]
	v_pk_fma_f32 v[22:23], v[52:53], v[96:97], v[22:23] op_sel_hi:[1,0,1]
	v_pk_fma_f32 v[24:25], v[58:59], v[96:97], v[24:25] op_sel_hi:[1,0,1]
	v_pk_fma_f32 v[26:27], v[56:57], v[96:97], v[26:27] op_sel_hi:[1,0,1]
	v_cvt_scalef32_pk_f32_fp4 v[54:55], v158, 1.0
	v_cvt_scalef32_pk_f32_fp4 v[52:53], v158, 1.0 op_sel:[1,0,0]
	v_cvt_scalef32_pk_f32_fp4 v[58:59], v158, 1.0 op_sel:[0,1,0]
	v_cvt_scalef32_pk_f32_fp4 v[56:57], v158, 1.0 op_sel:[1,1,0]
	v_pk_fma_f32 v[28:29], v[62:63], v[96:97], v[28:29] op_sel_hi:[1,0,1]
	v_pk_fma_f32 v[30:31], v[60:61], v[96:97], v[30:31] op_sel_hi:[1,0,1]
	v_pk_fma_f32 v[32:33], v[18:19], v[96:97], v[32:33] op_sel_hi:[1,0,1]
	v_pk_fma_f32 v[34:35], v[64:65], v[96:97], v[34:35] op_sel_hi:[1,0,1]
	v_cvt_scalef32_pk_f32_fp4 v[62:63], v159, 1.0
	v_cvt_scalef32_pk_f32_fp4 v[60:61], v159, 1.0 op_sel:[1,0,0]
	v_cvt_scalef32_pk_f32_fp4 v[18:19], v159, 1.0 op_sel:[0,1,0]
	v_cvt_scalef32_pk_f32_fp4 v[64:65], v159, 1.0 op_sel:[1,1,0]
	v_pk_fma_f32 v[36:37], v[54:55], v[96:97], v[36:37] op_sel_hi:[1,0,1]
	v_pk_fma_f32 v[38:39], v[52:53], v[96:97], v[38:39] op_sel_hi:[1,0,1]
	v_pk_fma_f32 v[40:41], v[58:59], v[96:97], v[40:41] op_sel_hi:[1,0,1]
	v_pk_fma_f32 v[42:43], v[56:57], v[96:97], v[42:43] op_sel_hi:[1,0,1]
	v_pk_fma_f32 v[44:45], v[62:63], v[96:97], v[44:45] op_sel_hi:[1,0,1]
	v_pk_fma_f32 v[46:47], v[60:61], v[96:97], v[46:47] op_sel_hi:[1,0,1]
	v_pk_fma_f32 v[48:49], v[18:19], v[96:97], v[48:49] op_sel_hi:[1,0,1]
	v_pk_fma_f32 v[50:51], v[64:65], v[96:97], v[50:51] op_sel_hi:[1,0,1]
	global_load_dwordx4 v[156:159], v8, s[40:41]
	s_waitcnt vmcnt(15)
	v_cvt_scalef32_pk_f32_fp4 v[54:55], v160, 1.0
	v_cvt_scalef32_pk_f32_fp4 v[52:53], v160, 1.0 op_sel:[1,0,0]
	v_cvt_scalef32_pk_f32_fp4 v[58:59], v160, 1.0 op_sel:[0,1,0]
	v_cvt_scalef32_pk_f32_fp4 v[56:57], v160, 1.0 op_sel:[1,1,0]
	v_cvt_scalef32_pk_f32_fp4 v[62:63], v161, 1.0
	v_cvt_scalef32_pk_f32_fp4 v[60:61], v161, 1.0 op_sel:[1,0,0]
	v_cvt_scalef32_pk_f32_fp4 v[18:19], v161, 1.0 op_sel:[0,1,0]
	v_cvt_scalef32_pk_f32_fp4 v[64:65], v161, 1.0 op_sel:[1,1,0]
	v_pk_fma_f32 v[20:21], v[54:55], v[96:97], v[20:21] op_sel:[0,1,0] op_sel_hi:[1,1,1]
	v_pk_fma_f32 v[22:23], v[52:53], v[96:97], v[22:23] op_sel:[0,1,0] op_sel_hi:[1,1,1]
	v_pk_fma_f32 v[24:25], v[58:59], v[96:97], v[24:25] op_sel:[0,1,0] op_sel_hi:[1,1,1]
	v_pk_fma_f32 v[26:27], v[56:57], v[96:97], v[26:27] op_sel:[0,1,0] op_sel_hi:[1,1,1]
	v_cvt_scalef32_pk_f32_fp4 v[54:55], v162, 1.0
	v_cvt_scalef32_pk_f32_fp4 v[52:53], v162, 1.0 op_sel:[1,0,0]
	v_cvt_scalef32_pk_f32_fp4 v[58:59], v162, 1.0 op_sel:[0,1,0]
	v_cvt_scalef32_pk_f32_fp4 v[56:57], v162, 1.0 op_sel:[1,1,0]
	v_pk_fma_f32 v[28:29], v[62:63], v[96:97], v[28:29] op_sel:[0,1,0] op_sel_hi:[1,1,1]
	v_pk_fma_f32 v[30:31], v[60:61], v[96:97], v[30:31] op_sel:[0,1,0] op_sel_hi:[1,1,1]
	v_pk_fma_f32 v[32:33], v[18:19], v[96:97], v[32:33] op_sel:[0,1,0] op_sel_hi:[1,1,1]
	v_pk_fma_f32 v[34:35], v[64:65], v[96:97], v[34:35] op_sel:[0,1,0] op_sel_hi:[1,1,1]
	v_cvt_scalef32_pk_f32_fp4 v[62:63], v163, 1.0
	v_cvt_scalef32_pk_f32_fp4 v[60:61], v163, 1.0 op_sel:[1,0,0]
	v_cvt_scalef32_pk_f32_fp4 v[18:19], v163, 1.0 op_sel:[0,1,0]
	v_cvt_scalef32_pk_f32_fp4 v[64:65], v163, 1.0 op_sel:[1,1,0]
	v_pk_fma_f32 v[36:37], v[54:55], v[96:97], v[36:37] op_sel:[0,1,0] op_sel_hi:[1,1,1]
	v_pk_fma_f32 v[38:39], v[52:53], v[96:97], v[38:39] op_sel:[0,1,0] op_sel_hi:[1,1,1]
	v_pk_fma_f32 v[40:41], v[58:59], v[96:97], v[40:41] op_sel:[0,1,0] op_sel_hi:[1,1,1]
	v_pk_fma_f32 v[42:43], v[56:57], v[96:97], v[42:43] op_sel:[0,1,0] op_sel_hi:[1,1,1]
	v_pk_fma_f32 v[44:45], v[62:63], v[96:97], v[44:45] op_sel:[0,1,0] op_sel_hi:[1,1,1]
	v_pk_fma_f32 v[46:47], v[60:61], v[96:97], v[46:47] op_sel:[0,1,0] op_sel_hi:[1,1,1]
	v_pk_fma_f32 v[48:49], v[18:19], v[96:97], v[48:49] op_sel:[0,1,0] op_sel_hi:[1,1,1]
	v_pk_fma_f32 v[50:51], v[64:65], v[96:97], v[50:51] op_sel:[0,1,0] op_sel_hi:[1,1,1]
	global_load_dwordx4 v[160:163], v9, s[40:41]
	s_add_i32 s14, s14, 1
	s_cmp_lt_u32 s14, 8
	s_cbranch_scc1 .Lg4_v_gp
	s_lshl_b32 s100, s13, 7
	v_add_u32_e32 v1, s100, v174
	v_add_u32_e32 v10, 0x1000, v1
	global_store_dwordx4 v1, v[20:23], s[42:43] offset:0
	global_store_dwordx4 v1, v[24:27], s[42:43] offset:1024
	global_store_dwordx4 v1, v[28:31], s[42:43] offset:2048
	global_store_dwordx4 v1, v[32:35], s[42:43] offset:3072
	global_store_dwordx4 v10, v[36:39], s[42:43] offset:0
	global_store_dwordx4 v10, v[40:43], s[42:43] offset:1024
	global_store_dwordx4 v10, v[44:47], s[42:43] offset:2048
	global_store_dwordx4 v10, v[48:51], s[42:43] offset:3072
	s_add_i32 s13, s13, 1
	s_cmp_lt_u32 s13, 8
	s_cbranch_scc1 .Lg4_v_slice
	s_waitcnt vmcnt(0) lgkmcnt(0)
	s_branch .LBB0_927

.LBB0_927:
	s_ashr_i32 s17, s16, 31
	s_lshl_b64 s[14:15], s[16:17], 4
	s_add_u32 s14, s11, s14
	s_addc_u32 s15, s12, s15
	v_mov_b64_e32 v[2:3], s[14:15]
	flat_load_dwordx4 v[2:5], v[2:3]
	s_lshl_b64 s[14:15], s[16:17], 9
	v_lshl_or_b32 v12, v66, 2, s14
	v_mov_b32_e32 v13, s15
	v_mov_b32_e32 v8, v66
	v_lshl_add_u64 v[10:11], s[18:19], 0, v[12:13]
	v_or_b32_e32 v14, 0x100, v12
	v_mov_b32_e32 v15, s15
	v_lshl_add_u64 v[10:11], s[18:19], 0, v[14:15]
	v_ashrrev_i32_e32 v9, 31, v8
	v_readlane_b32 s4, v254, 61
	v_lshlrev_b64 v[16:17], 4, v[8:9]
	v_readlane_b32 s5, v254, 62
	v_lshl_add_u64 v[42:43], s[50:51], 0, v[16:17]
	s_lshl_b64 s[44:45], s[16:17], 12
	v_lshl_add_u64 v[40:41], s[4:5], 0, v[16:17]
	v_add_co_u32_e32 v60, vcc, s8, v40
	v_lshl_add_u64 v[78:79], v[72:73], 0, s[44:45]
	s_nop 0
	v_addc_co_u32_e32 v61, vcc, 0, v41, vcc
	v_add_co_u32_e32 v84, vcc, s8, v42
	v_lshl_add_u64 v[12:13], s[20:21], 0, v[12:13]
	v_lshl_add_u64 v[14:15], s[20:21], 0, v[14:15]
	v_addc_co_u32_e32 v85, vcc, 0, v43, vcc
	s_waitcnt lgkmcnt(0)
	global_load_dwordx2 v[6:7], v[78:79], off
	global_load_dwordx4 v[8:11], v[40:41], off
	global_load_dwordx2 v[64:65], v[78:79], off offset:512
	global_load_dwordx2 v[92:93], v[78:79], off offset:1024
	global_load_dwordx2 v[96:97], v[78:79], off offset:1536
	global_load_dwordx2 v[100:101], v[78:79], off offset:2048
	global_load_dwordx2 v[104:105], v[78:79], off offset:2560
	global_load_dwordx2 v[118:119], v[78:79], off offset:3072
	global_load_dwordx2 v[120:121], v[78:79], off offset:3584
	s_nop 0
	global_load_dwordx4 v[12:15], v[40:41], off offset:1024
	global_load_dwordx4 v[16:19], v[42:43], off
	global_load_dwordx4 v[20:23], v[42:43], off offset:1024
	global_load_dwordx4 v[24:27], v[40:41], off offset:2048
	global_load_dwordx4 v[28:31], v[40:41], off offset:3072
	global_load_dwordx4 v[32:35], v[42:43], off offset:2048
	global_load_dwordx4 v[36:39], v[42:43], off offset:3072
	s_nop 0
	global_load_dwordx4 v[40:43], v[60:61], off
	global_load_dwordx4 v[44:47], v[60:61], off offset:1024
	global_load_dwordx4 v[48:51], v[84:85], off
	global_load_dwordx4 v[52:55], v[84:85], off offset:1024
	global_load_dwordx4 v[56:59], v[60:61], off offset:2048
	s_nop 0
	global_load_dwordx4 v[60:63], v[60:61], off offset:3072
	s_nop 0
	global_load_dwordx4 v[110:113], v[84:85], off offset:2048
	global_load_dwordx4 v[114:117], v[84:85], off offset:3072
	s_mov_b32 s4, 0x3a000000
	v_mov_b32_e32 v108, 0
	s_mov_b32 s13, 0
	v_mov_b32_e32 v125, v108
	v_mov_b32_e32 v126, v108
	v_mov_b32_e32 v127, v108
	v_mov_b32_e32 v128, v108
	v_mov_b32_e32 v129, v108
	v_mov_b32_e32 v130, v108
	v_mov_b32_e32 v131, v108
	v_mov_b32_e32 v132, v108
	v_mov_b32_e32 v133, v108
	v_mov_b32_e32 v134, v108
	v_mov_b32_e32 v135, v108
	v_mov_b32_e32 v136, v108
	v_mov_b32_e32 v137, v108
	v_mov_b32_e32 v138, v108
	v_mov_b32_e32 v139, v108
	v_mov_b32_e32 v140, v108
	v_mov_b32_e32 v141, v108
	v_mov_b32_e32 v142, v108
	v_mov_b32_e32 v143, v108
	v_mov_b32_e32 v144, v108
	v_mov_b32_e32 v145, v108
	v_mov_b32_e32 v146, v108
	v_mov_b32_e32 v147, v108
	s_waitcnt vmcnt(0)
	v_cvt_f64_i32_e32 v[84:85], v3
	v_cvt_f64_u32_e32 v[2:3], v2
	v_ldexp_f64 v[84:85], v[84:85], 32
	v_cvt_f64_i32_e32 v[86:87], v5
	v_add_f64 v[2:3], v[84:85], v[2:3]
	v_cvt_f64_u32_e32 v[4:5], v4
	v_ldexp_f64 v[86:87], v[86:87], 32
	v_ldexp_f64 v[2:3], v[2:3], s33
	v_add_f64 v[4:5], v[86:87], v[4:5]
	v_cvt_f32_f64_e32 v2, v[2:3]
	v_ldexp_f64 v[4:5], v[4:5], s33
	v_mul_f32_e32 v2, 0x3a000000, v2
	v_cvt_f32_f64_e32 v3, v[4:5]
	v_mul_f32_e32 v4, v2, v2
	v_fma_f32 v3, v3, s4, -v4
	v_add_f32_e32 v3, 0x3727c5ac, v3
	v_mul_f32_e32 v4, 0x4f800000, v3
	v_cmp_gt_f32_e32 vcc, s6, v3
	v_ashrrev_i32_e32 v81, 31, v80
	v_lshlrev_b64 v[84:85], 2, v[80:81]
	v_cndmask_b32_e32 v3, v3, v4, vcc
	v_sqrt_f32_e32 v81, v3
	v_ashrrev_i32_e32 v83, 31, v82
	v_lshlrev_b64 v[90:91], 2, v[82:83]
	v_lshl_add_u64 v[86:87], s[54:55], 0, v[84:85]
	v_add_u32_e32 v83, -1, v81
	v_add_u32_e32 v94, 1, v81
	v_fma_f32 v95, -v83, v81, v3
	v_fma_f32 v98, -v94, v81, v3
	v_cmp_ge_f32_e64 s[42:43], 0, v95
	v_lshl_add_u64 v[4:5], s[52:53], 0, v[84:85]
	v_lshl_add_u64 v[84:85], s[54:55], 0, v[90:91]
	v_cndmask_b32_e64 v81, v81, v83, s[42:43]
	v_cmp_lt_f32_e64 s[42:43], 0, v98
	v_lshl_add_u64 v[90:91], s[52:53], 0, v[90:91]
	v_lshlrev_b32_e32 v88, 16, v6
	v_cndmask_b32_e64 v81, v81, v94, s[42:43]
	v_mul_f32_e32 v83, 0x37800000, v81
	v_cndmask_b32_e32 v81, v81, v83, vcc
	v_cmp_class_f32_e32 vcc, v3, v229
	v_and_b32_e32 v89, 0xffff0000, v6
	v_lshlrev_b32_e32 v6, 16, v7
	v_cndmask_b32_e32 v3, v81, v3, vcc
	v_div_scale_f32 v81, s[14:15], v3, v3, 1.0
	v_rcp_f32_e32 v83, v81
	v_div_scale_f32 v94, vcc, 1.0, v3, 1.0
	v_and_b32_e32 v7, 0xffff0000, v7
	v_fma_f32 v95, -v81, v83, 1.0
	v_fmac_f32_e32 v83, v95, v83
	v_mul_f32_e32 v95, v94, v83
	v_fma_f32 v98, -v81, v95, v94
	v_fmac_f32_e32 v95, v98, v83
	v_fma_f32 v81, -v81, v95, v94
	v_div_fmas_f32 v81, v81, v83, v95
	v_div_fixup_f32 v122, v81, v3, 1.0
	v_xor_b32_e32 v11, 0x80000000, v11
	v_xor_b32_e32 v10, 0x80000000, v10
	v_pk_fma_f32 v[4:5], v[10:11], v[2:3], v[6:7] op_sel_hi:[1,0,1]
	v_pk_fma_f32 v[6:7], v[8:9], v[2:3], v[88:89] op_sel_hi:[1,0,1] neg_lo:[1,0,0] neg_hi:[1,0,0]
	s_mov_b32 s14, 0
	s_waitcnt vmcnt(0) lgkmcnt(0)
	v_pk_fma_f32 v[86:87], v[122:123], v[4:5], v[18:19] op_sel_hi:[0,1,1]
	v_pk_fma_f32 v[84:85], v[122:123], v[6:7], v[16:17] op_sel_hi:[0,1,1]
	v_lshlrev_b32_e32 v4, 16, v64
	v_and_b32_e32 v5, 0xffff0000, v64
	v_lshlrev_b32_e32 v6, 16, v65
	v_and_b32_e32 v7, 0xffff0000, v65
	v_pk_fma_f32 v[6:7], v[2:3], v[14:15], v[6:7] op_sel_hi:[0,1,1] neg_lo:[1,0,0] neg_hi:[1,0,0]
	v_pk_fma_f32 v[4:5], v[2:3], v[12:13], v[4:5] op_sel_hi:[0,1,1] neg_lo:[1,0,0] neg_hi:[1,0,0]
	v_pk_fma_f32 v[90:91], v[122:123], v[6:7], v[22:23] op_sel_hi:[0,1,1]
	v_pk_fma_f32 v[88:89], v[122:123], v[4:5], v[20:21] op_sel_hi:[0,1,1]
	v_lshlrev_b32_e32 v4, 16, v92
	v_and_b32_e32 v5, 0xffff0000, v92
	v_lshlrev_b32_e32 v6, 16, v93
	v_and_b32_e32 v7, 0xffff0000, v93
	v_pk_fma_f32 v[6:7], v[2:3], v[26:27], v[6:7] op_sel_hi:[0,1,1] neg_lo:[1,0,0] neg_hi:[1,0,0]
	v_pk_fma_f32 v[4:5], v[2:3], v[24:25], v[4:5] op_sel_hi:[0,1,1] neg_lo:[1,0,0] neg_hi:[1,0,0]
	v_pk_fma_f32 v[94:95], v[122:123], v[6:7], v[34:35] op_sel_hi:[0,1,1]
	v_pk_fma_f32 v[92:93], v[122:123], v[4:5], v[32:33] op_sel_hi:[0,1,1]
	v_lshlrev_b32_e32 v4, 16, v96
	v_and_b32_e32 v5, 0xffff0000, v96
	v_lshlrev_b32_e32 v6, 16, v97
	v_and_b32_e32 v7, 0xffff0000, v97
	v_pk_fma_f32 v[6:7], v[2:3], v[30:31], v[6:7] op_sel_hi:[0,1,1] neg_lo:[1,0,0] neg_hi:[1,0,0]
	v_pk_fma_f32 v[4:5], v[2:3], v[28:29], v[4:5] op_sel_hi:[0,1,1] neg_lo:[1,0,0] neg_hi:[1,0,0]
	v_pk_fma_f32 v[98:99], v[122:123], v[6:7], v[38:39] op_sel_hi:[0,1,1]
	v_pk_fma_f32 v[96:97], v[122:123], v[4:5], v[36:37] op_sel_hi:[0,1,1]
	v_lshlrev_b32_e32 v4, 16, v100
	v_and_b32_e32 v5, 0xffff0000, v100
	v_lshlrev_b32_e32 v6, 16, v101
	v_and_b32_e32 v7, 0xffff0000, v101
	v_pk_fma_f32 v[4:5], v[2:3], v[40:41], v[4:5] op_sel_hi:[0,1,1] neg_lo:[1,0,0] neg_hi:[1,0,0]
	v_pk_fma_f32 v[6:7], v[2:3], v[42:43], v[6:7] op_sel_hi:[0,1,1] neg_lo:[1,0,0] neg_hi:[1,0,0]
	v_pk_fma_f32 v[102:103], v[122:123], v[6:7], v[50:51] op_sel_hi:[0,1,1]
	v_pk_fma_f32 v[100:101], v[122:123], v[4:5], v[48:49] op_sel_hi:[0,1,1]
	v_lshlrev_b32_e32 v4, 16, v104
	v_and_b32_e32 v5, 0xffff0000, v104
	v_lshlrev_b32_e32 v6, 16, v105
	v_and_b32_e32 v7, 0xffff0000, v105
	v_pk_fma_f32 v[4:5], v[2:3], v[44:45], v[4:5] op_sel_hi:[0,1,1] neg_lo:[1,0,0] neg_hi:[1,0,0]
	v_pk_fma_f32 v[6:7], v[2:3], v[46:47], v[6:7] op_sel_hi:[0,1,1] neg_lo:[1,0,0] neg_hi:[1,0,0]
	v_pk_fma_f32 v[106:107], v[122:123], v[6:7], v[54:55] op_sel_hi:[0,1,1]
	v_pk_fma_f32 v[104:105], v[122:123], v[4:5], v[52:53] op_sel_hi:[0,1,1]
	v_lshlrev_b32_e32 v4, 16, v118
	v_and_b32_e32 v5, 0xffff0000, v118
	v_lshlrev_b32_e32 v6, 16, v119
	v_and_b32_e32 v7, 0xffff0000, v119
	v_pk_fma_f32 v[4:5], v[2:3], v[56:57], v[4:5] op_sel_hi:[0,1,1] neg_lo:[1,0,0] neg_hi:[1,0,0]
	v_pk_fma_f32 v[6:7], v[2:3], v[58:59], v[6:7] op_sel_hi:[0,1,1] neg_lo:[1,0,0] neg_hi:[1,0,0]
	v_pk_fma_f32 v[112:113], v[122:123], v[6:7], v[112:113] op_sel_hi:[0,1,1]
	v_pk_fma_f32 v[110:111], v[122:123], v[4:5], v[110:111] op_sel_hi:[0,1,1]
	v_lshlrev_b32_e32 v4, 16, v120
	v_and_b32_e32 v5, 0xffff0000, v120
	v_lshlrev_b32_e32 v6, 16, v121
	v_and_b32_e32 v7, 0xffff0000, v121
	v_pk_fma_f32 v[4:5], v[2:3], v[60:61], v[4:5] op_sel_hi:[0,1,1] neg_lo:[1,0,0] neg_hi:[1,0,0]
	v_pk_fma_f32 v[2:3], v[2:3], v[62:63], v[6:7] op_sel_hi:[0,1,1] neg_lo:[1,0,0] neg_hi:[1,0,0]
	v_pk_fma_f32 v[116:117], v[122:123], v[2:3], v[116:117] op_sel_hi:[0,1,1]
	v_and_b32_e32 v2, 64, v230
	v_mul_f32_e32 v164, v1, v123
	v_xor_b32_e32 v1, 32, v230
	v_add_u32_e32 v3, 64, v2
	v_cmp_lt_i32_e32 vcc, v1, v3
	v_pk_fma_f32 v[114:115], v[122:123], v[4:5], v[114:115] op_sel_hi:[0,1,1]
	v_cvt_pk_bf16_f32 v148, v84, v85
	v_cndmask_b32_e32 v1, v230, v1, vcc
	v_lshlrev_b32_e32 v166, 2, v1
	v_xor_b32_e32 v1, 16, v230
	v_cmp_lt_i32_e32 vcc, v1, v3
	v_cvt_pk_bf16_f32 v149, v86, v87
	v_cvt_pk_bf16_f32 v150, v88, v89
	v_cndmask_b32_e32 v1, v230, v1, vcc
	v_lshlrev_b32_e32 v167, 2, v1
	v_xor_b32_e32 v1, 8, v230
	v_cmp_lt_i32_e32 vcc, v1, v3
	v_cvt_pk_bf16_f32 v151, v90, v91
	v_cvt_pk_bf16_f32 v152, v92, v93
	v_cndmask_b32_e32 v1, v230, v1, vcc
	v_lshlrev_b32_e32 v168, 2, v1
	v_xor_b32_e32 v1, 4, v230
	v_cmp_lt_i32_e32 vcc, v1, v3
	v_cvt_pk_bf16_f32 v153, v94, v95
	v_cvt_pk_bf16_f32 v154, v96, v97
	v_cndmask_b32_e32 v1, v230, v1, vcc
	v_lshlrev_b32_e32 v169, 2, v1
	v_xor_b32_e32 v1, 2, v230
	v_cmp_lt_i32_e32 vcc, v1, v3
	v_cvt_pk_bf16_f32 v155, v98, v99
	v_cvt_pk_bf16_f32 v156, v100, v101
	v_cndmask_b32_e32 v1, v230, v1, vcc
	v_lshlrev_b32_e32 v170, 2, v1
	v_xor_b32_e32 v1, 1, v230
	v_cmp_lt_i32_e32 vcc, v1, v3
	v_cvt_pk_bf16_f32 v157, v102, v103
	v_cvt_pk_bf16_f32 v158, v104, v105
	v_cndmask_b32_e32 v1, v230, v1, vcc
	v_cvt_pk_bf16_f32 v159, v106, v107
	v_cvt_pk_bf16_f32 v160, v110, v111
	v_cvt_pk_bf16_f32 v161, v112, v113
	v_cvt_pk_bf16_f32 v162, v114, v115
	v_cvt_pk_bf16_f32 v163, v116, v117
	v_mul_f32_e32 v165, v109, v124
	v_lshlrev_b32_e32 v171, 2, v1
	v_or_b32_e32 v172, v2, v67
	s_lshl_b64 s[100:101], s[16:17], 13
	s_add_u32 s100, s100, s78
	s_addc_u32 s101, s101, s79
	s_add_u32 s100, s100, 0x2da00000
	s_addc_u32 s101, s101, 0
	v_lshlrev_b32_e32 v1, 4, v66
	v_add_u32_e32 v2, 0x1000, v1
	global_load_dwordx2 v[108:109], v1, s[100:101]
	global_load_dwordx2 v[118:119], v1, s[100:101] offset:8
	global_load_dwordx4 v[120:123], v1, s[100:101] offset:1024
	global_load_dwordx4 v[124:127], v1, s[100:101] offset:2048
	global_load_dwordx4 v[128:131], v1, s[100:101] offset:3072
	global_load_dwordx4 v[132:135], v2, s[100:101] offset:0
	global_load_dwordx4 v[136:139], v2, s[100:101] offset:1024
	global_load_dwordx4 v[140:143], v2, s[100:101] offset:2048
	global_load_dwordx4 v[144:147], v2, s[100:101] offset:3072
	s_waitcnt vmcnt(0)
	v_pk_fma_f32 v[38:39], v[84:85], s[94:95], v[108:109] op_sel_hi:[1,0,1]
	v_pk_fma_f32 v[36:37], v[86:87], s[94:95], v[118:119] op_sel_hi:[1,0,1]
	v_add_f32_e32 v49, v38, v39
	v_pk_fma_f32 v[34:35], v[88:89], s[94:95], v[120:121] op_sel_hi:[1,0,1]
	v_add_f32_e32 v48, v36, v37
	v_add_f32_e32 v49, 0, v49
	v_pk_fma_f32 v[32:33], v[90:91], s[94:95], v[122:123] op_sel_hi:[1,0,1]
	v_add_f32_e32 v47, v34, v35
	v_add_f32_e32 v48, v48, v49
	v_pk_fma_f32 v[30:31], v[92:93], s[94:95], v[124:125] op_sel_hi:[1,0,1]
	v_add_f32_e32 v46, v32, v33
	v_add_f32_e32 v47, v47, v48
	v_pk_fma_f32 v[28:29], v[94:95], s[94:95], v[126:127] op_sel_hi:[1,0,1]
	v_add_f32_e32 v45, v30, v31
	v_add_f32_e32 v46, v46, v47
	v_pk_fma_f32 v[26:27], v[96:97], s[94:95], v[128:129] op_sel_hi:[1,0,1]
	v_add_f32_e32 v44, v28, v29
	v_add_f32_e32 v45, v45, v46
	v_pk_fma_f32 v[4:5], v[116:117], s[94:95], v[146:147] op_sel_hi:[1,0,1]
	v_pk_fma_f32 v[6:7], v[114:115], s[94:95], v[144:145] op_sel_hi:[1,0,1]
	v_pk_fma_f32 v[24:25], v[98:99], s[94:95], v[130:131] op_sel_hi:[1,0,1]
	v_add_f32_e32 v43, v26, v27
	v_add_f32_e32 v44, v44, v45
	v_mov_b32_e32 v8, v4
	v_mov_b32_e32 v9, v6
	v_mov_b32_e32 v10, v5
	v_mov_b32_e32 v11, v7
	v_pk_fma_f32 v[22:23], v[100:101], s[94:95], v[132:133] op_sel_hi:[1,0,1]
	v_add_f32_e32 v42, v24, v25
	v_add_f32_e32 v43, v43, v44
	v_pk_add_f32 v[8:9], v[8:9], v[10:11]
	v_pk_fma_f32 v[10:11], v[112:113], s[94:95], v[142:143] op_sel_hi:[1,0,1]
	v_pk_fma_f32 v[12:13], v[110:111], s[94:95], v[140:141] op_sel_hi:[1,0,1]
	v_pk_fma_f32 v[20:21], v[102:103], s[94:95], v[134:135] op_sel_hi:[1,0,1]
	v_add_f32_e32 v41, v22, v23
	v_add_f32_e32 v42, v42, v43
	v_mov_b32_e32 v14, v10
	v_mov_b32_e32 v15, v12
	v_mov_b32_e32 v16, v11
	v_mov_b32_e32 v17, v13
	v_pk_fma_f32 v[18:19], v[104:105], s[94:95], v[136:137] op_sel_hi:[1,0,1]
	v_add_f32_e32 v40, v20, v21
	v_add_f32_e32 v41, v41, v42
	v_pk_add_f32 v[14:15], v[14:15], v[16:17]
	v_pk_fma_f32 v[16:17], v[106:107], s[94:95], v[138:139] op_sel_hi:[1,0,1]
	v_add_f32_e32 v3, v18, v19
	v_add_f32_e32 v40, v40, v41
	v_add_f32_e32 v1, v16, v17
	v_add_f32_e32 v3, v3, v40
	v_add_f32_e32 v1, v1, v3
	v_add_f32_e32 v1, v15, v1
	v_add_f32_e32 v1, v14, v1
	v_add_f32_e32 v1, v9, v1
	v_add_f32_e32 v1, v8, v1
	v_mov_b32_e32 v3, v187
	v_mov_b32_e32 v2, v66
	v_add_f32_dpp v1, v1, v1 quad_perm:[1,0,3,2] row_mask:0xf bank_mask:0xf bound_ctrl:1
	s_cmp_lt_i32 s96, 3
	s_nop 0
	v_add_f32_dpp v1, v1, v1 quad_perm:[2,3,0,1] row_mask:0xf bank_mask:0xf bound_ctrl:1
	s_nop 1
	v_add_f32_dpp v1, v1, v1 row_half_mirror row_mask:0xf bank_mask:0xf bound_ctrl:1
	s_nop 1
	v_add_f32_dpp v1, v1, v1 row_mirror row_mask:0xf bank_mask:0xf bound_ctrl:1
	s_nop 1
	v_mov_b32_dpp v3, v1 row_bcast:15 row_mask:0xa bank_mask:0xf
	v_add_f32_e32 v1, v1, v3
	v_mov_b32_e32 v3, v187
	s_nop 1
	v_mov_b32_dpp v3, v1 row_bcast:31 row_mask:0xc bank_mask:0xf
	v_add_f32_e32 v1, v1, v3
	v_mov_b32_e32 v3, v187
	v_readlane_b32 s13, v1, 63
	s_nop 1
	v_mul_f32_e32 v8, s13, v0
	v_pk_add_f32 v[114:115], v[38:39], v[8:9] op_sel_hi:[1,0] neg_lo:[0,1] neg_hi:[0,1]
	v_pk_add_f32 v[116:117], v[36:37], v[8:9] op_sel_hi:[1,0] neg_lo:[0,1] neg_hi:[0,1]
	v_pk_mul_f32 v[14:15], v[114:115], v[114:115]
	v_pk_mul_f32 v[36:37], v[116:117], v[116:117]
	v_add_f32_e32 v1, v14, v15
	v_pk_add_f32 v[110:111], v[34:35], v[8:9] op_sel_hi:[1,0] neg_lo:[0,1] neg_hi:[0,1]
	v_add_f32_e32 v1, v36, v1
	v_pk_mul_f32 v[34:35], v[110:111], v[110:111]
	v_add_f32_e32 v1, v37, v1
	v_pk_add_f32 v[112:113], v[32:33], v[8:9] op_sel_hi:[1,0] neg_lo:[0,1] neg_hi:[0,1]
	v_add_f32_e32 v1, v34, v1
	v_pk_mul_f32 v[32:33], v[112:113], v[112:113]
	v_add_f32_e32 v1, v35, v1
	v_pk_add_f32 v[106:107], v[30:31], v[8:9] op_sel_hi:[1,0] neg_lo:[0,1] neg_hi:[0,1]
	v_add_f32_e32 v1, v32, v1
	v_pk_mul_f32 v[30:31], v[106:107], v[106:107]
	v_add_f32_e32 v1, v33, v1
	v_pk_add_f32 v[108:109], v[28:29], v[8:9] op_sel_hi:[1,0] neg_lo:[0,1] neg_hi:[0,1]
	v_add_f32_e32 v1, v30, v1
	v_pk_mul_f32 v[28:29], v[108:109], v[108:109]
	v_add_f32_e32 v1, v31, v1
	v_pk_add_f32 v[102:103], v[26:27], v[8:9] op_sel_hi:[1,0] neg_lo:[0,1] neg_hi:[0,1]
	v_add_f32_e32 v1, v28, v1
	v_pk_mul_f32 v[26:27], v[102:103], v[102:103]
	v_add_f32_e32 v1, v29, v1
	v_pk_add_f32 v[104:105], v[24:25], v[8:9] op_sel_hi:[1,0] neg_lo:[0,1] neg_hi:[0,1]
	v_add_f32_e32 v1, v26, v1
	v_pk_mul_f32 v[24:25], v[104:105], v[104:105]
	v_add_f32_e32 v1, v27, v1
	v_pk_add_f32 v[98:99], v[22:23], v[8:9] op_sel_hi:[1,0] neg_lo:[0,1] neg_hi:[0,1]
	v_add_f32_e32 v1, v24, v1
	v_pk_mul_f32 v[22:23], v[98:99], v[98:99]
	v_add_f32_e32 v1, v25, v1
	v_pk_add_f32 v[100:101], v[20:21], v[8:9] op_sel_hi:[1,0] neg_lo:[0,1] neg_hi:[0,1]
	v_add_f32_e32 v1, v22, v1
	v_pk_mul_f32 v[20:21], v[100:101], v[100:101]
	v_add_f32_e32 v1, v23, v1
	v_pk_add_f32 v[94:95], v[18:19], v[8:9] op_sel_hi:[1,0] neg_lo:[0,1] neg_hi:[0,1]
	v_add_f32_e32 v1, v20, v1
	v_pk_mul_f32 v[18:19], v[94:95], v[94:95]
	v_add_f32_e32 v1, v21, v1
	v_pk_add_f32 v[96:97], v[16:17], v[8:9] op_sel_hi:[1,0] neg_lo:[0,1] neg_hi:[0,1]
	v_add_f32_e32 v1, v18, v1
	v_pk_mul_f32 v[16:17], v[96:97], v[96:97]
	v_add_f32_e32 v1, v19, v1
	v_pk_add_f32 v[86:87], v[12:13], v[8:9] op_sel_hi:[1,0] neg_lo:[0,1] neg_hi:[0,1]
	v_add_f32_e32 v1, v16, v1
	v_pk_mul_f32 v[12:13], v[86:87], v[86:87]
	v_add_f32_e32 v1, v17, v1
	v_pk_add_f32 v[88:89], v[10:11], v[8:9] op_sel_hi:[1,0] neg_lo:[0,1] neg_hi:[0,1]
	v_add_f32_e32 v1, v12, v1
	v_pk_mul_f32 v[10:11], v[88:89], v[88:89]
	v_add_f32_e32 v1, v13, v1
	v_pk_add_f32 v[80:81], v[6:7], v[8:9] op_sel_hi:[1,0] neg_lo:[0,1] neg_hi:[0,1]
	v_add_f32_e32 v1, v10, v1
	v_pk_mul_f32 v[6:7], v[80:81], v[80:81]
	v_add_f32_e32 v1, v11, v1
	v_pk_add_f32 v[82:83], v[4:5], v[8:9] op_sel_hi:[1,0] neg_lo:[0,1] neg_hi:[0,1]
	v_add_f32_e32 v1, v6, v1
	v_pk_mul_f32 v[4:5], v[82:83], v[82:83]
	v_add_f32_e32 v1, v7, v1
	v_add_f32_e32 v1, v4, v1
	v_add_f32_e32 v1, v5, v1
	s_nop 1
	v_add_f32_dpp v1, v1, v1 quad_perm:[1,0,3,2] row_mask:0xf bank_mask:0xf bound_ctrl:1
	s_nop 1
	v_add_f32_dpp v1, v1, v1 quad_perm:[2,3,0,1] row_mask:0xf bank_mask:0xf bound_ctrl:1
	s_nop 1
	v_add_f32_dpp v1, v1, v1 row_half_mirror row_mask:0xf bank_mask:0xf bound_ctrl:1
	s_nop 1
	v_add_f32_dpp v1, v1, v1 row_mirror row_mask:0xf bank_mask:0xf bound_ctrl:1
	s_nop 1
	v_mov_b32_dpp v3, v1 row_bcast:15 row_mask:0xa bank_mask:0xf
	v_add_f32_e32 v1, v1, v3
	v_mov_b32_e32 v3, v187
	s_nop 1
	v_mov_b32_dpp v3, v1 row_bcast:31 row_mask:0xc bank_mask:0xf
	v_add_f32_e32 v1, v1, v3
	v_ashrrev_i32_e32 v3, 31, v2
	v_lshlrev_b64 v[2:3], 4, v[2:3]
	v_lshl_add_u64 v[4:5], s[64:65], 0, v[2:3]
	v_lshl_add_u64 v[2:3], s[62:63], 0, v[2:3]
	global_load_dwordx4 v[58:61], v[4:5], off
	global_load_dwordx4 v[50:53], v[4:5], off offset:1024
	global_load_dwordx4 v[62:65], v[2:3], off
	global_load_dwordx4 v[54:57], v[2:3], off offset:1024
	global_load_dwordx4 v[42:45], v[4:5], off offset:2048
	global_load_dwordx4 v[34:37], v[4:5], off offset:3072
	global_load_dwordx4 v[46:49], v[2:3], off offset:2048
	global_load_dwordx4 v[38:41], v[2:3], off offset:3072
	v_add_co_u32_e32 v4, vcc, 0x1000, v4
	v_readlane_b32 s13, v1, 63
	s_nop 0
	v_addc_co_u32_e32 v5, vcc, 0, v5, vcc
	v_add_co_u32_e32 v6, vcc, 0x1000, v2
	v_fma_f32 v1, s13, v0, v228
	s_nop 0
	v_addc_co_u32_e32 v7, vcc, 0, v3, vcc
	global_load_dwordx4 v[26:29], v[4:5], off
	global_load_dwordx4 v[18:21], v[4:5], off offset:1024
	global_load_dwordx4 v[30:33], v[6:7], off
	global_load_dwordx4 v[22:25], v[6:7], off offset:1024
	global_load_dwordx4 v[10:13], v[4:5], off offset:2048
	s_nop 0
	global_load_dwordx4 v[2:5], v[4:5], off offset:3072
	s_nop 0
	global_load_dwordx4 v[14:17], v[6:7], off offset:2048
	s_nop 0
	global_load_dwordx4 v[6:9], v[6:7], off offset:3072
	v_mul_f32_e32 v84, 0x4f800000, v1
	v_cmp_gt_f32_e32 vcc, s6, v1
	s_nop 1
	v_cndmask_b32_e32 v1, v1, v84, vcc
	v_sqrt_f32_e32 v84, v1
	s_nop 0
	v_add_u32_e32 v85, -1, v84
	v_fma_f32 v90, -v85, v84, v1
	v_cmp_ge_f32_e64 s[42:43], 0, v90
	v_add_u32_e32 v90, 1, v84
	s_nop 0
	v_cndmask_b32_e64 v85, v84, v85, s[42:43]
	v_fma_f32 v84, -v90, v84, v1
	v_cmp_lt_f32_e64 s[42:43], 0, v84
	s_nop 1
	v_cndmask_b32_e64 v84, v85, v90, s[42:43]
	v_mul_f32_e32 v85, 0x37800000, v84
	v_cndmask_b32_e32 v84, v84, v85, vcc
	v_cmp_class_f32_e32 vcc, v1, v229
	s_nop 1
	v_cndmask_b32_e32 v92, v84, v1, vcc
	v_div_scale_f32 v1, s[14:15], v92, v92, 1.0
	v_rcp_f32_e32 v84, v1
	s_nop 0
	v_fma_f32 v85, -v1, v84, 1.0
	v_fmac_f32_e32 v84, v85, v84
	v_div_scale_f32 v85, vcc, 1.0, v92, 1.0
	v_mul_f32_e32 v90, v85, v84
	v_fma_f32 v91, -v1, v90, v85
	v_fmac_f32_e32 v90, v91, v84
	v_fma_f32 v1, -v1, v90, v85
	v_div_fmas_f32 v93, v1, v84, v90
	s_cbranch_scc1 .LBB0_931
	s_cmp_eq_u32 s96, 3
	s_cselect_b64 s[42:43], -1, 0
	s_cbranch_execz .LBB0_932
	s_branch .LBB0_933
